# v5 minus the mid-segment s_setprio 0/1 yield pairs
# speedup vs baseline: 1.0184x; 1.0057x over previous
.LBB0_109:
	ds_read_b128 v[130:133], v158
	ds_read_b128 v[162:165], v158 offset:1024
	ds_read_b128 v[166:169], v158 offset:2048
	ds_read_b128 v[170:173], v158 offset:3072
	ds_read_b128 v[174:177], v159
	ds_read_b128 v[178:181], v159 offset:1024
	ds_read_b128 v[182:185], v159 offset:2048
	ds_read_b128 v[186:189], v159 offset:3072
	s_add_u32 s22, s20, 0xfff04000
	s_addc_u32 s23, s21, -1
	s_cmp_eq_u32 s46, 60
	s_cselect_b32 s26, s42, s22
	s_cselect_b32 s27, s15, s23
	s_cselect_b32 s24, s43, s44
	s_cselect_b32 s25, s13, s45
	s_add_u32 s22, s26, 0x4000
	s_addc_u32 s23, s27, 0
	s_add_i32 m0, s29, 0xc000
	ds_read_b128 v[190:193], v160
	ds_read_b128 v[194:197], v160 offset:1024
	ds_read_b128 v[198:201], v160 offset:2048
	ds_read_b128 v[202:205], v160 offset:3072
	ds_read_b128 v[206:209], v160 offset:4096
	ds_read_b128 v[210:213], v160 offset:5120
	ds_read_b128 v[214:217], v160 offset:6144
	ds_read_b128 v[218:221], v160 offset:7168
	global_load_lds_dwordx4 v146, s[20:21]
	s_add_i32 m0, s29, 0xe000
	s_nop 0
	global_load_lds_dwordx4 v148, s[20:21]
	s_waitcnt vmcnt(8)
	s_waitcnt lgkmcnt(0)
	s_barrier
	s_setprio 1
	s_waitcnt lgkmcnt(0)
	v_mfma_f32_16x16x32_bf16 v[62:65], v[130:133], v[190:193], v[62:65]
	v_mfma_f32_16x16x32_bf16 v[62:65], v[162:165], v[194:197], v[62:65]
	v_mfma_f32_16x16x32_bf16 v[58:61], v[166:169], v[190:193], v[58:61]
	v_mfma_f32_16x16x32_bf16 v[58:61], v[170:173], v[194:197], v[58:61]
	v_mfma_f32_16x16x32_bf16 v[54:57], v[130:133], v[198:201], v[54:57]
	v_mfma_f32_16x16x32_bf16 v[54:57], v[162:165], v[202:205], v[54:57]
	v_mfma_f32_16x16x32_bf16 v[50:53], v[166:169], v[198:201], v[50:53]
	v_mfma_f32_16x16x32_bf16 v[50:53], v[170:173], v[202:205], v[50:53]
	v_mfma_f32_16x16x32_bf16 v[46:49], v[130:133], v[206:209], v[46:49]
	v_mfma_f32_16x16x32_bf16 v[46:49], v[162:165], v[210:213], v[46:49]
	v_mfma_f32_16x16x32_bf16 v[42:45], v[166:169], v[206:209], v[42:45]
	v_mfma_f32_16x16x32_bf16 v[42:45], v[170:173], v[210:213], v[42:45]
	v_mfma_f32_16x16x32_bf16 v[38:41], v[130:133], v[214:217], v[38:41]
	v_mfma_f32_16x16x32_bf16 v[38:41], v[162:165], v[218:221], v[38:41]
	v_mfma_f32_16x16x32_bf16 v[34:37], v[166:169], v[214:217], v[34:37]
	v_mfma_f32_16x16x32_bf16 v[34:37], v[170:173], v[218:221], v[34:37]
	v_mfma_f32_16x16x32_bf16 v[126:129], v[174:177], v[190:193], v[126:129]
	v_mfma_f32_16x16x32_bf16 v[126:129], v[178:181], v[194:197], v[126:129]
	v_mfma_f32_16x16x32_bf16 v[122:125], v[182:185], v[190:193], v[122:125]
	v_mfma_f32_16x16x32_bf16 v[122:125], v[186:189], v[194:197], v[122:125]
	v_mfma_f32_16x16x32_bf16 v[118:121], v[174:177], v[198:201], v[118:121]
	v_mfma_f32_16x16x32_bf16 v[118:121], v[178:181], v[202:205], v[118:121]
	v_mfma_f32_16x16x32_bf16 v[114:117], v[182:185], v[198:201], v[114:117]
	v_mfma_f32_16x16x32_bf16 v[114:117], v[186:189], v[202:205], v[114:117]
	v_mfma_f32_16x16x32_bf16 v[110:113], v[174:177], v[206:209], v[110:113]
	v_mfma_f32_16x16x32_bf16 v[110:113], v[178:181], v[210:213], v[110:113]
	v_mfma_f32_16x16x32_bf16 v[106:109], v[182:185], v[206:209], v[106:109]
	v_mfma_f32_16x16x32_bf16 v[106:109], v[186:189], v[210:213], v[106:109]
	v_mfma_f32_16x16x32_bf16 v[102:105], v[174:177], v[214:217], v[102:105]
	v_mfma_f32_16x16x32_bf16 v[102:105], v[178:181], v[218:221], v[102:105]
	v_mfma_f32_16x16x32_bf16 v[98:101], v[182:185], v[214:217], v[98:101]
	v_mfma_f32_16x16x32_bf16 v[98:101], v[186:189], v[218:221], v[98:101]
	s_setprio 0
	s_barrier
	s_add_i32 s47, s36, s28
	s_mov_b32 m0, s47
	ds_read_b128 v[190:193], v160 offset:16384
	ds_read_b128 v[194:197], v160 offset:17408
	ds_read_b128 v[198:201], v160 offset:18432
	ds_read_b128 v[202:205], v160 offset:19456
	ds_read_b128 v[206:209], v160 offset:20480
	ds_read_b128 v[210:213], v160 offset:21504
	ds_read_b128 v[214:217], v160 offset:22528
	ds_read_b128 v[218:221], v160 offset:23552
	global_load_lds_dwordx4 v138, s[24:25]
	s_add_i32 m0, s47, 0x2000
	s_add_u32 s48, s24, 0x100000
	s_addc_u32 s49, s25, 0
	s_add_i32 s47, s37, s28
	global_load_lds_dwordx4 v134, s[24:25]
	s_mov_b32 m0, s47
	s_nop 0
	global_load_lds_dwordx4 v138, s[48:49]
	s_add_i32 m0, s47, 0x2000
	s_nop 0
	global_load_lds_dwordx4 v134, s[48:49]
	s_mov_b32 m0, s29
	s_nop 0
	global_load_lds_dwordx4 v140, s[26:27]
	s_mov_b32 m0, s30
	s_nop 0
	global_load_lds_dwordx4 v136, s[26:27]
	s_waitcnt vmcnt(8)
	s_waitcnt lgkmcnt(0)
	s_barrier
	s_setprio 1
	s_waitcnt lgkmcnt(0)
	v_mfma_f32_16x16x32_bf16 v[30:33], v[130:133], v[190:193], v[30:33]
	v_mfma_f32_16x16x32_bf16 v[30:33], v[162:165], v[194:197], v[30:33]
	v_mfma_f32_16x16x32_bf16 v[26:29], v[166:169], v[190:193], v[26:29]
	v_mfma_f32_16x16x32_bf16 v[26:29], v[170:173], v[194:197], v[26:29]
	v_mfma_f32_16x16x32_bf16 v[22:25], v[130:133], v[198:201], v[22:25]
	v_mfma_f32_16x16x32_bf16 v[22:25], v[162:165], v[202:205], v[22:25]
	v_mfma_f32_16x16x32_bf16 v[18:21], v[166:169], v[198:201], v[18:21]
	v_mfma_f32_16x16x32_bf16 v[18:21], v[170:173], v[202:205], v[18:21]
	v_mfma_f32_16x16x32_bf16 v[14:17], v[130:133], v[206:209], v[14:17]
	v_mfma_f32_16x16x32_bf16 v[14:17], v[162:165], v[210:213], v[14:17]
	v_mfma_f32_16x16x32_bf16 v[10:13], v[166:169], v[206:209], v[10:13]
	v_mfma_f32_16x16x32_bf16 v[10:13], v[170:173], v[210:213], v[10:13]
	v_mfma_f32_16x16x32_bf16 v[6:9], v[130:133], v[214:217], v[6:9]
	v_mfma_f32_16x16x32_bf16 v[6:9], v[162:165], v[218:221], v[6:9]
	v_mfma_f32_16x16x32_bf16 v[2:5], v[166:169], v[214:217], v[2:5]
	v_mfma_f32_16x16x32_bf16 v[2:5], v[170:173], v[218:221], v[2:5]
	v_mfma_f32_16x16x32_bf16 v[94:97], v[174:177], v[190:193], v[94:97]
	v_mfma_f32_16x16x32_bf16 v[94:97], v[178:181], v[194:197], v[94:97]
	v_mfma_f32_16x16x32_bf16 v[90:93], v[182:185], v[190:193], v[90:93]
	v_mfma_f32_16x16x32_bf16 v[90:93], v[186:189], v[194:197], v[90:93]
	v_mfma_f32_16x16x32_bf16 v[86:89], v[174:177], v[198:201], v[86:89]
	v_mfma_f32_16x16x32_bf16 v[86:89], v[178:181], v[202:205], v[86:89]
	v_mfma_f32_16x16x32_bf16 v[82:85], v[182:185], v[198:201], v[82:85]
	v_mfma_f32_16x16x32_bf16 v[82:85], v[186:189], v[202:205], v[82:85]
	v_mfma_f32_16x16x32_bf16 v[78:81], v[174:177], v[206:209], v[78:81]
	v_mfma_f32_16x16x32_bf16 v[78:81], v[178:181], v[210:213], v[78:81]
	v_mfma_f32_16x16x32_bf16 v[74:77], v[182:185], v[206:209], v[74:77]
	v_mfma_f32_16x16x32_bf16 v[74:77], v[186:189], v[210:213], v[74:77]
	v_mfma_f32_16x16x32_bf16 v[70:73], v[174:177], v[214:217], v[70:73]
	v_mfma_f32_16x16x32_bf16 v[70:73], v[178:181], v[218:221], v[70:73]
	v_mfma_f32_16x16x32_bf16 v[66:69], v[182:185], v[214:217], v[66:69]
	v_mfma_f32_16x16x32_bf16 v[66:69], v[186:189], v[218:221], v[66:69]
	s_setprio 0
	s_barrier
	s_add_i32 s47, 0, 0x18000
	v_add_u32_e32 v154, s47, v156
	s_add_i32 s48, 0, 0x1c000
	ds_read_b128 v[130:133], v154
	ds_read_b128 v[162:165], v154 offset:1024
	ds_read_b128 v[166:169], v154 offset:2048
	ds_read_b128 v[170:173], v154 offset:3072
	v_add_u32_e32 v154, s48, v156
	ds_read_b128 v[174:177], v154
	ds_read_b128 v[178:181], v154 offset:1024
	ds_read_b128 v[182:185], v154 offset:2048
	ds_read_b128 v[186:189], v154 offset:3072
	s_add_u32 s26, s26, 0x100000
	s_addc_u32 s27, s27, 0
	s_mov_b32 m0, s31
	ds_read_b128 v[190:193], v160 offset:32768
	ds_read_b128 v[194:197], v160 offset:33792
	ds_read_b128 v[198:201], v160 offset:34816
	ds_read_b128 v[202:205], v160 offset:35840
	ds_read_b128 v[206:209], v160 offset:36864
	ds_read_b128 v[210:213], v160 offset:37888
	ds_read_b128 v[214:217], v160 offset:38912
	ds_read_b128 v[218:221], v160 offset:39936
	global_load_lds_dwordx4 v140, s[26:27]
	s_mov_b32 m0, s33
	s_nop 0
	global_load_lds_dwordx4 v136, s[26:27]
	s_waitcnt vmcnt(8)
	s_waitcnt lgkmcnt(0)
	s_barrier
	s_setprio 1
	s_waitcnt lgkmcnt(0)
	v_mfma_f32_16x16x32_bf16 v[62:65], v[130:133], v[190:193], v[62:65]
	v_mfma_f32_16x16x32_bf16 v[62:65], v[162:165], v[194:197], v[62:65]
	v_mfma_f32_16x16x32_bf16 v[58:61], v[166:169], v[190:193], v[58:61]
	v_mfma_f32_16x16x32_bf16 v[58:61], v[170:173], v[194:197], v[58:61]
	v_mfma_f32_16x16x32_bf16 v[54:57], v[130:133], v[198:201], v[54:57]
	v_mfma_f32_16x16x32_bf16 v[54:57], v[162:165], v[202:205], v[54:57]
	v_mfma_f32_16x16x32_bf16 v[50:53], v[166:169], v[198:201], v[50:53]
	v_mfma_f32_16x16x32_bf16 v[50:53], v[170:173], v[202:205], v[50:53]
	v_mfma_f32_16x16x32_bf16 v[46:49], v[130:133], v[206:209], v[46:49]
	v_mfma_f32_16x16x32_bf16 v[46:49], v[162:165], v[210:213], v[46:49]
	v_mfma_f32_16x16x32_bf16 v[42:45], v[166:169], v[206:209], v[42:45]
	v_mfma_f32_16x16x32_bf16 v[42:45], v[170:173], v[210:213], v[42:45]
	v_mfma_f32_16x16x32_bf16 v[38:41], v[130:133], v[214:217], v[38:41]
	v_mfma_f32_16x16x32_bf16 v[38:41], v[162:165], v[218:221], v[38:41]
	v_mfma_f32_16x16x32_bf16 v[34:37], v[166:169], v[214:217], v[34:37]
	v_mfma_f32_16x16x32_bf16 v[34:37], v[170:173], v[218:221], v[34:37]
	v_mfma_f32_16x16x32_bf16 v[126:129], v[174:177], v[190:193], v[126:129]
	v_mfma_f32_16x16x32_bf16 v[126:129], v[178:181], v[194:197], v[126:129]
	v_mfma_f32_16x16x32_bf16 v[122:125], v[182:185], v[190:193], v[122:125]
	v_mfma_f32_16x16x32_bf16 v[122:125], v[186:189], v[194:197], v[122:125]
	v_mfma_f32_16x16x32_bf16 v[118:121], v[174:177], v[198:201], v[118:121]
	v_mfma_f32_16x16x32_bf16 v[118:121], v[178:181], v[202:205], v[118:121]
	v_mfma_f32_16x16x32_bf16 v[114:117], v[182:185], v[198:201], v[114:117]
	v_mfma_f32_16x16x32_bf16 v[114:117], v[186:189], v[202:205], v[114:117]
	v_mfma_f32_16x16x32_bf16 v[110:113], v[174:177], v[206:209], v[110:113]
	v_mfma_f32_16x16x32_bf16 v[110:113], v[178:181], v[210:213], v[110:113]
	v_mfma_f32_16x16x32_bf16 v[106:109], v[182:185], v[206:209], v[106:109]
	v_mfma_f32_16x16x32_bf16 v[106:109], v[186:189], v[210:213], v[106:109]
	v_mfma_f32_16x16x32_bf16 v[102:105], v[174:177], v[214:217], v[102:105]
	v_mfma_f32_16x16x32_bf16 v[102:105], v[178:181], v[218:221], v[102:105]
	v_mfma_f32_16x16x32_bf16 v[98:101], v[182:185], v[214:217], v[98:101]
	v_mfma_f32_16x16x32_bf16 v[98:101], v[186:189], v[218:221], v[98:101]
	s_setprio 0
	s_barrier
	s_add_u32 s26, s24, 0x4000
	s_addc_u32 s27, s25, 0
	s_add_i32 s47, s47, s28
	s_mov_b32 m0, s47
	ds_read_b128 v[190:193], v160 offset:49152
	ds_read_b128 v[194:197], v160 offset:50176
	ds_read_b128 v[198:201], v160 offset:51200
	ds_read_b128 v[202:205], v160 offset:52224
	ds_read_b128 v[206:209], v160 offset:53248
	ds_read_b128 v[210:213], v160 offset:54272
	ds_read_b128 v[214:217], v160 offset:55296
	ds_read_b128 v[218:221], v160 offset:56320
	global_load_lds_dwordx4 v138, s[26:27]
	s_add_i32 m0, s47, 0x2000
	s_add_u32 s24, s24, 0x104000
	s_addc_u32 s25, s25, 0
	global_load_lds_dwordx4 v134, s[26:27]
	s_add_i32 s26, s48, s28
	s_mov_b32 m0, s26
	s_nop 0
	global_load_lds_dwordx4 v138, s[24:25]
	s_add_i32 m0, s26, 0x2000
	s_nop 0
	global_load_lds_dwordx4 v134, s[24:25]
	s_mov_b32 m0, s34
	s_nop 0
	global_load_lds_dwordx4 v140, s[22:23]
	s_mov_b32 m0, s35
	s_nop 0
	global_load_lds_dwordx4 v136, s[22:23]
	s_waitcnt vmcnt(8)
	s_waitcnt lgkmcnt(0)
	s_barrier
	s_setprio 1
	s_waitcnt lgkmcnt(0)
	v_mfma_f32_16x16x32_bf16 v[30:33], v[130:133], v[190:193], v[30:33]
	v_mfma_f32_16x16x32_bf16 v[30:33], v[162:165], v[194:197], v[30:33]
	v_mfma_f32_16x16x32_bf16 v[26:29], v[166:169], v[190:193], v[26:29]
	v_mfma_f32_16x16x32_bf16 v[26:29], v[170:173], v[194:197], v[26:29]
	v_mfma_f32_16x16x32_bf16 v[22:25], v[130:133], v[198:201], v[22:25]
	v_mfma_f32_16x16x32_bf16 v[22:25], v[162:165], v[202:205], v[22:25]
	v_mfma_f32_16x16x32_bf16 v[18:21], v[166:169], v[198:201], v[18:21]
	v_mfma_f32_16x16x32_bf16 v[18:21], v[170:173], v[202:205], v[18:21]
	v_mfma_f32_16x16x32_bf16 v[14:17], v[130:133], v[206:209], v[14:17]
	v_mfma_f32_16x16x32_bf16 v[14:17], v[162:165], v[210:213], v[14:17]
	v_mfma_f32_16x16x32_bf16 v[10:13], v[166:169], v[206:209], v[10:13]
	v_mfma_f32_16x16x32_bf16 v[10:13], v[170:173], v[210:213], v[10:13]
	v_mfma_f32_16x16x32_bf16 v[6:9], v[130:133], v[214:217], v[6:9]
	v_mfma_f32_16x16x32_bf16 v[6:9], v[162:165], v[218:221], v[6:9]
	v_mfma_f32_16x16x32_bf16 v[2:5], v[166:169], v[214:217], v[2:5]
	v_mfma_f32_16x16x32_bf16 v[2:5], v[170:173], v[218:221], v[2:5]
	v_mfma_f32_16x16x32_bf16 v[94:97], v[174:177], v[190:193], v[94:97]
	v_mfma_f32_16x16x32_bf16 v[94:97], v[178:181], v[194:197], v[94:97]
	v_mfma_f32_16x16x32_bf16 v[90:93], v[182:185], v[190:193], v[90:93]
	v_mfma_f32_16x16x32_bf16 v[90:93], v[186:189], v[194:197], v[90:93]
	v_mfma_f32_16x16x32_bf16 v[86:89], v[174:177], v[198:201], v[86:89]
	v_mfma_f32_16x16x32_bf16 v[86:89], v[178:181], v[202:205], v[86:89]
	v_mfma_f32_16x16x32_bf16 v[82:85], v[182:185], v[198:201], v[82:85]
	v_mfma_f32_16x16x32_bf16 v[82:85], v[186:189], v[202:205], v[82:85]
	v_mfma_f32_16x16x32_bf16 v[78:81], v[174:177], v[206:209], v[78:81]
	v_mfma_f32_16x16x32_bf16 v[78:81], v[178:181], v[210:213], v[78:81]
	v_mfma_f32_16x16x32_bf16 v[74:77], v[182:185], v[206:209], v[74:77]
	v_mfma_f32_16x16x32_bf16 v[74:77], v[186:189], v[210:213], v[74:77]
	v_mfma_f32_16x16x32_bf16 v[70:73], v[174:177], v[214:217], v[70:73]
	v_mfma_f32_16x16x32_bf16 v[70:73], v[178:181], v[218:221], v[70:73]
	v_mfma_f32_16x16x32_bf16 v[66:69], v[182:185], v[214:217], v[66:69]
	v_mfma_f32_16x16x32_bf16 v[66:69], v[186:189], v[218:221], v[66:69]
	s_setprio 0
	s_barrier
	s_add_i32 s46, s46, 2
	s_add_u32 s20, s20, 0x8000
	s_addc_u32 s21, s21, 0
	s_add_u32 s44, s44, 0x8000
	s_addc_u32 s45, s45, 0
	s_cmp_gt_u32 s46, 61
	s_cbranch_scc0 .LBB0_109
	s_and_b64 vcc, exec, s[8:9]
	s_cbranch_vccnz .LBB0_113
	v_lshl_add_u32 v154, s4, 8, v1
	s_cmp_lg_u32 s41, 24
	s_mov_b64 s[20:21], -1
	s_cbranch_scc1 .LBB0_114

.LBB0_376:
	ds_read_b128 v[130:133], v159
	ds_read_b128 v[162:165], v159 offset:1024
	ds_read_b128 v[166:169], v159 offset:2048
	ds_read_b128 v[170:173], v159 offset:3072
	ds_read_b128 v[174:177], v160
	ds_read_b128 v[178:181], v160 offset:1024
	ds_read_b128 v[182:185], v160 offset:2048
	ds_read_b128 v[186:189], v160 offset:3072
	s_add_u32 s34, s26, 0xfff04000
	s_addc_u32 s35, s27, -1
	s_cmp_eq_u32 s87, 60
	s_cselect_b32 s38, s80, s34
	s_cselect_b32 s39, s21, s35
	s_cselect_b32 s36, s81, s83
	s_cselect_b32 s37, s19, s86
	s_add_u32 s34, s38, 0x4000
	s_addc_u32 s35, s39, 0
	s_add_i32 m0, s46, 0xc000
	ds_read_b128 v[190:193], v161
	ds_read_b128 v[194:197], v161 offset:1024
	ds_read_b128 v[198:201], v161 offset:2048
	ds_read_b128 v[202:205], v161 offset:3072
	ds_read_b128 v[206:209], v161 offset:4096
	ds_read_b128 v[210:213], v161 offset:5120
	ds_read_b128 v[214:217], v161 offset:6144
	ds_read_b128 v[218:221], v161 offset:7168
	global_load_lds_dwordx4 v146, s[26:27]
	s_add_i32 m0, s46, 0xe000
	s_nop 0
	global_load_lds_dwordx4 v148, s[26:27]
	s_waitcnt vmcnt(8)
	s_waitcnt lgkmcnt(0)
	s_barrier
	s_setprio 1
	s_waitcnt lgkmcnt(0)
	v_mfma_f32_16x16x32_bf16 v[62:65], v[130:133], v[190:193], v[62:65]
	v_mfma_f32_16x16x32_bf16 v[62:65], v[162:165], v[194:197], v[62:65]
	v_mfma_f32_16x16x32_bf16 v[58:61], v[166:169], v[190:193], v[58:61]
	v_mfma_f32_16x16x32_bf16 v[58:61], v[170:173], v[194:197], v[58:61]
	v_mfma_f32_16x16x32_bf16 v[54:57], v[130:133], v[198:201], v[54:57]
	v_mfma_f32_16x16x32_bf16 v[54:57], v[162:165], v[202:205], v[54:57]
	v_mfma_f32_16x16x32_bf16 v[50:53], v[166:169], v[198:201], v[50:53]
	v_mfma_f32_16x16x32_bf16 v[50:53], v[170:173], v[202:205], v[50:53]
	v_mfma_f32_16x16x32_bf16 v[46:49], v[130:133], v[206:209], v[46:49]
	v_mfma_f32_16x16x32_bf16 v[46:49], v[162:165], v[210:213], v[46:49]
	v_mfma_f32_16x16x32_bf16 v[42:45], v[166:169], v[206:209], v[42:45]
	v_mfma_f32_16x16x32_bf16 v[42:45], v[170:173], v[210:213], v[42:45]
	v_mfma_f32_16x16x32_bf16 v[38:41], v[130:133], v[214:217], v[38:41]
	v_mfma_f32_16x16x32_bf16 v[38:41], v[162:165], v[218:221], v[38:41]
	v_mfma_f32_16x16x32_bf16 v[34:37], v[166:169], v[214:217], v[34:37]
	v_mfma_f32_16x16x32_bf16 v[34:37], v[170:173], v[218:221], v[34:37]
	v_mfma_f32_16x16x32_bf16 v[126:129], v[174:177], v[190:193], v[126:129]
	v_mfma_f32_16x16x32_bf16 v[126:129], v[178:181], v[194:197], v[126:129]
	v_mfma_f32_16x16x32_bf16 v[122:125], v[182:185], v[190:193], v[122:125]
	v_mfma_f32_16x16x32_bf16 v[122:125], v[186:189], v[194:197], v[122:125]
	v_mfma_f32_16x16x32_bf16 v[118:121], v[174:177], v[198:201], v[118:121]
	v_mfma_f32_16x16x32_bf16 v[118:121], v[178:181], v[202:205], v[118:121]
	v_mfma_f32_16x16x32_bf16 v[114:117], v[182:185], v[198:201], v[114:117]
	v_mfma_f32_16x16x32_bf16 v[114:117], v[186:189], v[202:205], v[114:117]
	v_mfma_f32_16x16x32_bf16 v[110:113], v[174:177], v[206:209], v[110:113]
	v_mfma_f32_16x16x32_bf16 v[110:113], v[178:181], v[210:213], v[110:113]
	v_mfma_f32_16x16x32_bf16 v[106:109], v[182:185], v[206:209], v[106:109]
	v_mfma_f32_16x16x32_bf16 v[106:109], v[186:189], v[210:213], v[106:109]
	v_mfma_f32_16x16x32_bf16 v[102:105], v[174:177], v[214:217], v[102:105]
	v_mfma_f32_16x16x32_bf16 v[102:105], v[178:181], v[218:221], v[102:105]
	v_mfma_f32_16x16x32_bf16 v[98:101], v[182:185], v[214:217], v[98:101]
	v_mfma_f32_16x16x32_bf16 v[98:101], v[186:189], v[218:221], v[98:101]
	s_setprio 0
	s_barrier
	s_add_i32 s88, s66, s41
	s_mov_b32 m0, s88
	ds_read_b128 v[190:193], v161 offset:16384
	ds_read_b128 v[194:197], v161 offset:17408
	ds_read_b128 v[198:201], v161 offset:18432
	ds_read_b128 v[202:205], v161 offset:19456
	ds_read_b128 v[206:209], v161 offset:20480
	ds_read_b128 v[210:213], v161 offset:21504
	ds_read_b128 v[214:217], v161 offset:22528
	ds_read_b128 v[218:221], v161 offset:23552
	global_load_lds_dwordx4 v138, s[36:37]
	s_add_i32 m0, s88, 0x2000
	s_add_u32 s88, s36, 0x100000
	s_addc_u32 s89, s37, 0
	s_add_i32 vcc_lo, s67, s41
	global_load_lds_dwordx4 v134, s[36:37]
	s_mov_b32 m0, vcc_lo
	s_nop 0
	global_load_lds_dwordx4 v138, s[88:89]
	s_add_i32 m0, vcc_lo, 0x2000
	s_nop 0
	global_load_lds_dwordx4 v134, s[88:89]
	s_mov_b32 m0, s46
	s_nop 0
	global_load_lds_dwordx4 v140, s[38:39]
	s_mov_b32 m0, s47
	s_nop 0
	global_load_lds_dwordx4 v136, s[38:39]
	s_waitcnt vmcnt(8)
	s_waitcnt lgkmcnt(0)
	s_barrier
	s_setprio 1
	s_waitcnt lgkmcnt(0)
	v_mfma_f32_16x16x32_bf16 v[30:33], v[130:133], v[190:193], v[30:33]
	v_mfma_f32_16x16x32_bf16 v[30:33], v[162:165], v[194:197], v[30:33]
	v_mfma_f32_16x16x32_bf16 v[26:29], v[166:169], v[190:193], v[26:29]
	v_mfma_f32_16x16x32_bf16 v[26:29], v[170:173], v[194:197], v[26:29]
	v_mfma_f32_16x16x32_bf16 v[22:25], v[130:133], v[198:201], v[22:25]
	v_mfma_f32_16x16x32_bf16 v[22:25], v[162:165], v[202:205], v[22:25]
	v_mfma_f32_16x16x32_bf16 v[18:21], v[166:169], v[198:201], v[18:21]
	v_mfma_f32_16x16x32_bf16 v[18:21], v[170:173], v[202:205], v[18:21]
	v_mfma_f32_16x16x32_bf16 v[14:17], v[130:133], v[206:209], v[14:17]
	v_mfma_f32_16x16x32_bf16 v[14:17], v[162:165], v[210:213], v[14:17]
	v_mfma_f32_16x16x32_bf16 v[10:13], v[166:169], v[206:209], v[10:13]
	v_mfma_f32_16x16x32_bf16 v[10:13], v[170:173], v[210:213], v[10:13]
	v_mfma_f32_16x16x32_bf16 v[6:9], v[130:133], v[214:217], v[6:9]
	v_mfma_f32_16x16x32_bf16 v[6:9], v[162:165], v[218:221], v[6:9]
	v_mfma_f32_16x16x32_bf16 v[2:5], v[166:169], v[214:217], v[2:5]
	v_mfma_f32_16x16x32_bf16 v[2:5], v[170:173], v[218:221], v[2:5]
	v_mfma_f32_16x16x32_bf16 v[94:97], v[174:177], v[190:193], v[94:97]
	v_mfma_f32_16x16x32_bf16 v[94:97], v[178:181], v[194:197], v[94:97]
	v_mfma_f32_16x16x32_bf16 v[90:93], v[182:185], v[190:193], v[90:93]
	v_mfma_f32_16x16x32_bf16 v[90:93], v[186:189], v[194:197], v[90:93]
	v_mfma_f32_16x16x32_bf16 v[86:89], v[174:177], v[198:201], v[86:89]
	v_mfma_f32_16x16x32_bf16 v[86:89], v[178:181], v[202:205], v[86:89]
	v_mfma_f32_16x16x32_bf16 v[82:85], v[182:185], v[198:201], v[82:85]
	v_mfma_f32_16x16x32_bf16 v[82:85], v[186:189], v[202:205], v[82:85]
	v_mfma_f32_16x16x32_bf16 v[78:81], v[174:177], v[206:209], v[78:81]
	v_mfma_f32_16x16x32_bf16 v[78:81], v[178:181], v[210:213], v[78:81]
	v_mfma_f32_16x16x32_bf16 v[74:77], v[182:185], v[206:209], v[74:77]
	v_mfma_f32_16x16x32_bf16 v[74:77], v[186:189], v[210:213], v[74:77]
	v_mfma_f32_16x16x32_bf16 v[70:73], v[174:177], v[214:217], v[70:73]
	v_mfma_f32_16x16x32_bf16 v[70:73], v[178:181], v[218:221], v[70:73]
	v_mfma_f32_16x16x32_bf16 v[66:69], v[182:185], v[214:217], v[66:69]
	v_mfma_f32_16x16x32_bf16 v[66:69], v[186:189], v[218:221], v[66:69]
	s_setprio 0
	s_barrier
	s_add_i32 s88, 0, 0x18000
	v_add_u32_e32 v154, s88, v157
	s_add_i32 s89, 0, 0x1c000
	ds_read_b128 v[130:133], v154
	ds_read_b128 v[162:165], v154 offset:1024
	ds_read_b128 v[166:169], v154 offset:2048
	ds_read_b128 v[170:173], v154 offset:3072
	v_add_u32_e32 v154, s89, v157
	ds_read_b128 v[174:177], v154
	ds_read_b128 v[178:181], v154 offset:1024
	ds_read_b128 v[182:185], v154 offset:2048
	ds_read_b128 v[186:189], v154 offset:3072
	s_add_u32 s38, s38, 0x100000
	s_addc_u32 s39, s39, 0
	s_mov_b32 m0, s58
	ds_read_b128 v[190:193], v161 offset:32768
	ds_read_b128 v[194:197], v161 offset:33792
	ds_read_b128 v[198:201], v161 offset:34816
	ds_read_b128 v[202:205], v161 offset:35840
	ds_read_b128 v[206:209], v161 offset:36864
	ds_read_b128 v[210:213], v161 offset:37888
	ds_read_b128 v[214:217], v161 offset:38912
	ds_read_b128 v[218:221], v161 offset:39936
	global_load_lds_dwordx4 v140, s[38:39]
	s_mov_b32 m0, s59
	s_nop 0
	global_load_lds_dwordx4 v136, s[38:39]
	s_waitcnt vmcnt(8)
	s_waitcnt lgkmcnt(0)
	s_barrier
	s_setprio 1
	s_waitcnt lgkmcnt(0)
	v_mfma_f32_16x16x32_bf16 v[62:65], v[130:133], v[190:193], v[62:65]
	v_mfma_f32_16x16x32_bf16 v[62:65], v[162:165], v[194:197], v[62:65]
	v_mfma_f32_16x16x32_bf16 v[58:61], v[166:169], v[190:193], v[58:61]
	v_mfma_f32_16x16x32_bf16 v[58:61], v[170:173], v[194:197], v[58:61]
	v_mfma_f32_16x16x32_bf16 v[54:57], v[130:133], v[198:201], v[54:57]
	v_mfma_f32_16x16x32_bf16 v[54:57], v[162:165], v[202:205], v[54:57]
	v_mfma_f32_16x16x32_bf16 v[50:53], v[166:169], v[198:201], v[50:53]
	v_mfma_f32_16x16x32_bf16 v[50:53], v[170:173], v[202:205], v[50:53]
	v_mfma_f32_16x16x32_bf16 v[46:49], v[130:133], v[206:209], v[46:49]
	v_mfma_f32_16x16x32_bf16 v[46:49], v[162:165], v[210:213], v[46:49]
	v_mfma_f32_16x16x32_bf16 v[42:45], v[166:169], v[206:209], v[42:45]
	v_mfma_f32_16x16x32_bf16 v[42:45], v[170:173], v[210:213], v[42:45]
	v_mfma_f32_16x16x32_bf16 v[38:41], v[130:133], v[214:217], v[38:41]
	v_mfma_f32_16x16x32_bf16 v[38:41], v[162:165], v[218:221], v[38:41]
	v_mfma_f32_16x16x32_bf16 v[34:37], v[166:169], v[214:217], v[34:37]
	v_mfma_f32_16x16x32_bf16 v[34:37], v[170:173], v[218:221], v[34:37]
	v_mfma_f32_16x16x32_bf16 v[126:129], v[174:177], v[190:193], v[126:129]
	v_mfma_f32_16x16x32_bf16 v[126:129], v[178:181], v[194:197], v[126:129]
	v_mfma_f32_16x16x32_bf16 v[122:125], v[182:185], v[190:193], v[122:125]
	v_mfma_f32_16x16x32_bf16 v[122:125], v[186:189], v[194:197], v[122:125]
	v_mfma_f32_16x16x32_bf16 v[118:121], v[174:177], v[198:201], v[118:121]
	v_mfma_f32_16x16x32_bf16 v[118:121], v[178:181], v[202:205], v[118:121]
	v_mfma_f32_16x16x32_bf16 v[114:117], v[182:185], v[198:201], v[114:117]
	v_mfma_f32_16x16x32_bf16 v[114:117], v[186:189], v[202:205], v[114:117]
	v_mfma_f32_16x16x32_bf16 v[110:113], v[174:177], v[206:209], v[110:113]
	v_mfma_f32_16x16x32_bf16 v[110:113], v[178:181], v[210:213], v[110:113]
	v_mfma_f32_16x16x32_bf16 v[106:109], v[182:185], v[206:209], v[106:109]
	v_mfma_f32_16x16x32_bf16 v[106:109], v[186:189], v[210:213], v[106:109]
	v_mfma_f32_16x16x32_bf16 v[102:105], v[174:177], v[214:217], v[102:105]
	v_mfma_f32_16x16x32_bf16 v[102:105], v[178:181], v[218:221], v[102:105]
	v_mfma_f32_16x16x32_bf16 v[98:101], v[182:185], v[214:217], v[98:101]
	v_mfma_f32_16x16x32_bf16 v[98:101], v[186:189], v[218:221], v[98:101]
	s_setprio 0
	s_barrier
	s_add_u32 s38, s36, 0x4000
	s_addc_u32 s39, s37, 0
	s_add_i32 s88, s88, s41
	s_mov_b32 m0, s88
	ds_read_b128 v[190:193], v161 offset:49152
	ds_read_b128 v[194:197], v161 offset:50176
	ds_read_b128 v[198:201], v161 offset:51200
	ds_read_b128 v[202:205], v161 offset:52224
	ds_read_b128 v[206:209], v161 offset:53248
	ds_read_b128 v[210:213], v161 offset:54272
	ds_read_b128 v[214:217], v161 offset:55296
	ds_read_b128 v[218:221], v161 offset:56320
	global_load_lds_dwordx4 v138, s[38:39]
	s_add_i32 m0, s88, 0x2000
	s_add_u32 s36, s36, 0x104000
	s_addc_u32 s37, s37, 0
	global_load_lds_dwordx4 v134, s[38:39]
	s_add_i32 s38, s89, s41
	s_mov_b32 m0, s38
	s_nop 0
	global_load_lds_dwordx4 v138, s[36:37]
	s_add_i32 m0, s38, 0x2000
	s_nop 0
	global_load_lds_dwordx4 v134, s[36:37]
	s_mov_b32 m0, s64
	s_nop 0
	global_load_lds_dwordx4 v140, s[34:35]
	s_mov_b32 m0, s65
	s_nop 0
	global_load_lds_dwordx4 v136, s[34:35]
	s_waitcnt vmcnt(8)
	s_waitcnt lgkmcnt(0)
	s_barrier
	s_setprio 1
	s_waitcnt lgkmcnt(0)
	v_mfma_f32_16x16x32_bf16 v[30:33], v[130:133], v[190:193], v[30:33]
	v_mfma_f32_16x16x32_bf16 v[30:33], v[162:165], v[194:197], v[30:33]
	v_mfma_f32_16x16x32_bf16 v[26:29], v[166:169], v[190:193], v[26:29]
	v_mfma_f32_16x16x32_bf16 v[26:29], v[170:173], v[194:197], v[26:29]
	v_mfma_f32_16x16x32_bf16 v[22:25], v[130:133], v[198:201], v[22:25]
	v_mfma_f32_16x16x32_bf16 v[22:25], v[162:165], v[202:205], v[22:25]
	v_mfma_f32_16x16x32_bf16 v[18:21], v[166:169], v[198:201], v[18:21]
	v_mfma_f32_16x16x32_bf16 v[18:21], v[170:173], v[202:205], v[18:21]
	v_mfma_f32_16x16x32_bf16 v[14:17], v[130:133], v[206:209], v[14:17]
	v_mfma_f32_16x16x32_bf16 v[14:17], v[162:165], v[210:213], v[14:17]
	v_mfma_f32_16x16x32_bf16 v[10:13], v[166:169], v[206:209], v[10:13]
	v_mfma_f32_16x16x32_bf16 v[10:13], v[170:173], v[210:213], v[10:13]
	v_mfma_f32_16x16x32_bf16 v[6:9], v[130:133], v[214:217], v[6:9]
	v_mfma_f32_16x16x32_bf16 v[6:9], v[162:165], v[218:221], v[6:9]
	v_mfma_f32_16x16x32_bf16 v[2:5], v[166:169], v[214:217], v[2:5]
	v_mfma_f32_16x16x32_bf16 v[2:5], v[170:173], v[218:221], v[2:5]
	v_mfma_f32_16x16x32_bf16 v[94:97], v[174:177], v[190:193], v[94:97]
	v_mfma_f32_16x16x32_bf16 v[94:97], v[178:181], v[194:197], v[94:97]
	v_mfma_f32_16x16x32_bf16 v[90:93], v[182:185], v[190:193], v[90:93]
	v_mfma_f32_16x16x32_bf16 v[90:93], v[186:189], v[194:197], v[90:93]
	v_mfma_f32_16x16x32_bf16 v[86:89], v[174:177], v[198:201], v[86:89]
	v_mfma_f32_16x16x32_bf16 v[86:89], v[178:181], v[202:205], v[86:89]
	v_mfma_f32_16x16x32_bf16 v[82:85], v[182:185], v[198:201], v[82:85]
	v_mfma_f32_16x16x32_bf16 v[82:85], v[186:189], v[202:205], v[82:85]
	v_mfma_f32_16x16x32_bf16 v[78:81], v[174:177], v[206:209], v[78:81]
	v_mfma_f32_16x16x32_bf16 v[78:81], v[178:181], v[210:213], v[78:81]
	v_mfma_f32_16x16x32_bf16 v[74:77], v[182:185], v[206:209], v[74:77]
	v_mfma_f32_16x16x32_bf16 v[74:77], v[186:189], v[210:213], v[74:77]
	v_mfma_f32_16x16x32_bf16 v[70:73], v[174:177], v[214:217], v[70:73]
	v_mfma_f32_16x16x32_bf16 v[70:73], v[178:181], v[218:221], v[70:73]
	v_mfma_f32_16x16x32_bf16 v[66:69], v[182:185], v[214:217], v[66:69]
	v_mfma_f32_16x16x32_bf16 v[66:69], v[186:189], v[218:221], v[66:69]
	s_setprio 0
	s_barrier
	s_add_i32 s87, s87, 2
	s_add_u32 s26, s26, 0x8000
	s_addc_u32 s27, s27, 0
	s_add_u32 s83, s83, 0x8000
	s_addc_u32 s86, s86, 0
	s_cmp_gt_u32 s87, 61
	s_cbranch_scc0 .LBB0_376
	s_and_b64 vcc, exec, s[14:15]
	s_cbranch_vccz .LBB0_379
	s_barrier

.LBB0_536:
	ds_read_b128 v[130:133], v159
	ds_read_b128 v[162:165], v159 offset:1024
	ds_read_b128 v[166:169], v159 offset:2048
	ds_read_b128 v[170:173], v159 offset:3072
	ds_read_b128 v[174:177], v160
	ds_read_b128 v[178:181], v160 offset:1024
	ds_read_b128 v[182:185], v160 offset:2048
	ds_read_b128 v[186:189], v160 offset:3072
	s_add_u32 s30, s26, 0xfff04000
	s_addc_u32 s31, s27, -1
	s_cmp_eq_u32 s80, 60
	s_cselect_b32 s36, s74, s30
	s_cselect_b32 s37, s21, s31
	s_cselect_b32 s34, s75, s78
	s_cselect_b32 s35, s19, s79
	s_add_u32 s30, s36, 0x4000
	s_addc_u32 s31, s37, 0
	s_add_i32 m0, s42, 0xc000
	ds_read_b128 v[190:193], v161
	ds_read_b128 v[194:197], v161 offset:1024
	ds_read_b128 v[198:201], v161 offset:2048
	ds_read_b128 v[202:205], v161 offset:3072
	ds_read_b128 v[206:209], v161 offset:4096
	ds_read_b128 v[210:213], v161 offset:5120
	ds_read_b128 v[214:217], v161 offset:6144
	ds_read_b128 v[218:221], v161 offset:7168
	global_load_lds_dwordx4 v146, s[26:27]
	s_add_i32 m0, s42, 0xe000
	s_nop 0
	global_load_lds_dwordx4 v148, s[26:27]
	s_waitcnt vmcnt(8)
	s_waitcnt lgkmcnt(0)
	s_barrier
	s_setprio 1
	s_waitcnt lgkmcnt(0)
	v_mfma_f32_16x16x32_bf16 v[62:65], v[130:133], v[190:193], v[62:65]
	v_mfma_f32_16x16x32_bf16 v[62:65], v[162:165], v[194:197], v[62:65]
	v_mfma_f32_16x16x32_bf16 v[58:61], v[166:169], v[190:193], v[58:61]
	v_mfma_f32_16x16x32_bf16 v[58:61], v[170:173], v[194:197], v[58:61]
	v_mfma_f32_16x16x32_bf16 v[54:57], v[130:133], v[198:201], v[54:57]
	v_mfma_f32_16x16x32_bf16 v[54:57], v[162:165], v[202:205], v[54:57]
	v_mfma_f32_16x16x32_bf16 v[50:53], v[166:169], v[198:201], v[50:53]
	v_mfma_f32_16x16x32_bf16 v[50:53], v[170:173], v[202:205], v[50:53]
	v_mfma_f32_16x16x32_bf16 v[46:49], v[130:133], v[206:209], v[46:49]
	v_mfma_f32_16x16x32_bf16 v[46:49], v[162:165], v[210:213], v[46:49]
	v_mfma_f32_16x16x32_bf16 v[42:45], v[166:169], v[206:209], v[42:45]
	v_mfma_f32_16x16x32_bf16 v[42:45], v[170:173], v[210:213], v[42:45]
	v_mfma_f32_16x16x32_bf16 v[38:41], v[130:133], v[214:217], v[38:41]
	v_mfma_f32_16x16x32_bf16 v[38:41], v[162:165], v[218:221], v[38:41]
	v_mfma_f32_16x16x32_bf16 v[34:37], v[166:169], v[214:217], v[34:37]
	v_mfma_f32_16x16x32_bf16 v[34:37], v[170:173], v[218:221], v[34:37]
	v_mfma_f32_16x16x32_bf16 v[126:129], v[174:177], v[190:193], v[126:129]
	v_mfma_f32_16x16x32_bf16 v[126:129], v[178:181], v[194:197], v[126:129]
	v_mfma_f32_16x16x32_bf16 v[122:125], v[182:185], v[190:193], v[122:125]
	v_mfma_f32_16x16x32_bf16 v[122:125], v[186:189], v[194:197], v[122:125]
	v_mfma_f32_16x16x32_bf16 v[118:121], v[174:177], v[198:201], v[118:121]
	v_mfma_f32_16x16x32_bf16 v[118:121], v[178:181], v[202:205], v[118:121]
	v_mfma_f32_16x16x32_bf16 v[114:117], v[182:185], v[198:201], v[114:117]
	v_mfma_f32_16x16x32_bf16 v[114:117], v[186:189], v[202:205], v[114:117]
	v_mfma_f32_16x16x32_bf16 v[110:113], v[174:177], v[206:209], v[110:113]
	v_mfma_f32_16x16x32_bf16 v[110:113], v[178:181], v[210:213], v[110:113]
	v_mfma_f32_16x16x32_bf16 v[106:109], v[182:185], v[206:209], v[106:109]
	v_mfma_f32_16x16x32_bf16 v[106:109], v[186:189], v[210:213], v[106:109]
	v_mfma_f32_16x16x32_bf16 v[102:105], v[174:177], v[214:217], v[102:105]
	v_mfma_f32_16x16x32_bf16 v[102:105], v[178:181], v[218:221], v[102:105]
	v_mfma_f32_16x16x32_bf16 v[98:101], v[182:185], v[214:217], v[98:101]
	v_mfma_f32_16x16x32_bf16 v[98:101], v[186:189], v[218:221], v[98:101]
	s_setprio 0
	s_barrier
	s_add_i32 s81, s62, s38
	s_mov_b32 m0, s81
	ds_read_b128 v[190:193], v161 offset:16384
	ds_read_b128 v[194:197], v161 offset:17408
	ds_read_b128 v[198:201], v161 offset:18432
	ds_read_b128 v[202:205], v161 offset:19456
	ds_read_b128 v[206:209], v161 offset:20480
	ds_read_b128 v[210:213], v161 offset:21504
	ds_read_b128 v[214:217], v161 offset:22528
	ds_read_b128 v[218:221], v161 offset:23552
	global_load_lds_dwordx4 v138, s[34:35]
	s_add_i32 m0, s81, 0x2000
	s_add_u32 s86, s34, 0x100000
	s_addc_u32 s87, s35, 0
	s_add_i32 s81, s63, s38
	global_load_lds_dwordx4 v134, s[34:35]
	s_mov_b32 m0, s81
	s_nop 0
	global_load_lds_dwordx4 v138, s[86:87]
	s_add_i32 m0, s81, 0x2000
	s_nop 0
	global_load_lds_dwordx4 v134, s[86:87]
	s_mov_b32 m0, s42
	s_nop 0
	global_load_lds_dwordx4 v140, s[36:37]
	s_mov_b32 m0, s43
	s_nop 0
	global_load_lds_dwordx4 v136, s[36:37]
	s_waitcnt vmcnt(8)
	s_waitcnt lgkmcnt(0)
	s_barrier
	s_setprio 1
	s_waitcnt lgkmcnt(0)
	v_mfma_f32_16x16x32_bf16 v[30:33], v[130:133], v[190:193], v[30:33]
	v_mfma_f32_16x16x32_bf16 v[30:33], v[162:165], v[194:197], v[30:33]
	v_mfma_f32_16x16x32_bf16 v[26:29], v[166:169], v[190:193], v[26:29]
	v_mfma_f32_16x16x32_bf16 v[26:29], v[170:173], v[194:197], v[26:29]
	v_mfma_f32_16x16x32_bf16 v[22:25], v[130:133], v[198:201], v[22:25]
	v_mfma_f32_16x16x32_bf16 v[22:25], v[162:165], v[202:205], v[22:25]
	v_mfma_f32_16x16x32_bf16 v[18:21], v[166:169], v[198:201], v[18:21]
	v_mfma_f32_16x16x32_bf16 v[18:21], v[170:173], v[202:205], v[18:21]
	v_mfma_f32_16x16x32_bf16 v[14:17], v[130:133], v[206:209], v[14:17]
	v_mfma_f32_16x16x32_bf16 v[14:17], v[162:165], v[210:213], v[14:17]
	v_mfma_f32_16x16x32_bf16 v[10:13], v[166:169], v[206:209], v[10:13]
	v_mfma_f32_16x16x32_bf16 v[10:13], v[170:173], v[210:213], v[10:13]
	v_mfma_f32_16x16x32_bf16 v[6:9], v[130:133], v[214:217], v[6:9]
	v_mfma_f32_16x16x32_bf16 v[6:9], v[162:165], v[218:221], v[6:9]
	v_mfma_f32_16x16x32_bf16 v[2:5], v[166:169], v[214:217], v[2:5]
	v_mfma_f32_16x16x32_bf16 v[2:5], v[170:173], v[218:221], v[2:5]
	v_mfma_f32_16x16x32_bf16 v[94:97], v[174:177], v[190:193], v[94:97]
	v_mfma_f32_16x16x32_bf16 v[94:97], v[178:181], v[194:197], v[94:97]
	v_mfma_f32_16x16x32_bf16 v[90:93], v[182:185], v[190:193], v[90:93]
	v_mfma_f32_16x16x32_bf16 v[90:93], v[186:189], v[194:197], v[90:93]
	v_mfma_f32_16x16x32_bf16 v[86:89], v[174:177], v[198:201], v[86:89]
	v_mfma_f32_16x16x32_bf16 v[86:89], v[178:181], v[202:205], v[86:89]
	v_mfma_f32_16x16x32_bf16 v[82:85], v[182:185], v[198:201], v[82:85]
	v_mfma_f32_16x16x32_bf16 v[82:85], v[186:189], v[202:205], v[82:85]
	v_mfma_f32_16x16x32_bf16 v[78:81], v[174:177], v[206:209], v[78:81]
	v_mfma_f32_16x16x32_bf16 v[78:81], v[178:181], v[210:213], v[78:81]
	v_mfma_f32_16x16x32_bf16 v[74:77], v[182:185], v[206:209], v[74:77]
	v_mfma_f32_16x16x32_bf16 v[74:77], v[186:189], v[210:213], v[74:77]
	v_mfma_f32_16x16x32_bf16 v[70:73], v[174:177], v[214:217], v[70:73]
	v_mfma_f32_16x16x32_bf16 v[70:73], v[178:181], v[218:221], v[70:73]
	v_mfma_f32_16x16x32_bf16 v[66:69], v[182:185], v[214:217], v[66:69]
	v_mfma_f32_16x16x32_bf16 v[66:69], v[186:189], v[218:221], v[66:69]
	s_setprio 0
	s_barrier
	s_add_i32 s81, 0, 0x18000
	v_add_u32_e32 v154, s81, v157
	s_add_i32 s83, 0, 0x1c000
	ds_read_b128 v[130:133], v154
	ds_read_b128 v[162:165], v154 offset:1024
	ds_read_b128 v[166:169], v154 offset:2048
	ds_read_b128 v[170:173], v154 offset:3072
	v_add_u32_e32 v154, s83, v157
	ds_read_b128 v[174:177], v154
	ds_read_b128 v[178:181], v154 offset:1024
	ds_read_b128 v[182:185], v154 offset:2048
	ds_read_b128 v[186:189], v154 offset:3072
	s_add_u32 s36, s36, 0x100000
	s_addc_u32 s37, s37, 0
	s_mov_b32 m0, s46
	ds_read_b128 v[190:193], v161 offset:32768
	ds_read_b128 v[194:197], v161 offset:33792
	ds_read_b128 v[198:201], v161 offset:34816
	ds_read_b128 v[202:205], v161 offset:35840
	ds_read_b128 v[206:209], v161 offset:36864
	ds_read_b128 v[210:213], v161 offset:37888
	ds_read_b128 v[214:217], v161 offset:38912
	ds_read_b128 v[218:221], v161 offset:39936
	global_load_lds_dwordx4 v140, s[36:37]
	s_mov_b32 m0, s47
	s_nop 0
	global_load_lds_dwordx4 v136, s[36:37]
	s_waitcnt vmcnt(8)
	s_waitcnt lgkmcnt(0)
	s_barrier
	s_setprio 1
	s_waitcnt lgkmcnt(0)
	v_mfma_f32_16x16x32_bf16 v[62:65], v[130:133], v[190:193], v[62:65]
	v_mfma_f32_16x16x32_bf16 v[62:65], v[162:165], v[194:197], v[62:65]
	v_mfma_f32_16x16x32_bf16 v[58:61], v[166:169], v[190:193], v[58:61]
	v_mfma_f32_16x16x32_bf16 v[58:61], v[170:173], v[194:197], v[58:61]
	v_mfma_f32_16x16x32_bf16 v[54:57], v[130:133], v[198:201], v[54:57]
	v_mfma_f32_16x16x32_bf16 v[54:57], v[162:165], v[202:205], v[54:57]
	v_mfma_f32_16x16x32_bf16 v[50:53], v[166:169], v[198:201], v[50:53]
	v_mfma_f32_16x16x32_bf16 v[50:53], v[170:173], v[202:205], v[50:53]
	v_mfma_f32_16x16x32_bf16 v[46:49], v[130:133], v[206:209], v[46:49]
	v_mfma_f32_16x16x32_bf16 v[46:49], v[162:165], v[210:213], v[46:49]
	v_mfma_f32_16x16x32_bf16 v[42:45], v[166:169], v[206:209], v[42:45]
	v_mfma_f32_16x16x32_bf16 v[42:45], v[170:173], v[210:213], v[42:45]
	v_mfma_f32_16x16x32_bf16 v[38:41], v[130:133], v[214:217], v[38:41]
	v_mfma_f32_16x16x32_bf16 v[38:41], v[162:165], v[218:221], v[38:41]
	v_mfma_f32_16x16x32_bf16 v[34:37], v[166:169], v[214:217], v[34:37]
	v_mfma_f32_16x16x32_bf16 v[34:37], v[170:173], v[218:221], v[34:37]
	v_mfma_f32_16x16x32_bf16 v[126:129], v[174:177], v[190:193], v[126:129]
	v_mfma_f32_16x16x32_bf16 v[126:129], v[178:181], v[194:197], v[126:129]
	v_mfma_f32_16x16x32_bf16 v[122:125], v[182:185], v[190:193], v[122:125]
	v_mfma_f32_16x16x32_bf16 v[122:125], v[186:189], v[194:197], v[122:125]
	v_mfma_f32_16x16x32_bf16 v[118:121], v[174:177], v[198:201], v[118:121]
	v_mfma_f32_16x16x32_bf16 v[118:121], v[178:181], v[202:205], v[118:121]
	v_mfma_f32_16x16x32_bf16 v[114:117], v[182:185], v[198:201], v[114:117]
	v_mfma_f32_16x16x32_bf16 v[114:117], v[186:189], v[202:205], v[114:117]
	v_mfma_f32_16x16x32_bf16 v[110:113], v[174:177], v[206:209], v[110:113]
	v_mfma_f32_16x16x32_bf16 v[110:113], v[178:181], v[210:213], v[110:113]
	v_mfma_f32_16x16x32_bf16 v[106:109], v[182:185], v[206:209], v[106:109]
	v_mfma_f32_16x16x32_bf16 v[106:109], v[186:189], v[210:213], v[106:109]
	v_mfma_f32_16x16x32_bf16 v[102:105], v[174:177], v[214:217], v[102:105]
	v_mfma_f32_16x16x32_bf16 v[102:105], v[178:181], v[218:221], v[102:105]
	v_mfma_f32_16x16x32_bf16 v[98:101], v[182:185], v[214:217], v[98:101]
	v_mfma_f32_16x16x32_bf16 v[98:101], v[186:189], v[218:221], v[98:101]
	s_setprio 0
	s_barrier
	s_add_u32 s36, s34, 0x4000
	s_addc_u32 s37, s35, 0
	s_add_i32 s81, s81, s38
	s_mov_b32 m0, s81
	ds_read_b128 v[190:193], v161 offset:49152
	ds_read_b128 v[194:197], v161 offset:50176
	ds_read_b128 v[198:201], v161 offset:51200
	ds_read_b128 v[202:205], v161 offset:52224
	ds_read_b128 v[206:209], v161 offset:53248
	ds_read_b128 v[210:213], v161 offset:54272
	ds_read_b128 v[214:217], v161 offset:55296
	ds_read_b128 v[218:221], v161 offset:56320
	global_load_lds_dwordx4 v138, s[36:37]
	s_add_i32 m0, s81, 0x2000
	s_add_u32 s34, s34, 0x104000
	s_addc_u32 s35, s35, 0
	global_load_lds_dwordx4 v134, s[36:37]
	s_add_i32 s36, s83, s38
	s_mov_b32 m0, s36
	s_nop 0
	global_load_lds_dwordx4 v138, s[34:35]
	s_add_i32 m0, s36, 0x2000
	s_nop 0
	global_load_lds_dwordx4 v134, s[34:35]
	s_mov_b32 m0, s58
	s_nop 0
	global_load_lds_dwordx4 v140, s[30:31]
	s_mov_b32 m0, s59
	s_nop 0
	global_load_lds_dwordx4 v136, s[30:31]
	s_waitcnt vmcnt(8)
	s_waitcnt lgkmcnt(0)
	s_barrier
	s_setprio 1
	s_waitcnt lgkmcnt(0)
	v_mfma_f32_16x16x32_bf16 v[30:33], v[130:133], v[190:193], v[30:33]
	v_mfma_f32_16x16x32_bf16 v[30:33], v[162:165], v[194:197], v[30:33]
	v_mfma_f32_16x16x32_bf16 v[26:29], v[166:169], v[190:193], v[26:29]
	v_mfma_f32_16x16x32_bf16 v[26:29], v[170:173], v[194:197], v[26:29]
	v_mfma_f32_16x16x32_bf16 v[22:25], v[130:133], v[198:201], v[22:25]
	v_mfma_f32_16x16x32_bf16 v[22:25], v[162:165], v[202:205], v[22:25]
	v_mfma_f32_16x16x32_bf16 v[18:21], v[166:169], v[198:201], v[18:21]
	v_mfma_f32_16x16x32_bf16 v[18:21], v[170:173], v[202:205], v[18:21]
	v_mfma_f32_16x16x32_bf16 v[14:17], v[130:133], v[206:209], v[14:17]
	v_mfma_f32_16x16x32_bf16 v[14:17], v[162:165], v[210:213], v[14:17]
	v_mfma_f32_16x16x32_bf16 v[10:13], v[166:169], v[206:209], v[10:13]
	v_mfma_f32_16x16x32_bf16 v[10:13], v[170:173], v[210:213], v[10:13]
	v_mfma_f32_16x16x32_bf16 v[6:9], v[130:133], v[214:217], v[6:9]
	v_mfma_f32_16x16x32_bf16 v[6:9], v[162:165], v[218:221], v[6:9]
	v_mfma_f32_16x16x32_bf16 v[2:5], v[166:169], v[214:217], v[2:5]
	v_mfma_f32_16x16x32_bf16 v[2:5], v[170:173], v[218:221], v[2:5]
	v_mfma_f32_16x16x32_bf16 v[94:97], v[174:177], v[190:193], v[94:97]
	v_mfma_f32_16x16x32_bf16 v[94:97], v[178:181], v[194:197], v[94:97]
	v_mfma_f32_16x16x32_bf16 v[90:93], v[182:185], v[190:193], v[90:93]
	v_mfma_f32_16x16x32_bf16 v[90:93], v[186:189], v[194:197], v[90:93]
	v_mfma_f32_16x16x32_bf16 v[86:89], v[174:177], v[198:201], v[86:89]
	v_mfma_f32_16x16x32_bf16 v[86:89], v[178:181], v[202:205], v[86:89]
	v_mfma_f32_16x16x32_bf16 v[82:85], v[182:185], v[198:201], v[82:85]
	v_mfma_f32_16x16x32_bf16 v[82:85], v[186:189], v[202:205], v[82:85]
	v_mfma_f32_16x16x32_bf16 v[78:81], v[174:177], v[206:209], v[78:81]
	v_mfma_f32_16x16x32_bf16 v[78:81], v[178:181], v[210:213], v[78:81]
	v_mfma_f32_16x16x32_bf16 v[74:77], v[182:185], v[206:209], v[74:77]
	v_mfma_f32_16x16x32_bf16 v[74:77], v[186:189], v[210:213], v[74:77]
	v_mfma_f32_16x16x32_bf16 v[70:73], v[174:177], v[214:217], v[70:73]
	v_mfma_f32_16x16x32_bf16 v[70:73], v[178:181], v[218:221], v[70:73]
	v_mfma_f32_16x16x32_bf16 v[66:69], v[182:185], v[214:217], v[66:69]
	v_mfma_f32_16x16x32_bf16 v[66:69], v[186:189], v[218:221], v[66:69]
	s_setprio 0
	s_barrier
	s_add_i32 s80, s80, 2
	s_add_u32 s26, s26, 0x8000
	s_addc_u32 s27, s27, 0
	s_add_u32 s78, s78, 0x8000
	s_addc_u32 s79, s79, 0
	s_cmp_gt_u32 s80, 61
	s_cbranch_scc0 .LBB0_536
	s_and_b64 vcc, exec, s[14:15]
	s_cbranch_vccz .LBB0_539
	s_barrier

.LBB0_1005:
	v_add_u32_e32 v142, s46, v200
	v_add_u32_e32 v158, s47, v200
	ds_read_b128 v[130:133], v142
	ds_read_b128 v[134:137], v142 offset:1024
	ds_read_b128 v[138:141], v142 offset:2048
	ds_read_b128 v[142:145], v142 offset:3072
	ds_read_b128 v[146:149], v158
	ds_read_b128 v[150:153], v158 offset:1024
	ds_read_b128 v[154:157], v158 offset:2048
	ds_read_b128 v[158:161], v158 offset:3072
	s_add_i32 s70, s31, 2
	s_add_u32 s26, s24, 0xfff44000
	s_addc_u32 s27, s25, -1
	s_cmp_eq_u32 s67, s31
	s_cselect_b32 s34, s6, s26
	s_cselect_b32 s35, s7, s27
	s_cselect_b32 s30, s20, s68
	s_cselect_b32 s31, s21, s69
	s_add_u32 s26, s34, 0x4000
	s_addc_u32 s27, s35, 0
	s_add_i32 m0, s37, 0xc000
	ds_read_b128 v[162:165], v201
	ds_read_b128 v[166:169], v201 offset:1024
	ds_read_b128 v[170:173], v201 offset:2048
	ds_read_b128 v[174:177], v201 offset:3072
	ds_read_b128 v[202:205], v201 offset:4096
	ds_read_b128 v[206:209], v201 offset:5120
	ds_read_b128 v[210:213], v201 offset:6144
	ds_read_b128 v[214:217], v201 offset:7168
	global_load_lds_dwordx4 v190, s[24:25]
	s_add_i32 m0, s37, 0xe000
	s_nop 0
	global_load_lds_dwordx4 v192, s[24:25]
	s_waitcnt vmcnt(8)
	s_waitcnt lgkmcnt(0)
	s_barrier
	s_setprio 1
	s_waitcnt lgkmcnt(0)
	v_mfma_f32_16x16x32_bf16 v[126:129], v[130:133], v[162:165], v[126:129]
	v_mfma_f32_16x16x32_bf16 v[126:129], v[134:137], v[166:169], v[126:129]
	v_mfma_f32_16x16x32_bf16 v[122:125], v[138:141], v[162:165], v[122:125]
	v_mfma_f32_16x16x32_bf16 v[122:125], v[142:145], v[166:169], v[122:125]
	v_mfma_f32_16x16x32_bf16 v[118:121], v[130:133], v[170:173], v[118:121]
	v_mfma_f32_16x16x32_bf16 v[118:121], v[134:137], v[174:177], v[118:121]
	v_mfma_f32_16x16x32_bf16 v[114:117], v[138:141], v[170:173], v[114:117]
	v_mfma_f32_16x16x32_bf16 v[114:117], v[142:145], v[174:177], v[114:117]
	v_mfma_f32_16x16x32_bf16 v[110:113], v[130:133], v[202:205], v[110:113]
	v_mfma_f32_16x16x32_bf16 v[110:113], v[134:137], v[206:209], v[110:113]
	v_mfma_f32_16x16x32_bf16 v[106:109], v[138:141], v[202:205], v[106:109]
	v_mfma_f32_16x16x32_bf16 v[106:109], v[142:145], v[206:209], v[106:109]
	v_mfma_f32_16x16x32_bf16 v[102:105], v[130:133], v[210:213], v[102:105]
	v_mfma_f32_16x16x32_bf16 v[102:105], v[134:137], v[214:217], v[102:105]
	v_mfma_f32_16x16x32_bf16 v[98:101], v[138:141], v[210:213], v[98:101]
	v_mfma_f32_16x16x32_bf16 v[98:101], v[142:145], v[214:217], v[98:101]
	v_mfma_f32_16x16x32_bf16 v[94:97], v[146:149], v[162:165], v[94:97]
	v_mfma_f32_16x16x32_bf16 v[94:97], v[150:153], v[166:169], v[94:97]
	v_mfma_f32_16x16x32_bf16 v[90:93], v[154:157], v[162:165], v[90:93]
	v_mfma_f32_16x16x32_bf16 v[90:93], v[158:161], v[166:169], v[90:93]
	v_mfma_f32_16x16x32_bf16 v[86:89], v[146:149], v[170:173], v[86:89]
	v_mfma_f32_16x16x32_bf16 v[86:89], v[150:153], v[174:177], v[86:89]
	v_mfma_f32_16x16x32_bf16 v[82:85], v[154:157], v[170:173], v[82:85]
	v_mfma_f32_16x16x32_bf16 v[82:85], v[158:161], v[174:177], v[82:85]
	v_mfma_f32_16x16x32_bf16 v[78:81], v[146:149], v[202:205], v[78:81]
	v_mfma_f32_16x16x32_bf16 v[78:81], v[150:153], v[206:209], v[78:81]
	v_mfma_f32_16x16x32_bf16 v[74:77], v[154:157], v[202:205], v[74:77]
	v_mfma_f32_16x16x32_bf16 v[74:77], v[158:161], v[206:209], v[74:77]
	v_mfma_f32_16x16x32_bf16 v[66:69], v[146:149], v[210:213], v[66:69]
	v_mfma_f32_16x16x32_bf16 v[66:69], v[150:153], v[214:217], v[66:69]
	v_mfma_f32_16x16x32_bf16 v[58:61], v[154:157], v[210:213], v[58:61]
	v_mfma_f32_16x16x32_bf16 v[58:61], v[158:161], v[214:217], v[58:61]
	s_setprio 0
	s_barrier
	s_add_i32 s71, s46, s36
	s_mov_b32 m0, s71
	ds_read_b128 v[162:165], v201 offset:16384
	ds_read_b128 v[166:169], v201 offset:17408
	ds_read_b128 v[170:173], v201 offset:18432
	ds_read_b128 v[174:177], v201 offset:19456
	ds_read_b128 v[202:205], v201 offset:20480
	ds_read_b128 v[206:209], v201 offset:21504
	ds_read_b128 v[210:213], v201 offset:22528
	ds_read_b128 v[214:217], v201 offset:23552
	global_load_lds_dwordx4 v182, s[30:31]
	s_add_i32 m0, s71, 0x2000
	s_add_u32 s72, s30, 0xc0000
	s_addc_u32 s73, s31, 0
	s_add_i32 s71, s47, s36
	global_load_lds_dwordx4 v178, s[30:31]
	s_mov_b32 m0, s71
	s_nop 0
	global_load_lds_dwordx4 v182, s[72:73]
	s_add_i32 m0, s71, 0x2000
	s_nop 0
	global_load_lds_dwordx4 v178, s[72:73]
	s_mov_b32 m0, s37
	s_nop 0
	global_load_lds_dwordx4 v184, s[34:35]
	s_mov_b32 m0, s38
	s_nop 0
	global_load_lds_dwordx4 v180, s[34:35]
	s_waitcnt vmcnt(8)
	s_waitcnt lgkmcnt(0)
	s_barrier
	s_setprio 1
	s_waitcnt lgkmcnt(0)
	v_mfma_f32_16x16x32_bf16 v[70:73], v[130:133], v[162:165], v[70:73]
	v_mfma_f32_16x16x32_bf16 v[70:73], v[134:137], v[166:169], v[70:73]
	v_mfma_f32_16x16x32_bf16 v[62:65], v[138:141], v[162:165], v[62:65]
	v_mfma_f32_16x16x32_bf16 v[62:65], v[142:145], v[166:169], v[62:65]
	v_mfma_f32_16x16x32_bf16 v[54:57], v[130:133], v[170:173], v[54:57]
	v_mfma_f32_16x16x32_bf16 v[54:57], v[134:137], v[174:177], v[54:57]
	v_mfma_f32_16x16x32_bf16 v[50:53], v[138:141], v[170:173], v[50:53]
	v_mfma_f32_16x16x32_bf16 v[50:53], v[142:145], v[174:177], v[50:53]
	v_mfma_f32_16x16x32_bf16 v[46:49], v[130:133], v[202:205], v[46:49]
	v_mfma_f32_16x16x32_bf16 v[46:49], v[134:137], v[206:209], v[46:49]
	v_mfma_f32_16x16x32_bf16 v[42:45], v[138:141], v[202:205], v[42:45]
	v_mfma_f32_16x16x32_bf16 v[42:45], v[142:145], v[206:209], v[42:45]
	v_mfma_f32_16x16x32_bf16 v[38:41], v[130:133], v[210:213], v[38:41]
	v_mfma_f32_16x16x32_bf16 v[38:41], v[134:137], v[214:217], v[38:41]
	v_mfma_f32_16x16x32_bf16 v[34:37], v[138:141], v[210:213], v[34:37]
	v_mfma_f32_16x16x32_bf16 v[34:37], v[142:145], v[214:217], v[34:37]
	v_mfma_f32_16x16x32_bf16 v[30:33], v[146:149], v[162:165], v[30:33]
	v_mfma_f32_16x16x32_bf16 v[30:33], v[150:153], v[166:169], v[30:33]
	v_mfma_f32_16x16x32_bf16 v[26:29], v[154:157], v[162:165], v[26:29]
	v_mfma_f32_16x16x32_bf16 v[26:29], v[158:161], v[166:169], v[26:29]
	v_mfma_f32_16x16x32_bf16 v[22:25], v[146:149], v[170:173], v[22:25]
	v_mfma_f32_16x16x32_bf16 v[22:25], v[150:153], v[174:177], v[22:25]
	v_mfma_f32_16x16x32_bf16 v[18:21], v[154:157], v[170:173], v[18:21]
	v_mfma_f32_16x16x32_bf16 v[18:21], v[158:161], v[174:177], v[18:21]
	v_mfma_f32_16x16x32_bf16 v[14:17], v[146:149], v[202:205], v[14:17]
	v_mfma_f32_16x16x32_bf16 v[14:17], v[150:153], v[206:209], v[14:17]
	v_mfma_f32_16x16x32_bf16 v[10:13], v[154:157], v[202:205], v[10:13]
	v_mfma_f32_16x16x32_bf16 v[10:13], v[158:161], v[206:209], v[10:13]
	v_mfma_f32_16x16x32_bf16 v[6:9], v[146:149], v[210:213], v[6:9]
	v_mfma_f32_16x16x32_bf16 v[6:9], v[150:153], v[214:217], v[6:9]
	v_mfma_f32_16x16x32_bf16 v[2:5], v[154:157], v[210:213], v[2:5]
	v_mfma_f32_16x16x32_bf16 v[2:5], v[158:161], v[214:217], v[2:5]
	s_setprio 0
	s_barrier
	s_add_i32 s71, 0, 0x18000
	s_add_i32 s72, 0, 0x1c000
	v_add_u32_e32 v142, s71, v200
	v_add_u32_e32 v158, s72, v200
	ds_read_b128 v[130:133], v142
	ds_read_b128 v[134:137], v142 offset:1024
	ds_read_b128 v[138:141], v142 offset:2048
	ds_read_b128 v[142:145], v142 offset:3072
	ds_read_b128 v[146:149], v158
	ds_read_b128 v[150:153], v158 offset:1024
	ds_read_b128 v[154:157], v158 offset:2048
	ds_read_b128 v[158:161], v158 offset:3072
	s_add_u32 s34, s34, 0xc0000
	s_addc_u32 s35, s35, 0
	s_mov_b32 m0, s39
	ds_read_b128 v[162:165], v201 offset:32768
	ds_read_b128 v[166:169], v201 offset:33792
	ds_read_b128 v[170:173], v201 offset:34816
	ds_read_b128 v[174:177], v201 offset:35840
	ds_read_b128 v[202:205], v201 offset:36864
	ds_read_b128 v[206:209], v201 offset:37888
	ds_read_b128 v[210:213], v201 offset:38912
	ds_read_b128 v[214:217], v201 offset:39936
	global_load_lds_dwordx4 v184, s[34:35]
	s_mov_b32 m0, s40
	s_nop 0
	global_load_lds_dwordx4 v180, s[34:35]
	s_waitcnt vmcnt(8)
	s_waitcnt lgkmcnt(0)
	s_barrier
	s_setprio 1
	s_waitcnt lgkmcnt(0)
	v_mfma_f32_16x16x32_bf16 v[126:129], v[130:133], v[162:165], v[126:129]
	v_mfma_f32_16x16x32_bf16 v[126:129], v[134:137], v[166:169], v[126:129]
	v_mfma_f32_16x16x32_bf16 v[122:125], v[138:141], v[162:165], v[122:125]
	v_mfma_f32_16x16x32_bf16 v[122:125], v[142:145], v[166:169], v[122:125]
	v_mfma_f32_16x16x32_bf16 v[118:121], v[130:133], v[170:173], v[118:121]
	v_mfma_f32_16x16x32_bf16 v[118:121], v[134:137], v[174:177], v[118:121]
	v_mfma_f32_16x16x32_bf16 v[114:117], v[138:141], v[170:173], v[114:117]
	v_mfma_f32_16x16x32_bf16 v[114:117], v[142:145], v[174:177], v[114:117]
	v_mfma_f32_16x16x32_bf16 v[110:113], v[130:133], v[202:205], v[110:113]
	v_mfma_f32_16x16x32_bf16 v[110:113], v[134:137], v[206:209], v[110:113]
	v_mfma_f32_16x16x32_bf16 v[106:109], v[138:141], v[202:205], v[106:109]
	v_mfma_f32_16x16x32_bf16 v[106:109], v[142:145], v[206:209], v[106:109]
	v_mfma_f32_16x16x32_bf16 v[102:105], v[130:133], v[210:213], v[102:105]
	v_mfma_f32_16x16x32_bf16 v[102:105], v[134:137], v[214:217], v[102:105]
	v_mfma_f32_16x16x32_bf16 v[98:101], v[138:141], v[210:213], v[98:101]
	v_mfma_f32_16x16x32_bf16 v[98:101], v[142:145], v[214:217], v[98:101]
	v_mfma_f32_16x16x32_bf16 v[94:97], v[146:149], v[162:165], v[94:97]
	v_mfma_f32_16x16x32_bf16 v[94:97], v[150:153], v[166:169], v[94:97]
	v_mfma_f32_16x16x32_bf16 v[90:93], v[154:157], v[162:165], v[90:93]
	v_mfma_f32_16x16x32_bf16 v[90:93], v[158:161], v[166:169], v[90:93]
	v_mfma_f32_16x16x32_bf16 v[86:89], v[146:149], v[170:173], v[86:89]
	v_mfma_f32_16x16x32_bf16 v[86:89], v[150:153], v[174:177], v[86:89]
	v_mfma_f32_16x16x32_bf16 v[82:85], v[154:157], v[170:173], v[82:85]
	v_mfma_f32_16x16x32_bf16 v[82:85], v[158:161], v[174:177], v[82:85]
	v_mfma_f32_16x16x32_bf16 v[78:81], v[146:149], v[202:205], v[78:81]
	v_mfma_f32_16x16x32_bf16 v[78:81], v[150:153], v[206:209], v[78:81]
	v_mfma_f32_16x16x32_bf16 v[74:77], v[154:157], v[202:205], v[74:77]
	v_mfma_f32_16x16x32_bf16 v[74:77], v[158:161], v[206:209], v[74:77]
	v_mfma_f32_16x16x32_bf16 v[66:69], v[146:149], v[210:213], v[66:69]
	v_mfma_f32_16x16x32_bf16 v[66:69], v[150:153], v[214:217], v[66:69]
	v_mfma_f32_16x16x32_bf16 v[58:61], v[154:157], v[210:213], v[58:61]
	v_mfma_f32_16x16x32_bf16 v[58:61], v[158:161], v[214:217], v[58:61]
	s_setprio 0
	s_barrier
	s_add_u32 s34, s30, 0x4000
	s_addc_u32 s35, s31, 0
	s_add_i32 s71, s71, s36
	s_mov_b32 m0, s71
	ds_read_b128 v[162:165], v201 offset:49152
	ds_read_b128 v[166:169], v201 offset:50176
	ds_read_b128 v[170:173], v201 offset:51200
	ds_read_b128 v[174:177], v201 offset:52224
	ds_read_b128 v[202:205], v201 offset:53248
	ds_read_b128 v[206:209], v201 offset:54272
	ds_read_b128 v[210:213], v201 offset:55296
	ds_read_b128 v[214:217], v201 offset:56320
	global_load_lds_dwordx4 v182, s[34:35]
	s_add_i32 m0, s71, 0x2000
	s_add_u32 s30, s30, 0xc4000
	s_addc_u32 s31, s31, 0
	global_load_lds_dwordx4 v178, s[34:35]
	s_add_i32 s34, s72, s36
	s_mov_b32 m0, s34
	s_nop 0
	global_load_lds_dwordx4 v182, s[30:31]
	s_add_i32 m0, s34, 0x2000
	s_nop 0
	global_load_lds_dwordx4 v178, s[30:31]
	s_mov_b32 m0, s42
	s_nop 0
	global_load_lds_dwordx4 v184, s[26:27]
	s_mov_b32 m0, s43
	s_nop 0
	global_load_lds_dwordx4 v180, s[26:27]
	s_waitcnt vmcnt(8)
	s_waitcnt lgkmcnt(0)
	s_barrier
	s_setprio 1
	s_waitcnt lgkmcnt(0)
	v_mfma_f32_16x16x32_bf16 v[70:73], v[130:133], v[162:165], v[70:73]
	v_mfma_f32_16x16x32_bf16 v[70:73], v[134:137], v[166:169], v[70:73]
	v_mfma_f32_16x16x32_bf16 v[62:65], v[138:141], v[162:165], v[62:65]
	v_mfma_f32_16x16x32_bf16 v[62:65], v[142:145], v[166:169], v[62:65]
	v_mfma_f32_16x16x32_bf16 v[54:57], v[130:133], v[170:173], v[54:57]
	v_mfma_f32_16x16x32_bf16 v[54:57], v[134:137], v[174:177], v[54:57]
	v_mfma_f32_16x16x32_bf16 v[50:53], v[138:141], v[170:173], v[50:53]
	v_mfma_f32_16x16x32_bf16 v[50:53], v[142:145], v[174:177], v[50:53]
	v_mfma_f32_16x16x32_bf16 v[46:49], v[130:133], v[202:205], v[46:49]
	v_mfma_f32_16x16x32_bf16 v[46:49], v[134:137], v[206:209], v[46:49]
	v_mfma_f32_16x16x32_bf16 v[42:45], v[138:141], v[202:205], v[42:45]
	v_mfma_f32_16x16x32_bf16 v[42:45], v[142:145], v[206:209], v[42:45]
	v_mfma_f32_16x16x32_bf16 v[38:41], v[130:133], v[210:213], v[38:41]
	v_mfma_f32_16x16x32_bf16 v[38:41], v[134:137], v[214:217], v[38:41]
	v_mfma_f32_16x16x32_bf16 v[34:37], v[138:141], v[210:213], v[34:37]
	v_mfma_f32_16x16x32_bf16 v[34:37], v[142:145], v[214:217], v[34:37]
	v_mfma_f32_16x16x32_bf16 v[30:33], v[146:149], v[162:165], v[30:33]
	v_mfma_f32_16x16x32_bf16 v[30:33], v[150:153], v[166:169], v[30:33]
	v_mfma_f32_16x16x32_bf16 v[26:29], v[154:157], v[162:165], v[26:29]
	v_mfma_f32_16x16x32_bf16 v[26:29], v[158:161], v[166:169], v[26:29]
	v_mfma_f32_16x16x32_bf16 v[22:25], v[146:149], v[170:173], v[22:25]
	v_mfma_f32_16x16x32_bf16 v[22:25], v[150:153], v[174:177], v[22:25]
	v_mfma_f32_16x16x32_bf16 v[18:21], v[154:157], v[170:173], v[18:21]
	v_mfma_f32_16x16x32_bf16 v[18:21], v[158:161], v[174:177], v[18:21]
	v_mfma_f32_16x16x32_bf16 v[14:17], v[146:149], v[202:205], v[14:17]
	v_mfma_f32_16x16x32_bf16 v[14:17], v[150:153], v[206:209], v[14:17]
	v_mfma_f32_16x16x32_bf16 v[10:13], v[154:157], v[202:205], v[10:13]
	v_mfma_f32_16x16x32_bf16 v[10:13], v[158:161], v[206:209], v[10:13]
	v_mfma_f32_16x16x32_bf16 v[6:9], v[146:149], v[210:213], v[6:9]
	v_mfma_f32_16x16x32_bf16 v[6:9], v[150:153], v[214:217], v[6:9]
	v_mfma_f32_16x16x32_bf16 v[2:5], v[154:157], v[210:213], v[2:5]
	v_mfma_f32_16x16x32_bf16 v[2:5], v[158:161], v[214:217], v[2:5]
	s_setprio 0
	s_barrier
	s_add_u32 s24, s24, 0x8000
	s_addc_u32 s25, s25, 0
	s_add_u32 s68, s68, 0x8000
	s_addc_u32 s69, s69, 0
	s_cmp_ge_u32 s70, s66
	s_mov_b32 s31, s70
	s_cbranch_scc0 .LBB0_1005
	s_and_b64 vcc, exec, s[18:19]
	s_cbranch_vccnz .LBB0_1010
	v_lshl_add_u32 v162, s65, 8, v189
	s_mov_b64 s[24:25], -1
	s_and_b64 vcc, exec, s[22:23]
	s_cbranch_vccnz .LBB0_1011

.LBB0_1088:
	ds_read_b128 v[130:133], v209
	ds_read_b128 v[134:137], v209 offset:1024
	ds_read_b128 v[138:141], v209 offset:2048
	ds_read_b128 v[142:145], v209 offset:3072
	ds_read_b128 v[146:149], v210
	ds_read_b128 v[150:153], v210 offset:1024
	ds_read_b128 v[154:157], v210 offset:2048
	ds_read_b128 v[158:161], v210 offset:3072
	s_add_u32 s38, s36, 0xfff04000
	s_addc_u32 s39, s37, -1
	s_cmp_eq_u32 s72, 60
	s_cselect_b32 s42, s35, s38
	s_cselect_b32 s43, s25, s39
	s_cselect_b32 s40, s69, s70
	s_cselect_b32 s41, s23, s71
	s_add_u32 s38, s42, 0x4000
	s_addc_u32 s39, s43, 0
	s_add_i32 m0, s47, 0xc000
	ds_read_b128 v[162:165], v211
	ds_read_b128 v[166:169], v211 offset:1024
	ds_read_b128 v[170:173], v211 offset:2048
	ds_read_b128 v[174:177], v211 offset:3072
	ds_read_b128 v[196:199], v211 offset:4096
	ds_read_b128 v[200:203], v211 offset:5120
	ds_read_b128 v[214:217], v211 offset:6144
	ds_read_b128 v[218:221], v211 offset:7168
	global_load_lds_dwordx4 v188, s[36:37]
	s_add_i32 m0, s47, 0xe000
	s_nop 0
	global_load_lds_dwordx4 v190, s[36:37]
	s_waitcnt vmcnt(8)
	s_waitcnt lgkmcnt(0)
	s_barrier
	s_setprio 1
	s_waitcnt lgkmcnt(0)
	v_mfma_f32_16x16x32_bf16 v[126:129], v[130:133], v[162:165], v[126:129]
	v_mfma_f32_16x16x32_bf16 v[126:129], v[134:137], v[166:169], v[126:129]
	v_mfma_f32_16x16x32_bf16 v[122:125], v[138:141], v[162:165], v[122:125]
	v_mfma_f32_16x16x32_bf16 v[122:125], v[142:145], v[166:169], v[122:125]
	v_mfma_f32_16x16x32_bf16 v[110:113], v[130:133], v[170:173], v[110:113]
	v_mfma_f32_16x16x32_bf16 v[110:113], v[134:137], v[174:177], v[110:113]
	v_mfma_f32_16x16x32_bf16 v[106:109], v[138:141], v[170:173], v[106:109]
	v_mfma_f32_16x16x32_bf16 v[106:109], v[142:145], v[174:177], v[106:109]
	v_mfma_f32_16x16x32_bf16 v[94:97], v[130:133], v[196:199], v[94:97]
	v_mfma_f32_16x16x32_bf16 v[94:97], v[134:137], v[200:203], v[94:97]
	v_mfma_f32_16x16x32_bf16 v[90:93], v[138:141], v[196:199], v[90:93]
	v_mfma_f32_16x16x32_bf16 v[90:93], v[142:145], v[200:203], v[90:93]
	v_mfma_f32_16x16x32_bf16 v[78:81], v[130:133], v[214:217], v[78:81]
	v_mfma_f32_16x16x32_bf16 v[78:81], v[134:137], v[218:221], v[78:81]
	v_mfma_f32_16x16x32_bf16 v[74:77], v[138:141], v[214:217], v[74:77]
	v_mfma_f32_16x16x32_bf16 v[74:77], v[142:145], v[218:221], v[74:77]
	v_mfma_f32_16x16x32_bf16 v[118:121], v[146:149], v[162:165], v[118:121]
	v_mfma_f32_16x16x32_bf16 v[118:121], v[150:153], v[166:169], v[118:121]
	v_mfma_f32_16x16x32_bf16 v[114:117], v[154:157], v[162:165], v[114:117]
	v_mfma_f32_16x16x32_bf16 v[114:117], v[158:161], v[166:169], v[114:117]
	v_mfma_f32_16x16x32_bf16 v[102:105], v[146:149], v[170:173], v[102:105]
	v_mfma_f32_16x16x32_bf16 v[102:105], v[150:153], v[174:177], v[102:105]
	v_mfma_f32_16x16x32_bf16 v[98:101], v[154:157], v[170:173], v[98:101]
	v_mfma_f32_16x16x32_bf16 v[98:101], v[158:161], v[174:177], v[98:101]
	v_mfma_f32_16x16x32_bf16 v[86:89], v[146:149], v[196:199], v[86:89]
	v_mfma_f32_16x16x32_bf16 v[86:89], v[150:153], v[200:203], v[86:89]
	v_mfma_f32_16x16x32_bf16 v[82:85], v[154:157], v[196:199], v[82:85]
	v_mfma_f32_16x16x32_bf16 v[82:85], v[158:161], v[200:203], v[82:85]
	v_mfma_f32_16x16x32_bf16 v[70:73], v[146:149], v[214:217], v[70:73]
	v_mfma_f32_16x16x32_bf16 v[70:73], v[150:153], v[218:221], v[70:73]
	v_mfma_f32_16x16x32_bf16 v[66:69], v[154:157], v[214:217], v[66:69]
	v_mfma_f32_16x16x32_bf16 v[66:69], v[158:161], v[218:221], v[66:69]
	s_setprio 0
	s_barrier
	s_add_i32 s73, s66, s46
	s_mov_b32 m0, s73
	ds_read_b128 v[162:165], v211 offset:16384
	ds_read_b128 v[166:169], v211 offset:17408
	ds_read_b128 v[170:173], v211 offset:18432
	ds_read_b128 v[174:177], v211 offset:19456
	ds_read_b128 v[196:199], v211 offset:20480
	ds_read_b128 v[200:203], v211 offset:21504
	ds_read_b128 v[214:217], v211 offset:22528
	ds_read_b128 v[218:221], v211 offset:23552
	global_load_lds_dwordx4 v180, s[40:41]
	s_add_i32 m0, s73, 0x2000
	s_add_u32 s74, s40, 0x100000
	s_addc_u32 s75, s41, 0
	s_add_i32 s73, s67, s46
	global_load_lds_dwordx4 v184, s[40:41]
	s_mov_b32 m0, s73
	s_nop 0
	global_load_lds_dwordx4 v180, s[74:75]
	s_add_i32 m0, s73, 0x2000
	s_nop 0
	global_load_lds_dwordx4 v184, s[74:75]
	s_mov_b32 m0, s47
	s_nop 0
	global_load_lds_dwordx4 v178, s[42:43]
	s_mov_b32 m0, s59
	s_nop 0
	global_load_lds_dwordx4 v182, s[42:43]
	s_waitcnt vmcnt(8)
	s_waitcnt lgkmcnt(0)
	s_barrier
	s_setprio 1
	s_waitcnt lgkmcnt(0)
	v_mfma_f32_16x16x32_bf16 v[62:65], v[130:133], v[162:165], v[62:65]
	v_mfma_f32_16x16x32_bf16 v[62:65], v[134:137], v[166:169], v[62:65]
	v_mfma_f32_16x16x32_bf16 v[58:61], v[138:141], v[162:165], v[58:61]
	v_mfma_f32_16x16x32_bf16 v[58:61], v[142:145], v[166:169], v[58:61]
	v_mfma_f32_16x16x32_bf16 v[46:49], v[130:133], v[170:173], v[46:49]
	v_mfma_f32_16x16x32_bf16 v[46:49], v[134:137], v[174:177], v[46:49]
	v_mfma_f32_16x16x32_bf16 v[42:45], v[138:141], v[170:173], v[42:45]
	v_mfma_f32_16x16x32_bf16 v[42:45], v[142:145], v[174:177], v[42:45]
	v_mfma_f32_16x16x32_bf16 v[30:33], v[130:133], v[196:199], v[30:33]
	v_mfma_f32_16x16x32_bf16 v[30:33], v[134:137], v[200:203], v[30:33]
	v_mfma_f32_16x16x32_bf16 v[26:29], v[138:141], v[196:199], v[26:29]
	v_mfma_f32_16x16x32_bf16 v[26:29], v[142:145], v[200:203], v[26:29]
	v_mfma_f32_16x16x32_bf16 v[14:17], v[130:133], v[214:217], v[14:17]
	v_mfma_f32_16x16x32_bf16 v[14:17], v[134:137], v[218:221], v[14:17]
	v_mfma_f32_16x16x32_bf16 v[10:13], v[138:141], v[214:217], v[10:13]
	v_mfma_f32_16x16x32_bf16 v[10:13], v[142:145], v[218:221], v[10:13]
	v_mfma_f32_16x16x32_bf16 v[54:57], v[146:149], v[162:165], v[54:57]
	v_mfma_f32_16x16x32_bf16 v[54:57], v[150:153], v[166:169], v[54:57]
	v_mfma_f32_16x16x32_bf16 v[50:53], v[154:157], v[162:165], v[50:53]
	v_mfma_f32_16x16x32_bf16 v[50:53], v[158:161], v[166:169], v[50:53]
	v_mfma_f32_16x16x32_bf16 v[38:41], v[146:149], v[170:173], v[38:41]
	v_mfma_f32_16x16x32_bf16 v[38:41], v[150:153], v[174:177], v[38:41]
	v_mfma_f32_16x16x32_bf16 v[34:37], v[154:157], v[170:173], v[34:37]
	v_mfma_f32_16x16x32_bf16 v[34:37], v[158:161], v[174:177], v[34:37]
	v_mfma_f32_16x16x32_bf16 v[22:25], v[146:149], v[196:199], v[22:25]
	v_mfma_f32_16x16x32_bf16 v[22:25], v[150:153], v[200:203], v[22:25]
	v_mfma_f32_16x16x32_bf16 v[18:21], v[154:157], v[196:199], v[18:21]
	v_mfma_f32_16x16x32_bf16 v[18:21], v[158:161], v[200:203], v[18:21]
	v_mfma_f32_16x16x32_bf16 v[6:9], v[146:149], v[214:217], v[6:9]
	v_mfma_f32_16x16x32_bf16 v[6:9], v[150:153], v[218:221], v[6:9]
	v_mfma_f32_16x16x32_bf16 v[2:5], v[154:157], v[214:217], v[2:5]
	v_mfma_f32_16x16x32_bf16 v[2:5], v[158:161], v[218:221], v[2:5]
	s_setprio 0
	s_barrier
	s_add_i32 s73, 0, 0x18000
	s_add_i32 s74, 0, 0x1c000
	v_add_u32_e32 v142, s73, v208
	v_add_u32_e32 v158, s74, v208
	ds_read_b128 v[130:133], v142
	ds_read_b128 v[134:137], v142 offset:1024
	ds_read_b128 v[138:141], v142 offset:2048
	ds_read_b128 v[142:145], v142 offset:3072
	ds_read_b128 v[146:149], v158
	ds_read_b128 v[150:153], v158 offset:1024
	ds_read_b128 v[154:157], v158 offset:2048
	ds_read_b128 v[158:161], v158 offset:3072
	s_add_u32 s42, s42, 0x100000
	s_addc_u32 s43, s43, 0
	s_mov_b32 m0, s60
	ds_read_b128 v[162:165], v211 offset:32768
	ds_read_b128 v[166:169], v211 offset:33792
	ds_read_b128 v[170:173], v211 offset:34816
	ds_read_b128 v[174:177], v211 offset:35840
	ds_read_b128 v[196:199], v211 offset:36864
	ds_read_b128 v[200:203], v211 offset:37888
	ds_read_b128 v[214:217], v211 offset:38912
	ds_read_b128 v[218:221], v211 offset:39936
	global_load_lds_dwordx4 v178, s[42:43]
	s_mov_b32 m0, s61
	s_nop 0
	global_load_lds_dwordx4 v182, s[42:43]
	s_waitcnt vmcnt(8)
	s_waitcnt lgkmcnt(0)
	s_barrier
	s_setprio 1
	s_waitcnt lgkmcnt(0)
	v_mfma_f32_16x16x32_bf16 v[126:129], v[130:133], v[162:165], v[126:129]
	v_mfma_f32_16x16x32_bf16 v[126:129], v[134:137], v[166:169], v[126:129]
	v_mfma_f32_16x16x32_bf16 v[122:125], v[138:141], v[162:165], v[122:125]
	v_mfma_f32_16x16x32_bf16 v[122:125], v[142:145], v[166:169], v[122:125]
	v_mfma_f32_16x16x32_bf16 v[110:113], v[130:133], v[170:173], v[110:113]
	v_mfma_f32_16x16x32_bf16 v[110:113], v[134:137], v[174:177], v[110:113]
	v_mfma_f32_16x16x32_bf16 v[106:109], v[138:141], v[170:173], v[106:109]
	v_mfma_f32_16x16x32_bf16 v[106:109], v[142:145], v[174:177], v[106:109]
	v_mfma_f32_16x16x32_bf16 v[94:97], v[130:133], v[196:199], v[94:97]
	v_mfma_f32_16x16x32_bf16 v[94:97], v[134:137], v[200:203], v[94:97]
	v_mfma_f32_16x16x32_bf16 v[90:93], v[138:141], v[196:199], v[90:93]
	v_mfma_f32_16x16x32_bf16 v[90:93], v[142:145], v[200:203], v[90:93]
	v_mfma_f32_16x16x32_bf16 v[78:81], v[130:133], v[214:217], v[78:81]
	v_mfma_f32_16x16x32_bf16 v[78:81], v[134:137], v[218:221], v[78:81]
	v_mfma_f32_16x16x32_bf16 v[74:77], v[138:141], v[214:217], v[74:77]
	v_mfma_f32_16x16x32_bf16 v[74:77], v[142:145], v[218:221], v[74:77]
	v_mfma_f32_16x16x32_bf16 v[118:121], v[146:149], v[162:165], v[118:121]
	v_mfma_f32_16x16x32_bf16 v[118:121], v[150:153], v[166:169], v[118:121]
	v_mfma_f32_16x16x32_bf16 v[114:117], v[154:157], v[162:165], v[114:117]
	v_mfma_f32_16x16x32_bf16 v[114:117], v[158:161], v[166:169], v[114:117]
	v_mfma_f32_16x16x32_bf16 v[102:105], v[146:149], v[170:173], v[102:105]
	v_mfma_f32_16x16x32_bf16 v[102:105], v[150:153], v[174:177], v[102:105]
	v_mfma_f32_16x16x32_bf16 v[98:101], v[154:157], v[170:173], v[98:101]
	v_mfma_f32_16x16x32_bf16 v[98:101], v[158:161], v[174:177], v[98:101]
	v_mfma_f32_16x16x32_bf16 v[86:89], v[146:149], v[196:199], v[86:89]
	v_mfma_f32_16x16x32_bf16 v[86:89], v[150:153], v[200:203], v[86:89]
	v_mfma_f32_16x16x32_bf16 v[82:85], v[154:157], v[196:199], v[82:85]
	v_mfma_f32_16x16x32_bf16 v[82:85], v[158:161], v[200:203], v[82:85]
	v_mfma_f32_16x16x32_bf16 v[70:73], v[146:149], v[214:217], v[70:73]
	v_mfma_f32_16x16x32_bf16 v[70:73], v[150:153], v[218:221], v[70:73]
	v_mfma_f32_16x16x32_bf16 v[66:69], v[154:157], v[214:217], v[66:69]
	v_mfma_f32_16x16x32_bf16 v[66:69], v[158:161], v[218:221], v[66:69]
	s_setprio 0
	s_barrier
	s_add_u32 s42, s40, 0x4000
	s_addc_u32 s43, s41, 0
	s_add_i32 s73, s73, s46
	s_mov_b32 m0, s73
	ds_read_b128 v[162:165], v211 offset:49152
	ds_read_b128 v[166:169], v211 offset:50176
	ds_read_b128 v[170:173], v211 offset:51200
	ds_read_b128 v[174:177], v211 offset:52224
	ds_read_b128 v[196:199], v211 offset:53248
	ds_read_b128 v[200:203], v211 offset:54272
	ds_read_b128 v[214:217], v211 offset:55296
	ds_read_b128 v[218:221], v211 offset:56320
	global_load_lds_dwordx4 v180, s[42:43]
	s_add_i32 m0, s73, 0x2000
	s_add_u32 s40, s40, 0x104000
	s_addc_u32 s41, s41, 0
	global_load_lds_dwordx4 v184, s[42:43]
	s_add_i32 s42, s74, s46
	s_mov_b32 m0, s42
	s_nop 0
	global_load_lds_dwordx4 v180, s[40:41]
	s_add_i32 m0, s42, 0x2000
	s_nop 0
	global_load_lds_dwordx4 v184, s[40:41]
	s_mov_b32 m0, s64
	s_nop 0
	global_load_lds_dwordx4 v178, s[38:39]
	s_mov_b32 m0, s65
	s_nop 0
	global_load_lds_dwordx4 v182, s[38:39]
	s_waitcnt vmcnt(8)
	s_waitcnt lgkmcnt(0)
	s_barrier
	s_setprio 1
	s_waitcnt lgkmcnt(0)
	v_mfma_f32_16x16x32_bf16 v[62:65], v[130:133], v[162:165], v[62:65]
	v_mfma_f32_16x16x32_bf16 v[62:65], v[134:137], v[166:169], v[62:65]
	v_mfma_f32_16x16x32_bf16 v[58:61], v[138:141], v[162:165], v[58:61]
	v_mfma_f32_16x16x32_bf16 v[58:61], v[142:145], v[166:169], v[58:61]
	v_mfma_f32_16x16x32_bf16 v[46:49], v[130:133], v[170:173], v[46:49]
	v_mfma_f32_16x16x32_bf16 v[46:49], v[134:137], v[174:177], v[46:49]
	v_mfma_f32_16x16x32_bf16 v[42:45], v[138:141], v[170:173], v[42:45]
	v_mfma_f32_16x16x32_bf16 v[42:45], v[142:145], v[174:177], v[42:45]
	v_mfma_f32_16x16x32_bf16 v[30:33], v[130:133], v[196:199], v[30:33]
	v_mfma_f32_16x16x32_bf16 v[30:33], v[134:137], v[200:203], v[30:33]
	v_mfma_f32_16x16x32_bf16 v[26:29], v[138:141], v[196:199], v[26:29]
	v_mfma_f32_16x16x32_bf16 v[26:29], v[142:145], v[200:203], v[26:29]
	v_mfma_f32_16x16x32_bf16 v[14:17], v[130:133], v[214:217], v[14:17]
	v_mfma_f32_16x16x32_bf16 v[14:17], v[134:137], v[218:221], v[14:17]
	v_mfma_f32_16x16x32_bf16 v[10:13], v[138:141], v[214:217], v[10:13]
	v_mfma_f32_16x16x32_bf16 v[10:13], v[142:145], v[218:221], v[10:13]
	v_mfma_f32_16x16x32_bf16 v[54:57], v[146:149], v[162:165], v[54:57]
	v_mfma_f32_16x16x32_bf16 v[54:57], v[150:153], v[166:169], v[54:57]
	v_mfma_f32_16x16x32_bf16 v[50:53], v[154:157], v[162:165], v[50:53]
	v_mfma_f32_16x16x32_bf16 v[50:53], v[158:161], v[166:169], v[50:53]
	v_mfma_f32_16x16x32_bf16 v[38:41], v[146:149], v[170:173], v[38:41]
	v_mfma_f32_16x16x32_bf16 v[38:41], v[150:153], v[174:177], v[38:41]
	v_mfma_f32_16x16x32_bf16 v[34:37], v[154:157], v[170:173], v[34:37]
	v_mfma_f32_16x16x32_bf16 v[34:37], v[158:161], v[174:177], v[34:37]
	v_mfma_f32_16x16x32_bf16 v[22:25], v[146:149], v[196:199], v[22:25]
	v_mfma_f32_16x16x32_bf16 v[22:25], v[150:153], v[200:203], v[22:25]
	v_mfma_f32_16x16x32_bf16 v[18:21], v[154:157], v[196:199], v[18:21]
	v_mfma_f32_16x16x32_bf16 v[18:21], v[158:161], v[200:203], v[18:21]
	v_mfma_f32_16x16x32_bf16 v[6:9], v[146:149], v[214:217], v[6:9]
	v_mfma_f32_16x16x32_bf16 v[6:9], v[150:153], v[218:221], v[6:9]
	v_mfma_f32_16x16x32_bf16 v[2:5], v[154:157], v[214:217], v[2:5]
	v_mfma_f32_16x16x32_bf16 v[2:5], v[158:161], v[218:221], v[2:5]
	s_setprio 0
	s_barrier
	s_add_i32 s72, s72, 2
	s_add_u32 s36, s36, 0x8000
	s_addc_u32 s37, s37, 0
	s_add_u32 s70, s70, 0x8000
	s_addc_u32 s71, s71, 0
	s_cmp_gt_u32 s72, 61
	s_cbranch_scc0 .LBB0_1088
	s_and_b64 vcc, exec, s[20:21]
	s_cbranch_vccz .LBB0_1091
	s_barrier

.LBB0_1125:
	s_ashr_i32 s27, s26, 31
	s_lshl_b64 s[28:29], s[26:27], 17
	v_readlane_b32 s30, v251, 19
	v_readlane_b32 s31, v251, 20
	s_add_u32 s28, s30, s28
	s_addc_u32 s29, s31, s29
	s_and_b64 s[30:31], s[6:7], exec
	s_waitcnt lgkmcnt(0)
	ds_read_b128 v[2:5], v149
	ds_read_b128 v[6:9], v149 offset:1024
	ds_read_b128 v[10:13], v149 offset:2048
	ds_read_b128 v[14:17], v149 offset:3072
	ds_read_b128 v[18:21], v150
	ds_read_b128 v[22:25], v150 offset:1024
	ds_read_b128 v[26:29], v150 offset:2048
	ds_read_b128 v[30:33], v150 offset:3072
	s_cselect_b32 s43, s29, s37
	s_cselect_b32 s42, s28, s36
	s_ashr_i32 s25, s24, 31
	s_lshl_b64 s[30:31], s[24:25], 17
	s_add_u32 s30, s54, s30
	s_addc_u32 s31, s55, s31
	s_and_b64 s[38:39], s[6:7], exec
	s_cselect_b32 s39, s31, s41
	s_cselect_b32 s38, s30, s40
	s_add_u32 s46, s36, 0x8000
	s_addc_u32 s47, s37, 0
	s_add_u32 s70, s40, 0x8000
	s_addc_u32 s71, s41, 0
	s_add_u32 s44, s36, 0xc000
	s_addc_u32 s45, s37, 0
	s_add_u32 s72, s36, 0x14000
	s_addc_u32 s73, s37, 0
	s_mov_b32 m0, s65
	v_lshl_add_u64 v[66:67], s[72:73], 0, v[130:131]
	ds_read_b128 v[34:37], v151
	ds_read_b128 v[38:41], v151 offset:1024
	ds_read_b128 v[42:45], v151 offset:2048
	ds_read_b128 v[46:49], v151 offset:3072
	ds_read_b128 v[50:53], v151 offset:4096
	ds_read_b128 v[54:57], v151 offset:5120
	ds_read_b128 v[58:61], v151 offset:6144
	ds_read_b128 v[62:65], v151 offset:7168
	global_load_lds_dwordx4 v[66:67], off
	v_lshl_add_u64 v[66:67], s[72:73], 0, v[134:135]
	s_mov_b32 m0, s66
	s_nop 0
	global_load_lds_dwordx4 v[66:67], off
	s_waitcnt vmcnt(8)
	s_waitcnt lgkmcnt(0)
	s_barrier
	s_setprio 1
	s_waitcnt lgkmcnt(0)
	v_mfma_f32_16x16x32_bf16 v[66:69], v[2:5], v[34:37], 0
	v_mfma_f32_16x16x32_bf16 v[70:73], v[10:13], v[34:37], 0
	v_mfma_f32_16x16x32_bf16 v[74:77], v[2:5], v[42:45], 0
	v_mfma_f32_16x16x32_bf16 v[78:81], v[10:13], v[42:45], 0
	v_mfma_f32_16x16x32_bf16 v[82:85], v[2:5], v[50:53], 0
	v_mfma_f32_16x16x32_bf16 v[86:89], v[10:13], v[50:53], 0
	v_mfma_f32_16x16x32_bf16 v[90:93], v[2:5], v[58:61], 0
	v_mfma_f32_16x16x32_bf16 v[94:97], v[10:13], v[58:61], 0
	v_mfma_f32_16x16x32_bf16 v[66:69], v[6:9], v[38:41], v[66:69]
	v_mfma_f32_16x16x32_bf16 v[70:73], v[14:17], v[38:41], v[70:73]
	v_mfma_f32_16x16x32_bf16 v[74:77], v[6:9], v[46:49], v[74:77]
	v_mfma_f32_16x16x32_bf16 v[78:81], v[14:17], v[46:49], v[78:81]
	v_mfma_f32_16x16x32_bf16 v[82:85], v[6:9], v[54:57], v[82:85]
	v_mfma_f32_16x16x32_bf16 v[86:89], v[14:17], v[54:57], v[86:89]
	v_mfma_f32_16x16x32_bf16 v[90:93], v[6:9], v[62:65], v[90:93]
	v_mfma_f32_16x16x32_bf16 v[94:97], v[14:17], v[62:65], v[94:97]
	v_mfma_f32_16x16x32_bf16 v[98:101], v[18:21], v[34:37], 0
	v_mfma_f32_16x16x32_bf16 v[34:37], v[26:29], v[34:37], 0
	v_mfma_f32_16x16x32_bf16 v[98:101], v[22:25], v[38:41], v[98:101]
	v_mfma_f32_16x16x32_bf16 v[34:37], v[30:33], v[38:41], v[34:37]
	v_mfma_f32_16x16x32_bf16 v[38:41], v[18:21], v[42:45], 0
	v_mfma_f32_16x16x32_bf16 v[42:45], v[26:29], v[42:45], 0
	v_mfma_f32_16x16x32_bf16 v[38:41], v[22:25], v[46:49], v[38:41]
	v_mfma_f32_16x16x32_bf16 v[42:45], v[30:33], v[46:49], v[42:45]
	v_mfma_f32_16x16x32_bf16 v[46:49], v[18:21], v[50:53], 0
	v_mfma_f32_16x16x32_bf16 v[50:53], v[26:29], v[50:53], 0
	v_mfma_f32_16x16x32_bf16 v[46:49], v[22:25], v[54:57], v[46:49]
	v_mfma_f32_16x16x32_bf16 v[50:53], v[30:33], v[54:57], v[50:53]
	v_mfma_f32_16x16x32_bf16 v[54:57], v[18:21], v[58:61], 0
	v_mfma_f32_16x16x32_bf16 v[58:61], v[26:29], v[58:61], 0
	v_mfma_f32_16x16x32_bf16 v[54:57], v[22:25], v[62:65], v[54:57]
	v_mfma_f32_16x16x32_bf16 v[58:61], v[30:33], v[62:65], v[58:61]
	s_setprio 0
	s_barrier
	s_mov_b32 m0, s67
	v_lshl_add_u64 v[142:143], s[70:71], 0, v[132:133]
	ds_read_b128 v[62:65], v151 offset:16384
	ds_read_b128 v[102:105], v151 offset:17408
	ds_read_b128 v[106:109], v151 offset:18432
	ds_read_b128 v[110:113], v151 offset:19456
	ds_read_b128 v[114:117], v151 offset:20480
	ds_read_b128 v[118:121], v151 offset:21504
	ds_read_b128 v[122:125], v151 offset:22528
	ds_read_b128 v[126:129], v151 offset:23552
	global_load_lds_dwordx4 v[142:143], off
	v_lshl_add_u64 v[142:143], s[70:71], 0, v[136:137]
	s_add_u32 s70, s40, 0x18000
	s_mov_b32 m0, s68
	s_addc_u32 s71, s41, 0
	global_load_lds_dwordx4 v[142:143], off
	v_lshl_add_u64 v[142:143], s[70:71], 0, v[132:133]
	s_mov_b32 m0, s69
	s_add_i32 s25, s69, 0x2000
	global_load_lds_dwordx4 v[142:143], off
	v_lshl_add_u64 v[142:143], s[70:71], 0, v[136:137]
	s_mov_b32 m0, s25
	s_nop 0
	global_load_lds_dwordx4 v[142:143], off
	v_lshl_add_u64 v[142:143], s[46:47], 0, v[130:131]
	s_mov_b32 m0, s57
	s_nop 0
	global_load_lds_dwordx4 v[142:143], off
	v_lshl_add_u64 v[142:143], s[46:47], 0, v[134:135]
	s_mov_b32 m0, s59
	s_nop 0
	global_load_lds_dwordx4 v[142:143], off
	s_waitcnt vmcnt(8)
	s_waitcnt lgkmcnt(0)
	s_barrier
	s_setprio 1
	s_waitcnt lgkmcnt(0)
	v_mfma_f32_16x16x32_bf16 v[142:145], v[2:5], v[62:65], 0
	v_mfma_f32_16x16x32_bf16 v[158:161], v[2:5], v[106:109], 0
	v_mfma_f32_16x16x32_bf16 v[166:169], v[2:5], v[114:117], 0
	v_mfma_f32_16x16x32_bf16 v[2:5], v[2:5], v[122:125], 0
	v_mfma_f32_16x16x32_bf16 v[142:145], v[6:9], v[102:105], v[142:145]
	v_mfma_f32_16x16x32_bf16 v[158:161], v[6:9], v[110:113], v[158:161]
	v_mfma_f32_16x16x32_bf16 v[166:169], v[6:9], v[118:121], v[166:169]
	v_mfma_f32_16x16x32_bf16 v[2:5], v[6:9], v[126:129], v[2:5]
	v_mfma_f32_16x16x32_bf16 v[6:9], v[10:13], v[122:125], 0
	v_mfma_f32_16x16x32_bf16 v[154:157], v[10:13], v[62:65], 0
	v_mfma_f32_16x16x32_bf16 v[162:165], v[10:13], v[106:109], 0
	v_mfma_f32_16x16x32_bf16 v[170:173], v[10:13], v[114:117], 0
	v_mfma_f32_16x16x32_bf16 v[6:9], v[14:17], v[126:129], v[6:9]
	v_mfma_f32_16x16x32_bf16 v[154:157], v[14:17], v[102:105], v[154:157]
	v_mfma_f32_16x16x32_bf16 v[162:165], v[14:17], v[110:113], v[162:165]
	v_mfma_f32_16x16x32_bf16 v[170:173], v[14:17], v[118:121], v[170:173]
	v_mfma_f32_16x16x32_bf16 v[10:13], v[18:21], v[62:65], 0
	v_mfma_f32_16x16x32_bf16 v[14:17], v[26:29], v[62:65], 0
	v_mfma_f32_16x16x32_bf16 v[10:13], v[22:25], v[102:105], v[10:13]
	v_mfma_f32_16x16x32_bf16 v[14:17], v[30:33], v[102:105], v[14:17]
	v_mfma_f32_16x16x32_bf16 v[62:65], v[18:21], v[106:109], 0
	v_mfma_f32_16x16x32_bf16 v[102:105], v[26:29], v[106:109], 0
	v_mfma_f32_16x16x32_bf16 v[106:109], v[18:21], v[114:117], 0
	v_mfma_f32_16x16x32_bf16 v[18:21], v[18:21], v[122:125], 0
	v_mfma_f32_16x16x32_bf16 v[62:65], v[22:25], v[110:113], v[62:65]
	v_mfma_f32_16x16x32_bf16 v[102:105], v[30:33], v[110:113], v[102:105]
	v_mfma_f32_16x16x32_bf16 v[106:109], v[22:25], v[118:121], v[106:109]
	v_mfma_f32_16x16x32_bf16 v[110:113], v[26:29], v[114:117], 0
	v_mfma_f32_16x16x32_bf16 v[18:21], v[22:25], v[126:129], v[18:21]
	v_mfma_f32_16x16x32_bf16 v[22:25], v[26:29], v[122:125], 0
	v_mfma_f32_16x16x32_bf16 v[110:113], v[30:33], v[118:121], v[110:113]
	v_mfma_f32_16x16x32_bf16 v[22:25], v[30:33], v[126:129], v[22:25]
	s_setprio 0
	s_barrier
	s_add_i32 s27, 0, 0x18000
	s_add_i32 s35, 0, 0x1c000
	v_add_u32_e32 v153, s27, v147
	v_add_u32_e32 v226, s35, v147
	ds_read_b128 v[26:29], v153
	ds_read_b128 v[30:33], v153 offset:1024
	ds_read_b128 v[114:117], v153 offset:2048
	ds_read_b128 v[118:121], v153 offset:3072
	ds_read_b128 v[122:125], v226
	ds_read_b128 v[126:129], v226 offset:1024
	ds_read_b128 v[174:177], v226 offset:2048
	ds_read_b128 v[178:181], v226 offset:3072
	s_add_u32 s46, s36, 0x18000
	s_addc_u32 s47, s37, 0
	s_mov_b32 m0, s60
	v_lshl_add_u64 v[214:215], s[46:47], 0, v[130:131]
	ds_read_b128 v[182:185], v151 offset:32768
	ds_read_b128 v[186:189], v151 offset:33792
	ds_read_b128 v[190:193], v151 offset:34816
	ds_read_b128 v[194:197], v151 offset:35840
	ds_read_b128 v[198:201], v151 offset:36864
	ds_read_b128 v[202:205], v151 offset:37888
	ds_read_b128 v[206:209], v151 offset:38912
	ds_read_b128 v[210:213], v151 offset:39936
	global_load_lds_dwordx4 v[214:215], off
	v_lshl_add_u64 v[214:215], s[46:47], 0, v[134:135]
	s_mov_b32 m0, s61
	s_nop 0
	global_load_lds_dwordx4 v[214:215], off
	s_waitcnt vmcnt(8)
	s_waitcnt lgkmcnt(0)
	s_barrier
	s_setprio 1
	s_waitcnt lgkmcnt(0)
	v_mfma_f32_16x16x32_bf16 v[66:69], v[26:29], v[182:185], v[66:69]
	v_mfma_f32_16x16x32_bf16 v[70:73], v[114:117], v[182:185], v[70:73]
	v_mfma_f32_16x16x32_bf16 v[74:77], v[26:29], v[190:193], v[74:77]
	v_mfma_f32_16x16x32_bf16 v[78:81], v[114:117], v[190:193], v[78:81]
	v_mfma_f32_16x16x32_bf16 v[82:85], v[26:29], v[198:201], v[82:85]
	v_mfma_f32_16x16x32_bf16 v[86:89], v[114:117], v[198:201], v[86:89]
	v_mfma_f32_16x16x32_bf16 v[90:93], v[26:29], v[206:209], v[90:93]
	v_mfma_f32_16x16x32_bf16 v[94:97], v[114:117], v[206:209], v[94:97]
	v_mfma_f32_16x16x32_bf16 v[66:69], v[30:33], v[186:189], v[66:69]
	v_mfma_f32_16x16x32_bf16 v[70:73], v[118:121], v[186:189], v[70:73]
	v_mfma_f32_16x16x32_bf16 v[74:77], v[30:33], v[194:197], v[74:77]
	v_mfma_f32_16x16x32_bf16 v[78:81], v[118:121], v[194:197], v[78:81]
	v_mfma_f32_16x16x32_bf16 v[82:85], v[30:33], v[202:205], v[82:85]
	v_mfma_f32_16x16x32_bf16 v[86:89], v[118:121], v[202:205], v[86:89]
	v_mfma_f32_16x16x32_bf16 v[90:93], v[30:33], v[210:213], v[90:93]
	v_mfma_f32_16x16x32_bf16 v[94:97], v[118:121], v[210:213], v[94:97]
	v_mfma_f32_16x16x32_bf16 v[98:101], v[122:125], v[182:185], v[98:101]
	v_mfma_f32_16x16x32_bf16 v[34:37], v[174:177], v[182:185], v[34:37]
	v_mfma_f32_16x16x32_bf16 v[38:41], v[122:125], v[190:193], v[38:41]
	v_mfma_f32_16x16x32_bf16 v[42:45], v[174:177], v[190:193], v[42:45]
	v_mfma_f32_16x16x32_bf16 v[46:49], v[122:125], v[198:201], v[46:49]
	v_mfma_f32_16x16x32_bf16 v[50:53], v[174:177], v[198:201], v[50:53]
	v_mfma_f32_16x16x32_bf16 v[54:57], v[122:125], v[206:209], v[54:57]
	v_mfma_f32_16x16x32_bf16 v[58:61], v[174:177], v[206:209], v[58:61]
	v_mfma_f32_16x16x32_bf16 v[98:101], v[126:129], v[186:189], v[98:101]
	v_mfma_f32_16x16x32_bf16 v[34:37], v[178:181], v[186:189], v[34:37]
	v_mfma_f32_16x16x32_bf16 v[38:41], v[126:129], v[194:197], v[38:41]
	v_mfma_f32_16x16x32_bf16 v[42:45], v[178:181], v[194:197], v[42:45]
	v_mfma_f32_16x16x32_bf16 v[46:49], v[126:129], v[202:205], v[46:49]
	v_mfma_f32_16x16x32_bf16 v[50:53], v[178:181], v[202:205], v[50:53]
	v_mfma_f32_16x16x32_bf16 v[54:57], v[126:129], v[210:213], v[54:57]
	v_mfma_f32_16x16x32_bf16 v[58:61], v[178:181], v[210:213], v[58:61]
	s_setprio 0
	s_barrier
	s_add_u32 s70, s40, 0xc000
	s_addc_u32 s71, s41, 0
	s_add_i32 s47, s27, s56
	s_add_i32 s27, s47, 0x2000
	v_lshl_add_u64 v[214:215], s[70:71], 0, v[132:133]
	s_mov_b32 m0, s47
	s_add_u32 s40, s40, 0x1c000
	ds_read_b128 v[182:185], v151 offset:49152
	ds_read_b128 v[186:189], v151 offset:50176
	ds_read_b128 v[190:193], v151 offset:51200
	ds_read_b128 v[194:197], v151 offset:52224
	ds_read_b128 v[198:201], v151 offset:53248
	ds_read_b128 v[202:205], v151 offset:54272
	ds_read_b128 v[206:209], v151 offset:55296
	ds_read_b128 v[210:213], v151 offset:56320
	global_load_lds_dwordx4 v[214:215], off
	v_lshl_add_u64 v[214:215], s[70:71], 0, v[136:137]
	s_mov_b32 m0, s27
	s_addc_u32 s41, s41, 0
	s_add_i32 s35, s35, s56
	global_load_lds_dwordx4 v[214:215], off
	v_lshl_add_u64 v[214:215], s[40:41], 0, v[132:133]
	s_mov_b32 m0, s35
	s_add_i32 s46, s35, 0x2000
	global_load_lds_dwordx4 v[214:215], off
	v_lshl_add_u64 v[214:215], s[40:41], 0, v[136:137]
	s_mov_b32 m0, s46
	s_nop 0
	global_load_lds_dwordx4 v[214:215], off
	v_lshl_add_u64 v[214:215], s[44:45], 0, v[130:131]
	s_mov_b32 m0, s63
	s_nop 0
	global_load_lds_dwordx4 v[214:215], off
	v_lshl_add_u64 v[214:215], s[44:45], 0, v[134:135]
	s_mov_b32 m0, s64
	s_nop 0
	global_load_lds_dwordx4 v[214:215], off
	s_waitcnt vmcnt(8)
	s_waitcnt lgkmcnt(0)
	s_barrier
	s_setprio 1
	s_waitcnt lgkmcnt(0)
	v_mfma_f32_16x16x32_bf16 v[2:5], v[26:29], v[206:209], v[2:5]
	v_mfma_f32_16x16x32_bf16 v[6:9], v[114:117], v[206:209], v[6:9]
	v_mfma_f32_16x16x32_bf16 v[142:145], v[26:29], v[182:185], v[142:145]
	v_mfma_f32_16x16x32_bf16 v[154:157], v[114:117], v[182:185], v[154:157]
	v_mfma_f32_16x16x32_bf16 v[158:161], v[26:29], v[190:193], v[158:161]
	v_mfma_f32_16x16x32_bf16 v[162:165], v[114:117], v[190:193], v[162:165]
	v_mfma_f32_16x16x32_bf16 v[166:169], v[26:29], v[198:201], v[166:169]
	v_mfma_f32_16x16x32_bf16 v[170:173], v[114:117], v[198:201], v[170:173]
	v_mfma_f32_16x16x32_bf16 v[2:5], v[30:33], v[210:213], v[2:5]
	v_mfma_f32_16x16x32_bf16 v[6:9], v[118:121], v[210:213], v[6:9]
	v_mfma_f32_16x16x32_bf16 v[142:145], v[30:33], v[186:189], v[142:145]
	v_mfma_f32_16x16x32_bf16 v[154:157], v[118:121], v[186:189], v[154:157]
	v_mfma_f32_16x16x32_bf16 v[158:161], v[30:33], v[194:197], v[158:161]
	v_mfma_f32_16x16x32_bf16 v[162:165], v[118:121], v[194:197], v[162:165]
	v_mfma_f32_16x16x32_bf16 v[166:169], v[30:33], v[202:205], v[166:169]
	v_mfma_f32_16x16x32_bf16 v[170:173], v[118:121], v[202:205], v[170:173]
	v_mfma_f32_16x16x32_bf16 v[10:13], v[122:125], v[182:185], v[10:13]
	v_mfma_f32_16x16x32_bf16 v[14:17], v[174:177], v[182:185], v[14:17]
	v_mfma_f32_16x16x32_bf16 v[26:29], v[122:125], v[190:193], v[62:65]
	v_mfma_f32_16x16x32_bf16 v[30:33], v[174:177], v[190:193], v[102:105]
	v_mfma_f32_16x16x32_bf16 v[62:65], v[122:125], v[198:201], v[106:109]
	v_mfma_f32_16x16x32_bf16 v[102:105], v[174:177], v[198:201], v[110:113]
	v_mfma_f32_16x16x32_bf16 v[18:21], v[122:125], v[206:209], v[18:21]
	v_mfma_f32_16x16x32_bf16 v[22:25], v[174:177], v[206:209], v[22:25]
	v_mfma_f32_16x16x32_bf16 v[10:13], v[126:129], v[186:189], v[10:13]
	v_mfma_f32_16x16x32_bf16 v[14:17], v[178:181], v[186:189], v[14:17]
	v_mfma_f32_16x16x32_bf16 v[26:29], v[126:129], v[194:197], v[26:29]
	v_mfma_f32_16x16x32_bf16 v[30:33], v[178:181], v[194:197], v[30:33]
	v_mfma_f32_16x16x32_bf16 v[62:65], v[126:129], v[202:205], v[62:65]
	v_mfma_f32_16x16x32_bf16 v[102:105], v[178:181], v[202:205], v[102:105]
	v_mfma_f32_16x16x32_bf16 v[18:21], v[126:129], v[210:213], v[18:21]
	v_mfma_f32_16x16x32_bf16 v[22:25], v[178:181], v[210:213], v[22:25]
	s_setprio 0
	s_barrier
	ds_read_b128 v[106:109], v149
	ds_read_b128 v[110:113], v149 offset:1024
	ds_read_b128 v[114:117], v149 offset:2048
	ds_read_b128 v[118:121], v149 offset:3072
	ds_read_b128 v[122:125], v150
	ds_read_b128 v[126:129], v150 offset:1024
	ds_read_b128 v[174:177], v150 offset:2048
	ds_read_b128 v[178:181], v150 offset:3072
	s_add_u32 s40, s42, 0x4000
	s_addc_u32 s41, s43, 0
	s_add_u32 s36, s36, 0x1c000
	s_addc_u32 s37, s37, 0
	s_mov_b32 m0, s65
	v_lshl_add_u64 v[214:215], s[36:37], 0, v[130:131]
	ds_read_b128 v[182:185], v151
	ds_read_b128 v[186:189], v151 offset:1024
	ds_read_b128 v[190:193], v151 offset:2048
	ds_read_b128 v[194:197], v151 offset:3072
	ds_read_b128 v[198:201], v151 offset:4096
	ds_read_b128 v[202:205], v151 offset:5120
	ds_read_b128 v[206:209], v151 offset:6144
	ds_read_b128 v[210:213], v151 offset:7168
	global_load_lds_dwordx4 v[214:215], off
	v_lshl_add_u64 v[214:215], s[36:37], 0, v[134:135]
	s_mov_b32 m0, s66
	s_nop 0
	global_load_lds_dwordx4 v[214:215], off
	s_waitcnt vmcnt(8)
	s_waitcnt lgkmcnt(0)
	s_barrier
	s_setprio 1
	s_waitcnt lgkmcnt(0)
	v_mfma_f32_16x16x32_bf16 v[66:69], v[106:109], v[182:185], v[66:69]
	v_mfma_f32_16x16x32_bf16 v[70:73], v[114:117], v[182:185], v[70:73]
	v_mfma_f32_16x16x32_bf16 v[74:77], v[106:109], v[190:193], v[74:77]
	v_mfma_f32_16x16x32_bf16 v[78:81], v[114:117], v[190:193], v[78:81]
	v_mfma_f32_16x16x32_bf16 v[82:85], v[106:109], v[198:201], v[82:85]
	v_mfma_f32_16x16x32_bf16 v[86:89], v[114:117], v[198:201], v[86:89]
	v_mfma_f32_16x16x32_bf16 v[90:93], v[106:109], v[206:209], v[90:93]
	v_mfma_f32_16x16x32_bf16 v[66:69], v[110:113], v[186:189], v[66:69]
	v_mfma_f32_16x16x32_bf16 v[70:73], v[118:121], v[186:189], v[70:73]
	v_mfma_f32_16x16x32_bf16 v[74:77], v[110:113], v[194:197], v[74:77]
	v_mfma_f32_16x16x32_bf16 v[78:81], v[118:121], v[194:197], v[78:81]
	v_mfma_f32_16x16x32_bf16 v[82:85], v[110:113], v[202:205], v[82:85]
	v_mfma_f32_16x16x32_bf16 v[86:89], v[118:121], v[202:205], v[86:89]
	v_mfma_f32_16x16x32_bf16 v[214:217], v[110:113], v[210:213], v[90:93]
	v_mfma_f32_16x16x32_bf16 v[90:93], v[114:117], v[206:209], v[94:97]
	v_mfma_f32_16x16x32_bf16 v[218:221], v[118:121], v[210:213], v[90:93]
	v_mfma_f32_16x16x32_bf16 v[90:93], v[122:125], v[182:185], v[98:101]
	v_mfma_f32_16x16x32_bf16 v[34:37], v[174:177], v[182:185], v[34:37]
	v_mfma_f32_16x16x32_bf16 v[38:41], v[122:125], v[190:193], v[38:41]
	v_mfma_f32_16x16x32_bf16 v[42:45], v[174:177], v[190:193], v[42:45]
	v_mfma_f32_16x16x32_bf16 v[46:49], v[122:125], v[198:201], v[46:49]
	v_mfma_f32_16x16x32_bf16 v[50:53], v[174:177], v[198:201], v[50:53]
	v_mfma_f32_16x16x32_bf16 v[54:57], v[122:125], v[206:209], v[54:57]
	v_mfma_f32_16x16x32_bf16 v[58:61], v[174:177], v[206:209], v[58:61]
	v_mfma_f32_16x16x32_bf16 v[98:101], v[126:129], v[186:189], v[90:93]
	v_mfma_f32_16x16x32_bf16 v[34:37], v[178:181], v[186:189], v[34:37]
	v_mfma_f32_16x16x32_bf16 v[38:41], v[126:129], v[194:197], v[38:41]
	v_mfma_f32_16x16x32_bf16 v[42:45], v[178:181], v[194:197], v[42:45]
	v_mfma_f32_16x16x32_bf16 v[46:49], v[126:129], v[202:205], v[46:49]
	v_mfma_f32_16x16x32_bf16 v[50:53], v[178:181], v[202:205], v[50:53]
	v_mfma_f32_16x16x32_bf16 v[54:57], v[126:129], v[210:213], v[54:57]
	v_mfma_f32_16x16x32_bf16 v[58:61], v[178:181], v[210:213], v[58:61]
	s_setprio 0
	s_barrier
	s_mov_b32 m0, s67
	v_lshl_add_u64 v[206:207], s[38:39], 0, v[132:133]
	s_add_u32 s36, s38, 0x10000
	ds_read_b128 v[90:93], v151 offset:16384
	ds_read_b128 v[94:97], v151 offset:17408
	ds_read_b128 v[182:185], v151 offset:18432
	ds_read_b128 v[186:189], v151 offset:19456
	ds_read_b128 v[190:193], v151 offset:20480
	ds_read_b128 v[194:197], v151 offset:21504
	ds_read_b128 v[198:201], v151 offset:22528
	ds_read_b128 v[202:205], v151 offset:23552
	global_load_lds_dwordx4 v[206:207], off
	v_lshl_add_u64 v[206:207], s[38:39], 0, v[136:137]
	s_mov_b32 m0, s68
	s_addc_u32 s37, s39, 0
	global_load_lds_dwordx4 v[206:207], off
	v_lshl_add_u64 v[206:207], s[36:37], 0, v[132:133]
	s_mov_b32 m0, s69
	s_nop 0
	global_load_lds_dwordx4 v[206:207], off
	v_lshl_add_u64 v[206:207], s[36:37], 0, v[136:137]
	s_mov_b32 m0, s25
	s_nop 0
	global_load_lds_dwordx4 v[206:207], off
	v_lshl_add_u64 v[206:207], s[42:43], 0, v[130:131]
	s_mov_b32 m0, s57
	s_nop 0
	global_load_lds_dwordx4 v[206:207], off
	v_lshl_add_u64 v[206:207], s[42:43], 0, v[134:135]
	s_mov_b32 m0, s59
	s_nop 0
	global_load_lds_dwordx4 v[206:207], off
	s_waitcnt vmcnt(8)
	s_waitcnt lgkmcnt(0)
	s_barrier
	s_setprio 1
	s_waitcnt lgkmcnt(0)
	v_mfma_f32_16x16x32_bf16 v[2:5], v[106:109], v[198:201], v[2:5]
	v_mfma_f32_16x16x32_bf16 v[6:9], v[114:117], v[198:201], v[6:9]
	v_mfma_f32_16x16x32_bf16 v[142:145], v[106:109], v[90:93], v[142:145]
	v_mfma_f32_16x16x32_bf16 v[154:157], v[114:117], v[90:93], v[154:157]
	v_mfma_f32_16x16x32_bf16 v[158:161], v[106:109], v[182:185], v[158:161]
	v_mfma_f32_16x16x32_bf16 v[162:165], v[114:117], v[182:185], v[162:165]
	v_mfma_f32_16x16x32_bf16 v[166:169], v[106:109], v[190:193], v[166:169]
	v_mfma_f32_16x16x32_bf16 v[170:173], v[114:117], v[190:193], v[170:173]
	v_mfma_f32_16x16x32_bf16 v[2:5], v[110:113], v[202:205], v[2:5]
	v_mfma_f32_16x16x32_bf16 v[6:9], v[118:121], v[202:205], v[6:9]
	v_mfma_f32_16x16x32_bf16 v[142:145], v[110:113], v[94:97], v[142:145]
	v_mfma_f32_16x16x32_bf16 v[154:157], v[118:121], v[94:97], v[154:157]
	v_mfma_f32_16x16x32_bf16 v[158:161], v[110:113], v[186:189], v[158:161]
	v_mfma_f32_16x16x32_bf16 v[162:165], v[118:121], v[186:189], v[162:165]
	v_mfma_f32_16x16x32_bf16 v[166:169], v[110:113], v[194:197], v[166:169]
	v_mfma_f32_16x16x32_bf16 v[170:173], v[118:121], v[194:197], v[170:173]
	v_mfma_f32_16x16x32_bf16 v[10:13], v[122:125], v[90:93], v[10:13]
	v_mfma_f32_16x16x32_bf16 v[206:209], v[126:129], v[94:97], v[10:13]
	v_mfma_f32_16x16x32_bf16 v[10:13], v[174:177], v[90:93], v[14:17]
	v_mfma_f32_16x16x32_bf16 v[210:213], v[178:181], v[94:97], v[10:13]
	v_mfma_f32_16x16x32_bf16 v[10:13], v[122:125], v[182:185], v[26:29]
	v_mfma_f32_16x16x32_bf16 v[222:225], v[126:129], v[186:189], v[10:13]
	v_mfma_f32_16x16x32_bf16 v[10:13], v[174:177], v[182:185], v[30:33]
	v_mfma_f32_16x16x32_bf16 v[182:185], v[178:181], v[186:189], v[10:13]
	v_mfma_f32_16x16x32_bf16 v[10:13], v[122:125], v[190:193], v[62:65]
	v_mfma_f32_16x16x32_bf16 v[186:189], v[126:129], v[194:197], v[10:13]
	v_mfma_f32_16x16x32_bf16 v[10:13], v[174:177], v[190:193], v[102:105]
	v_mfma_f32_16x16x32_bf16 v[190:193], v[178:181], v[194:197], v[10:13]
	v_mfma_f32_16x16x32_bf16 v[10:13], v[122:125], v[198:201], v[18:21]
	v_mfma_f32_16x16x32_bf16 v[194:197], v[126:129], v[202:205], v[10:13]
	v_mfma_f32_16x16x32_bf16 v[10:13], v[174:177], v[198:201], v[22:25]
	v_mfma_f32_16x16x32_bf16 v[174:177], v[178:181], v[202:205], v[10:13]
	s_setprio 0
	s_barrier
	s_nop 4
	ds_read_b128 v[10:13], v153
	ds_read_b128 v[14:17], v153 offset:1024
	ds_read_b128 v[18:21], v153 offset:2048
	ds_read_b128 v[22:25], v153 offset:3072
	ds_read_b128 v[178:181], v226
	ds_read_b128 v[198:201], v226 offset:1024
	ds_read_b128 v[202:205], v226 offset:2048
	ds_read_b128 v[226:229], v226 offset:3072
	s_add_u32 s36, s42, 0x10000
	s_addc_u32 s37, s43, 0
	s_mov_b32 m0, s60
	v_lshl_add_u64 v[90:91], s[36:37], 0, v[130:131]
	ds_read_b128 v[26:29], v151 offset:32768
	ds_read_b128 v[30:33], v151 offset:33792
	ds_read_b128 v[62:65], v151 offset:34816
	ds_read_b128 v[102:105], v151 offset:35840
	ds_read_b128 v[230:233], v151 offset:36864
	ds_read_b128 v[234:237], v151 offset:37888
	ds_read_b128 v[238:241], v151 offset:38912
	ds_read_b128 v[242:245], v151 offset:39936
	global_load_lds_dwordx4 v[90:91], off
	v_lshl_add_u64 v[90:91], s[36:37], 0, v[134:135]
	s_mov_b32 m0, s61
	s_nop 0
	global_load_lds_dwordx4 v[90:91], off
	s_waitcnt vmcnt(8)
	s_waitcnt lgkmcnt(0)
	s_barrier
	s_setprio 1
	s_waitcnt lgkmcnt(0)
	v_mfma_f32_16x16x32_bf16 v[66:69], v[10:13], v[26:29], v[66:69]
	v_mfma_f32_16x16x32_bf16 v[126:129], v[14:17], v[30:33], v[66:69]
	v_mfma_f32_16x16x32_bf16 v[66:69], v[18:21], v[26:29], v[70:73]
	v_mfma_f32_16x16x32_bf16 v[122:125], v[22:25], v[30:33], v[66:69]
	v_mfma_f32_16x16x32_bf16 v[66:69], v[10:13], v[62:65], v[74:77]
	v_mfma_f32_16x16x32_bf16 v[110:113], v[14:17], v[102:105], v[66:69]
	v_mfma_f32_16x16x32_bf16 v[66:69], v[18:21], v[62:65], v[78:81]
	v_mfma_f32_16x16x32_bf16 v[106:109], v[22:25], v[102:105], v[66:69]
	v_mfma_f32_16x16x32_bf16 v[66:69], v[10:13], v[230:233], v[82:85]
	v_mfma_f32_16x16x32_bf16 v[94:97], v[14:17], v[234:237], v[66:69]
	v_mfma_f32_16x16x32_bf16 v[66:69], v[18:21], v[230:233], v[86:89]
	v_mfma_f32_16x16x32_bf16 v[90:93], v[22:25], v[234:237], v[66:69]
	v_mfma_f32_16x16x32_bf16 v[66:69], v[10:13], v[238:241], v[214:217]
	v_mfma_f32_16x16x32_bf16 v[78:81], v[14:17], v[242:245], v[66:69]
	v_mfma_f32_16x16x32_bf16 v[66:69], v[18:21], v[238:241], v[218:221]
	v_mfma_f32_16x16x32_bf16 v[74:77], v[22:25], v[242:245], v[66:69]
	v_mfma_f32_16x16x32_bf16 v[66:69], v[178:181], v[26:29], v[98:101]
	v_mfma_f32_16x16x32_bf16 v[26:29], v[202:205], v[26:29], v[34:37]
	v_mfma_f32_16x16x32_bf16 v[118:121], v[226:229], v[30:33], v[26:29]
	v_mfma_f32_16x16x32_bf16 v[26:29], v[178:181], v[62:65], v[38:41]
	v_mfma_f32_16x16x32_bf16 v[98:101], v[198:201], v[102:105], v[26:29]
	v_mfma_f32_16x16x32_bf16 v[26:29], v[202:205], v[62:65], v[42:45]
	v_mfma_f32_16x16x32_bf16 v[102:105], v[226:229], v[102:105], v[26:29]
	v_mfma_f32_16x16x32_bf16 v[26:29], v[178:181], v[230:233], v[46:49]
	v_mfma_f32_16x16x32_bf16 v[82:85], v[198:201], v[234:237], v[26:29]
	v_mfma_f32_16x16x32_bf16 v[26:29], v[202:205], v[230:233], v[50:53]
	v_mfma_f32_16x16x32_bf16 v[86:89], v[226:229], v[234:237], v[26:29]
	v_mfma_f32_16x16x32_bf16 v[26:29], v[178:181], v[238:241], v[54:57]
	v_mfma_f32_16x16x32_bf16 v[62:65], v[198:201], v[242:245], v[26:29]
	v_mfma_f32_16x16x32_bf16 v[26:29], v[202:205], v[238:241], v[58:61]
	v_mfma_f32_16x16x32_bf16 v[114:117], v[198:201], v[30:33], v[66:69]
	v_mfma_f32_16x16x32_bf16 v[66:69], v[226:229], v[242:245], v[26:29]
	s_setprio 0
	s_barrier
	s_add_u32 s36, s38, 0x4000
	s_addc_u32 s37, s39, 0
	s_mov_b32 m0, s47
	s_nop 0
	v_lshl_add_u64 v[26:27], s[36:37], 0, v[132:133]
	ds_read_b128 v[34:37], v151 offset:49152
	ds_read_b128 v[38:41], v151 offset:50176
	ds_read_b128 v[214:217], v151 offset:51200
	ds_read_b128 v[218:221], v151 offset:52224
	ds_read_b128 v[230:233], v151 offset:53248
	ds_read_b128 v[234:237], v151 offset:54272
	ds_read_b128 v[238:241], v151 offset:55296
	ds_read_b128 v[242:245], v151 offset:56320
	global_load_lds_dwordx4 v[26:27], off
	v_lshl_add_u64 v[26:27], s[36:37], 0, v[136:137]
	s_add_u32 s36, s38, 0x14000
	s_mov_b32 m0, s27
	s_addc_u32 s37, s39, 0
	global_load_lds_dwordx4 v[26:27], off
	v_lshl_add_u64 v[26:27], s[36:37], 0, v[132:133]
	s_mov_b32 m0, s35
	s_nop 0
	global_load_lds_dwordx4 v[26:27], off
	v_lshl_add_u64 v[26:27], s[36:37], 0, v[136:137]
	s_mov_b32 m0, s46
	s_nop 0
	global_load_lds_dwordx4 v[26:27], off
	v_lshl_add_u64 v[26:27], s[40:41], 0, v[130:131]
	s_mov_b32 m0, s63
	s_nop 0
	global_load_lds_dwordx4 v[26:27], off
	v_lshl_add_u64 v[26:27], s[40:41], 0, v[134:135]
	s_mov_b32 m0, s64
	s_nop 0
	global_load_lds_dwordx4 v[26:27], off
	s_waitcnt vmcnt(8)
	s_waitcnt lgkmcnt(0)
	s_barrier
	s_setprio 1
	s_waitcnt lgkmcnt(0)
	v_mfma_f32_16x16x32_bf16 v[26:29], v[10:13], v[34:37], v[142:145]
	v_mfma_f32_16x16x32_bf16 v[70:73], v[14:17], v[38:41], v[26:29]
	v_mfma_f32_16x16x32_bf16 v[26:29], v[18:21], v[34:37], v[154:157]
	v_mfma_f32_16x16x32_bf16 v[58:61], v[22:25], v[38:41], v[26:29]
	v_mfma_f32_16x16x32_bf16 v[26:29], v[10:13], v[214:217], v[158:161]
	v_mfma_f32_16x16x32_bf16 v[46:49], v[14:17], v[218:221], v[26:29]
	v_mfma_f32_16x16x32_bf16 v[26:29], v[18:21], v[214:217], v[162:165]
	v_mfma_f32_16x16x32_bf16 v[42:45], v[22:25], v[218:221], v[26:29]
	v_mfma_f32_16x16x32_bf16 v[26:29], v[10:13], v[230:233], v[166:169]
	v_mfma_f32_16x16x32_bf16 v[2:5], v[10:13], v[238:241], v[2:5]
	v_mfma_f32_16x16x32_bf16 v[30:33], v[14:17], v[234:237], v[26:29]
	v_mfma_f32_16x16x32_bf16 v[26:29], v[18:21], v[230:233], v[170:173]
	v_mfma_f32_16x16x32_bf16 v[14:17], v[14:17], v[242:245], v[2:5]
	v_mfma_f32_16x16x32_bf16 v[2:5], v[18:21], v[238:241], v[6:9]
	v_mfma_f32_16x16x32_bf16 v[26:29], v[22:25], v[234:237], v[26:29]
	v_mfma_f32_16x16x32_bf16 v[10:13], v[22:25], v[242:245], v[2:5]
	v_mfma_f32_16x16x32_bf16 v[2:5], v[178:181], v[34:37], v[206:209]
	v_mfma_f32_16x16x32_bf16 v[50:53], v[198:201], v[38:41], v[2:5]
	v_mfma_f32_16x16x32_bf16 v[2:5], v[202:205], v[34:37], v[210:213]
	v_mfma_f32_16x16x32_bf16 v[54:57], v[226:229], v[38:41], v[2:5]
	v_mfma_f32_16x16x32_bf16 v[2:5], v[178:181], v[214:217], v[222:225]
	v_mfma_f32_16x16x32_bf16 v[34:37], v[198:201], v[218:221], v[2:5]
	v_mfma_f32_16x16x32_bf16 v[2:5], v[202:205], v[214:217], v[182:185]
	v_mfma_f32_16x16x32_bf16 v[38:41], v[226:229], v[218:221], v[2:5]
	v_mfma_f32_16x16x32_bf16 v[2:5], v[178:181], v[230:233], v[186:189]
	v_mfma_f32_16x16x32_bf16 v[18:21], v[198:201], v[234:237], v[2:5]
	v_mfma_f32_16x16x32_bf16 v[2:5], v[202:205], v[230:233], v[190:193]
	v_mfma_f32_16x16x32_bf16 v[22:25], v[226:229], v[234:237], v[2:5]
	v_mfma_f32_16x16x32_bf16 v[2:5], v[178:181], v[238:241], v[194:197]
	v_mfma_f32_16x16x32_bf16 v[6:9], v[202:205], v[238:241], v[174:177]
	v_mfma_f32_16x16x32_bf16 v[2:5], v[198:201], v[242:245], v[2:5]
	v_mfma_f32_16x16x32_bf16 v[6:9], v[226:229], v[242:245], v[6:9]
	s_setprio 0
	s_barrier
	s_andn2_b64 vcc, exec, s[20:21]
	s_cbranch_vccnz .LBB0_1127
	s_barrier

.LBB0_1215:
	ds_read_b128 v[160:163], v154
	ds_read_b128 v[164:167], v154 offset:1024
	ds_read_b128 v[168:171], v154 offset:2048
	ds_read_b128 v[172:175], v154 offset:3072
	ds_read_b128 v[176:179], v155
	ds_read_b128 v[180:183], v155 offset:1024
	ds_read_b128 v[184:187], v155 offset:2048
	ds_read_b128 v[188:191], v155 offset:3072
	s_add_u32 s30, s28, 0xfff04000
	s_addc_u32 s31, s29, -1
	s_cmp_eq_u32 s61, 60
	s_cselect_b32 s36, s56, s30
	s_cselect_b32 s37, s21, s31
	s_cselect_b32 s34, s57, s59
	s_cselect_b32 s35, s19, s60
	s_add_u32 s30, s36, 0x4000
	s_addc_u32 s31, s37, 0
	s_add_i32 m0, s39, 0xc000
	ds_read_b128 v[192:195], v156
	ds_read_b128 v[196:199], v156 offset:1024
	ds_read_b128 v[200:203], v156 offset:2048
	ds_read_b128 v[204:207], v156 offset:3072
	ds_read_b128 v[208:211], v156 offset:4096
	ds_read_b128 v[212:215], v156 offset:5120
	ds_read_b128 v[216:219], v156 offset:6144
	ds_read_b128 v[220:223], v156 offset:7168
	global_load_lds_dwordx4 v140, s[28:29]
	s_add_i32 m0, s39, 0xe000
	s_nop 0
	global_load_lds_dwordx4 v142, s[28:29]
	s_waitcnt vmcnt(8)
	s_waitcnt lgkmcnt(0)
	s_barrier
	s_setprio 1
	s_waitcnt lgkmcnt(0)
	v_mfma_f32_16x16x32_bf16 v[126:129], v[160:163], v[192:195], v[126:129]
	v_mfma_f32_16x16x32_bf16 v[126:129], v[164:167], v[196:199], v[126:129]
	v_mfma_f32_16x16x32_bf16 v[122:125], v[168:171], v[192:195], v[122:125]
	v_mfma_f32_16x16x32_bf16 v[122:125], v[172:175], v[196:199], v[122:125]
	v_mfma_f32_16x16x32_bf16 v[110:113], v[160:163], v[200:203], v[110:113]
	v_mfma_f32_16x16x32_bf16 v[110:113], v[164:167], v[204:207], v[110:113]
	v_mfma_f32_16x16x32_bf16 v[106:109], v[168:171], v[200:203], v[106:109]
	v_mfma_f32_16x16x32_bf16 v[106:109], v[172:175], v[204:207], v[106:109]
	v_mfma_f32_16x16x32_bf16 v[94:97], v[160:163], v[208:211], v[94:97]
	v_mfma_f32_16x16x32_bf16 v[94:97], v[164:167], v[212:215], v[94:97]
	v_mfma_f32_16x16x32_bf16 v[90:93], v[168:171], v[208:211], v[90:93]
	v_mfma_f32_16x16x32_bf16 v[90:93], v[172:175], v[212:215], v[90:93]
	v_mfma_f32_16x16x32_bf16 v[78:81], v[160:163], v[216:219], v[78:81]
	v_mfma_f32_16x16x32_bf16 v[78:81], v[164:167], v[220:223], v[78:81]
	v_mfma_f32_16x16x32_bf16 v[74:77], v[168:171], v[216:219], v[74:77]
	v_mfma_f32_16x16x32_bf16 v[74:77], v[172:175], v[220:223], v[74:77]
	v_mfma_f32_16x16x32_bf16 v[118:121], v[176:179], v[192:195], v[118:121]
	v_mfma_f32_16x16x32_bf16 v[118:121], v[180:183], v[196:199], v[118:121]
	v_mfma_f32_16x16x32_bf16 v[114:117], v[184:187], v[192:195], v[114:117]
	v_mfma_f32_16x16x32_bf16 v[114:117], v[188:191], v[196:199], v[114:117]
	v_mfma_f32_16x16x32_bf16 v[102:105], v[176:179], v[200:203], v[102:105]
	v_mfma_f32_16x16x32_bf16 v[102:105], v[180:183], v[204:207], v[102:105]
	v_mfma_f32_16x16x32_bf16 v[98:101], v[184:187], v[200:203], v[98:101]
	v_mfma_f32_16x16x32_bf16 v[98:101], v[188:191], v[204:207], v[98:101]
	v_mfma_f32_16x16x32_bf16 v[86:89], v[176:179], v[208:211], v[86:89]
	v_mfma_f32_16x16x32_bf16 v[86:89], v[180:183], v[212:215], v[86:89]
	v_mfma_f32_16x16x32_bf16 v[82:85], v[184:187], v[208:211], v[82:85]
	v_mfma_f32_16x16x32_bf16 v[82:85], v[188:191], v[212:215], v[82:85]
	v_mfma_f32_16x16x32_bf16 v[70:73], v[176:179], v[216:219], v[70:73]
	v_mfma_f32_16x16x32_bf16 v[70:73], v[180:183], v[220:223], v[70:73]
	v_mfma_f32_16x16x32_bf16 v[66:69], v[184:187], v[216:219], v[66:69]
	v_mfma_f32_16x16x32_bf16 v[66:69], v[188:191], v[220:223], v[66:69]
	s_setprio 0
	s_barrier
	s_add_i32 s62, s47, s38
	s_mov_b32 m0, s62
	ds_read_b128 v[192:195], v156 offset:16384
	ds_read_b128 v[196:199], v156 offset:17408
	ds_read_b128 v[200:203], v156 offset:18432
	ds_read_b128 v[204:207], v156 offset:19456
	ds_read_b128 v[208:211], v156 offset:20480
	ds_read_b128 v[212:215], v156 offset:21504
	ds_read_b128 v[216:219], v156 offset:22528
	ds_read_b128 v[220:223], v156 offset:23552
	global_load_lds_dwordx4 v134, s[34:35]
	s_add_i32 m0, s62, 0x2000
	s_add_u32 s62, s34, 0x100000
	s_addc_u32 s63, s35, 0
	s_add_i32 s64, s54, s38
	global_load_lds_dwordx4 v130, s[34:35]
	s_mov_b32 m0, s64
	s_nop 0
	global_load_lds_dwordx4 v134, s[62:63]
	s_add_i32 m0, s64, 0x2000
	s_nop 0
	global_load_lds_dwordx4 v130, s[62:63]
	s_mov_b32 m0, s39
	s_nop 0
	global_load_lds_dwordx4 v136, s[36:37]
	s_mov_b32 m0, s40
	s_nop 0
	global_load_lds_dwordx4 v132, s[36:37]
	s_waitcnt vmcnt(8)
	s_waitcnt lgkmcnt(0)
	s_barrier
	s_setprio 1
	s_waitcnt lgkmcnt(0)
	v_mfma_f32_16x16x32_bf16 v[62:65], v[160:163], v[192:195], v[62:65]
	v_mfma_f32_16x16x32_bf16 v[62:65], v[164:167], v[196:199], v[62:65]
	v_mfma_f32_16x16x32_bf16 v[58:61], v[168:171], v[192:195], v[58:61]
	v_mfma_f32_16x16x32_bf16 v[58:61], v[172:175], v[196:199], v[58:61]
	v_mfma_f32_16x16x32_bf16 v[46:49], v[160:163], v[200:203], v[46:49]
	v_mfma_f32_16x16x32_bf16 v[46:49], v[164:167], v[204:207], v[46:49]
	v_mfma_f32_16x16x32_bf16 v[42:45], v[168:171], v[200:203], v[42:45]
	v_mfma_f32_16x16x32_bf16 v[42:45], v[172:175], v[204:207], v[42:45]
	v_mfma_f32_16x16x32_bf16 v[30:33], v[160:163], v[208:211], v[30:33]
	v_mfma_f32_16x16x32_bf16 v[30:33], v[164:167], v[212:215], v[30:33]
	v_mfma_f32_16x16x32_bf16 v[26:29], v[168:171], v[208:211], v[26:29]
	v_mfma_f32_16x16x32_bf16 v[26:29], v[172:175], v[212:215], v[26:29]
	v_mfma_f32_16x16x32_bf16 v[14:17], v[160:163], v[216:219], v[14:17]
	v_mfma_f32_16x16x32_bf16 v[14:17], v[164:167], v[220:223], v[14:17]
	v_mfma_f32_16x16x32_bf16 v[10:13], v[168:171], v[216:219], v[10:13]
	v_mfma_f32_16x16x32_bf16 v[10:13], v[172:175], v[220:223], v[10:13]
	v_mfma_f32_16x16x32_bf16 v[54:57], v[176:179], v[192:195], v[54:57]
	v_mfma_f32_16x16x32_bf16 v[54:57], v[180:183], v[196:199], v[54:57]
	v_mfma_f32_16x16x32_bf16 v[50:53], v[184:187], v[192:195], v[50:53]
	v_mfma_f32_16x16x32_bf16 v[50:53], v[188:191], v[196:199], v[50:53]
	v_mfma_f32_16x16x32_bf16 v[38:41], v[176:179], v[200:203], v[38:41]
	v_mfma_f32_16x16x32_bf16 v[38:41], v[180:183], v[204:207], v[38:41]
	v_mfma_f32_16x16x32_bf16 v[34:37], v[184:187], v[200:203], v[34:37]
	v_mfma_f32_16x16x32_bf16 v[34:37], v[188:191], v[204:207], v[34:37]
	v_mfma_f32_16x16x32_bf16 v[22:25], v[176:179], v[208:211], v[22:25]
	v_mfma_f32_16x16x32_bf16 v[22:25], v[180:183], v[212:215], v[22:25]
	v_mfma_f32_16x16x32_bf16 v[18:21], v[184:187], v[208:211], v[18:21]
	v_mfma_f32_16x16x32_bf16 v[18:21], v[188:191], v[212:215], v[18:21]
	v_mfma_f32_16x16x32_bf16 v[6:9], v[176:179], v[216:219], v[6:9]
	v_mfma_f32_16x16x32_bf16 v[6:9], v[180:183], v[220:223], v[6:9]
	v_mfma_f32_16x16x32_bf16 v[2:5], v[184:187], v[216:219], v[2:5]
	v_mfma_f32_16x16x32_bf16 v[2:5], v[188:191], v[220:223], v[2:5]
	s_setprio 0
	s_barrier
	s_add_i32 s62, 0, 0x18000
	v_add_u32_e32 v138, s62, v153
	s_add_i32 s63, 0, 0x1c000
	ds_read_b128 v[160:163], v138
	ds_read_b128 v[164:167], v138 offset:1024
	ds_read_b128 v[168:171], v138 offset:2048
	ds_read_b128 v[172:175], v138 offset:3072
	v_add_u32_e32 v138, s63, v153
	ds_read_b128 v[176:179], v138
	ds_read_b128 v[180:183], v138 offset:1024
	ds_read_b128 v[184:187], v138 offset:2048
	ds_read_b128 v[188:191], v138 offset:3072
	s_add_u32 s36, s36, 0x100000
	s_addc_u32 s37, s37, 0
	s_mov_b32 m0, s41
	ds_read_b128 v[192:195], v156 offset:32768
	ds_read_b128 v[196:199], v156 offset:33792
	ds_read_b128 v[200:203], v156 offset:34816
	ds_read_b128 v[204:207], v156 offset:35840
	ds_read_b128 v[208:211], v156 offset:36864
	ds_read_b128 v[212:215], v156 offset:37888
	ds_read_b128 v[216:219], v156 offset:38912
	ds_read_b128 v[220:223], v156 offset:39936
	global_load_lds_dwordx4 v136, s[36:37]
	s_mov_b32 m0, s42
	s_nop 0
	global_load_lds_dwordx4 v132, s[36:37]
	s_waitcnt vmcnt(8)
	s_waitcnt lgkmcnt(0)
	s_barrier
	s_setprio 1
	s_waitcnt lgkmcnt(0)
	v_mfma_f32_16x16x32_bf16 v[126:129], v[160:163], v[192:195], v[126:129]
	v_mfma_f32_16x16x32_bf16 v[126:129], v[164:167], v[196:199], v[126:129]
	v_mfma_f32_16x16x32_bf16 v[122:125], v[168:171], v[192:195], v[122:125]
	v_mfma_f32_16x16x32_bf16 v[122:125], v[172:175], v[196:199], v[122:125]
	v_mfma_f32_16x16x32_bf16 v[110:113], v[160:163], v[200:203], v[110:113]
	v_mfma_f32_16x16x32_bf16 v[110:113], v[164:167], v[204:207], v[110:113]
	v_mfma_f32_16x16x32_bf16 v[106:109], v[168:171], v[200:203], v[106:109]
	v_mfma_f32_16x16x32_bf16 v[106:109], v[172:175], v[204:207], v[106:109]
	v_mfma_f32_16x16x32_bf16 v[94:97], v[160:163], v[208:211], v[94:97]
	v_mfma_f32_16x16x32_bf16 v[94:97], v[164:167], v[212:215], v[94:97]
	v_mfma_f32_16x16x32_bf16 v[90:93], v[168:171], v[208:211], v[90:93]
	v_mfma_f32_16x16x32_bf16 v[90:93], v[172:175], v[212:215], v[90:93]
	v_mfma_f32_16x16x32_bf16 v[78:81], v[160:163], v[216:219], v[78:81]
	v_mfma_f32_16x16x32_bf16 v[78:81], v[164:167], v[220:223], v[78:81]
	v_mfma_f32_16x16x32_bf16 v[74:77], v[168:171], v[216:219], v[74:77]
	v_mfma_f32_16x16x32_bf16 v[74:77], v[172:175], v[220:223], v[74:77]
	v_mfma_f32_16x16x32_bf16 v[118:121], v[176:179], v[192:195], v[118:121]
	v_mfma_f32_16x16x32_bf16 v[118:121], v[180:183], v[196:199], v[118:121]
	v_mfma_f32_16x16x32_bf16 v[114:117], v[184:187], v[192:195], v[114:117]
	v_mfma_f32_16x16x32_bf16 v[114:117], v[188:191], v[196:199], v[114:117]
	v_mfma_f32_16x16x32_bf16 v[102:105], v[176:179], v[200:203], v[102:105]
	v_mfma_f32_16x16x32_bf16 v[102:105], v[180:183], v[204:207], v[102:105]
	v_mfma_f32_16x16x32_bf16 v[98:101], v[184:187], v[200:203], v[98:101]
	v_mfma_f32_16x16x32_bf16 v[98:101], v[188:191], v[204:207], v[98:101]
	v_mfma_f32_16x16x32_bf16 v[86:89], v[176:179], v[208:211], v[86:89]
	v_mfma_f32_16x16x32_bf16 v[86:89], v[180:183], v[212:215], v[86:89]
	v_mfma_f32_16x16x32_bf16 v[82:85], v[184:187], v[208:211], v[82:85]
	v_mfma_f32_16x16x32_bf16 v[82:85], v[188:191], v[212:215], v[82:85]
	v_mfma_f32_16x16x32_bf16 v[70:73], v[176:179], v[216:219], v[70:73]
	v_mfma_f32_16x16x32_bf16 v[70:73], v[180:183], v[220:223], v[70:73]
	v_mfma_f32_16x16x32_bf16 v[66:69], v[184:187], v[216:219], v[66:69]
	v_mfma_f32_16x16x32_bf16 v[66:69], v[188:191], v[220:223], v[66:69]
	s_setprio 0
	s_barrier
	s_add_u32 s36, s34, 0x4000
	s_addc_u32 s37, s35, 0
	s_add_i32 s62, s62, s38
	s_mov_b32 m0, s62
	ds_read_b128 v[192:195], v156 offset:49152
	ds_read_b128 v[196:199], v156 offset:50176
	ds_read_b128 v[200:203], v156 offset:51200
	ds_read_b128 v[204:207], v156 offset:52224
	ds_read_b128 v[208:211], v156 offset:53248
	ds_read_b128 v[212:215], v156 offset:54272
	ds_read_b128 v[216:219], v156 offset:55296
	ds_read_b128 v[220:223], v156 offset:56320
	global_load_lds_dwordx4 v134, s[36:37]
	s_add_i32 m0, s62, 0x2000
	s_add_u32 s34, s34, 0x104000
	s_addc_u32 s35, s35, 0
	global_load_lds_dwordx4 v130, s[36:37]
	s_add_i32 s36, s63, s38
	s_mov_b32 m0, s36
	s_nop 0
	global_load_lds_dwordx4 v134, s[34:35]
	s_add_i32 m0, s36, 0x2000
	s_nop 0
	global_load_lds_dwordx4 v130, s[34:35]
	s_mov_b32 m0, s45
	s_nop 0
	global_load_lds_dwordx4 v136, s[30:31]
	s_mov_b32 m0, s46
	s_nop 0
	global_load_lds_dwordx4 v132, s[30:31]
	s_waitcnt vmcnt(8)
	s_waitcnt lgkmcnt(0)
	s_barrier
	s_setprio 1
	s_waitcnt lgkmcnt(0)
	v_mfma_f32_16x16x32_bf16 v[62:65], v[160:163], v[192:195], v[62:65]
	v_mfma_f32_16x16x32_bf16 v[62:65], v[164:167], v[196:199], v[62:65]
	v_mfma_f32_16x16x32_bf16 v[58:61], v[168:171], v[192:195], v[58:61]
	v_mfma_f32_16x16x32_bf16 v[58:61], v[172:175], v[196:199], v[58:61]
	v_mfma_f32_16x16x32_bf16 v[46:49], v[160:163], v[200:203], v[46:49]
	v_mfma_f32_16x16x32_bf16 v[46:49], v[164:167], v[204:207], v[46:49]
	v_mfma_f32_16x16x32_bf16 v[42:45], v[168:171], v[200:203], v[42:45]
	v_mfma_f32_16x16x32_bf16 v[42:45], v[172:175], v[204:207], v[42:45]
	v_mfma_f32_16x16x32_bf16 v[30:33], v[160:163], v[208:211], v[30:33]
	v_mfma_f32_16x16x32_bf16 v[30:33], v[164:167], v[212:215], v[30:33]
	v_mfma_f32_16x16x32_bf16 v[26:29], v[168:171], v[208:211], v[26:29]
	v_mfma_f32_16x16x32_bf16 v[26:29], v[172:175], v[212:215], v[26:29]
	v_mfma_f32_16x16x32_bf16 v[14:17], v[160:163], v[216:219], v[14:17]
	v_mfma_f32_16x16x32_bf16 v[14:17], v[164:167], v[220:223], v[14:17]
	v_mfma_f32_16x16x32_bf16 v[10:13], v[168:171], v[216:219], v[10:13]
	v_mfma_f32_16x16x32_bf16 v[10:13], v[172:175], v[220:223], v[10:13]
	v_mfma_f32_16x16x32_bf16 v[54:57], v[176:179], v[192:195], v[54:57]
	v_mfma_f32_16x16x32_bf16 v[54:57], v[180:183], v[196:199], v[54:57]
	v_mfma_f32_16x16x32_bf16 v[50:53], v[184:187], v[192:195], v[50:53]
	v_mfma_f32_16x16x32_bf16 v[50:53], v[188:191], v[196:199], v[50:53]
	v_mfma_f32_16x16x32_bf16 v[38:41], v[176:179], v[200:203], v[38:41]
	v_mfma_f32_16x16x32_bf16 v[38:41], v[180:183], v[204:207], v[38:41]
	v_mfma_f32_16x16x32_bf16 v[34:37], v[184:187], v[200:203], v[34:37]
	v_mfma_f32_16x16x32_bf16 v[34:37], v[188:191], v[204:207], v[34:37]
	v_mfma_f32_16x16x32_bf16 v[22:25], v[176:179], v[208:211], v[22:25]
	v_mfma_f32_16x16x32_bf16 v[22:25], v[180:183], v[212:215], v[22:25]
	v_mfma_f32_16x16x32_bf16 v[18:21], v[184:187], v[208:211], v[18:21]
	v_mfma_f32_16x16x32_bf16 v[18:21], v[188:191], v[212:215], v[18:21]
	v_mfma_f32_16x16x32_bf16 v[6:9], v[176:179], v[216:219], v[6:9]
	v_mfma_f32_16x16x32_bf16 v[6:9], v[180:183], v[220:223], v[6:9]
	v_mfma_f32_16x16x32_bf16 v[2:5], v[184:187], v[216:219], v[2:5]
	v_mfma_f32_16x16x32_bf16 v[2:5], v[188:191], v[220:223], v[2:5]
	s_setprio 0
	s_barrier
	s_add_i32 s61, s61, 2
	s_add_u32 s28, s28, 0x8000
	s_addc_u32 s29, s29, 0
	s_add_u32 s59, s59, 0x8000
	s_addc_u32 s60, s60, 0
	s_cmp_gt_u32 s61, 61
	s_cbranch_scc0 .LBB0_1215
	s_and_b64 vcc, exec, s[16:17]
	s_cbranch_vccz .LBB0_1218
	s_barrier

.LBB0_1292:
	ds_read_b128 v[130:133], v206
	ds_read_b128 v[134:137], v206 offset:1024
	ds_read_b128 v[138:141], v206 offset:2048
	ds_read_b128 v[142:145], v206 offset:3072
	ds_read_b128 v[146:149], v207
	ds_read_b128 v[150:153], v207 offset:1024
	ds_read_b128 v[176:179], v207 offset:2048
	ds_read_b128 v[180:183], v207 offset:3072
	s_add_u32 s42, s40, 0xffc04000
	s_addc_u32 s43, s41, -1
	s_cmpk_eq_i32 s66, 0xfc
	s_cselect_b32 s46, s29, s42
	s_cselect_b32 s47, s14, s43
	s_cselect_b32 s44, s37, s39
	s_cselect_b32 s45, s27, s65
	s_add_u32 s42, s46, 0x4000
	s_addc_u32 s43, s47, 0
	s_add_i32 m0, s53, 0xc000
	ds_read_b128 v[184:187], v208
	ds_read_b128 v[188:191], v208 offset:1024
	ds_read_b128 v[192:195], v208 offset:2048
	ds_read_b128 v[196:199], v208 offset:3072
	ds_read_b128 v[210:213], v208 offset:4096
	ds_read_b128 v[214:217], v208 offset:5120
	ds_read_b128 v[218:221], v208 offset:6144
	ds_read_b128 v[222:225], v208 offset:7168
	global_load_lds_dwordx4 v166, s[40:41]
	s_add_i32 m0, s53, 0xe000
	s_nop 0
	global_load_lds_dwordx4 v168, s[40:41]
	s_waitcnt vmcnt(8)
	s_waitcnt lgkmcnt(0)
	s_barrier
	s_setprio 1
	s_waitcnt lgkmcnt(0)
	v_mfma_f32_16x16x32_bf16 v[126:129], v[130:133], v[184:187], v[126:129]
	v_mfma_f32_16x16x32_bf16 v[126:129], v[134:137], v[188:191], v[126:129]
	v_mfma_f32_16x16x32_bf16 v[122:125], v[138:141], v[184:187], v[122:125]
	v_mfma_f32_16x16x32_bf16 v[122:125], v[142:145], v[188:191], v[122:125]
	v_mfma_f32_16x16x32_bf16 v[110:113], v[130:133], v[192:195], v[110:113]
	v_mfma_f32_16x16x32_bf16 v[110:113], v[134:137], v[196:199], v[110:113]
	v_mfma_f32_16x16x32_bf16 v[106:109], v[138:141], v[192:195], v[106:109]
	v_mfma_f32_16x16x32_bf16 v[106:109], v[142:145], v[196:199], v[106:109]
	v_mfma_f32_16x16x32_bf16 v[94:97], v[130:133], v[210:213], v[94:97]
	v_mfma_f32_16x16x32_bf16 v[94:97], v[134:137], v[214:217], v[94:97]
	v_mfma_f32_16x16x32_bf16 v[90:93], v[138:141], v[210:213], v[90:93]
	v_mfma_f32_16x16x32_bf16 v[90:93], v[142:145], v[214:217], v[90:93]
	v_mfma_f32_16x16x32_bf16 v[78:81], v[130:133], v[218:221], v[78:81]
	v_mfma_f32_16x16x32_bf16 v[78:81], v[134:137], v[222:225], v[78:81]
	v_mfma_f32_16x16x32_bf16 v[74:77], v[138:141], v[218:221], v[74:77]
	v_mfma_f32_16x16x32_bf16 v[74:77], v[142:145], v[222:225], v[74:77]
	v_mfma_f32_16x16x32_bf16 v[118:121], v[146:149], v[184:187], v[118:121]
	v_mfma_f32_16x16x32_bf16 v[118:121], v[150:153], v[188:191], v[118:121]
	v_mfma_f32_16x16x32_bf16 v[114:117], v[176:179], v[184:187], v[114:117]
	v_mfma_f32_16x16x32_bf16 v[114:117], v[180:183], v[188:191], v[114:117]
	v_mfma_f32_16x16x32_bf16 v[102:105], v[146:149], v[192:195], v[102:105]
	v_mfma_f32_16x16x32_bf16 v[102:105], v[150:153], v[196:199], v[102:105]
	v_mfma_f32_16x16x32_bf16 v[98:101], v[176:179], v[192:195], v[98:101]
	v_mfma_f32_16x16x32_bf16 v[98:101], v[180:183], v[196:199], v[98:101]
	v_mfma_f32_16x16x32_bf16 v[86:89], v[146:149], v[210:213], v[86:89]
	v_mfma_f32_16x16x32_bf16 v[86:89], v[150:153], v[214:217], v[86:89]
	v_mfma_f32_16x16x32_bf16 v[82:85], v[176:179], v[210:213], v[82:85]
	v_mfma_f32_16x16x32_bf16 v[82:85], v[180:183], v[214:217], v[82:85]
	v_mfma_f32_16x16x32_bf16 v[70:73], v[146:149], v[218:221], v[70:73]
	v_mfma_f32_16x16x32_bf16 v[70:73], v[150:153], v[222:225], v[70:73]
	v_mfma_f32_16x16x32_bf16 v[66:69], v[176:179], v[218:221], v[66:69]
	v_mfma_f32_16x16x32_bf16 v[66:69], v[180:183], v[222:225], v[66:69]
	s_setprio 0
	s_barrier
	s_add_i32 s67, s62, s52
	s_mov_b32 m0, s67
	ds_read_b128 v[184:187], v208 offset:16384
	ds_read_b128 v[188:191], v208 offset:17408
	ds_read_b128 v[192:195], v208 offset:18432
	ds_read_b128 v[196:199], v208 offset:19456
	ds_read_b128 v[210:213], v208 offset:20480
	ds_read_b128 v[214:217], v208 offset:21504
	ds_read_b128 v[218:221], v208 offset:22528
	ds_read_b128 v[222:225], v208 offset:23552
	global_load_lds_dwordx4 v156, s[44:45]
	s_add_i32 m0, s67, 0x2000
	s_add_u32 s68, s44, 0x400000
	s_addc_u32 s69, s45, 0
	s_add_i32 s67, s63, s52
	global_load_lds_dwordx4 v160, s[44:45]
	s_mov_b32 m0, s67
	s_nop 0
	global_load_lds_dwordx4 v156, s[68:69]
	s_add_i32 m0, s67, 0x2000
	s_nop 0
	global_load_lds_dwordx4 v160, s[68:69]
	s_mov_b32 m0, s53
	s_nop 0
	global_load_lds_dwordx4 v154, s[46:47]
	s_mov_b32 m0, s54
	s_nop 0
	global_load_lds_dwordx4 v158, s[46:47]
	s_waitcnt vmcnt(8)
	s_waitcnt lgkmcnt(0)
	s_barrier
	s_setprio 1
	s_waitcnt lgkmcnt(0)
	v_mfma_f32_16x16x32_bf16 v[62:65], v[130:133], v[184:187], v[62:65]
	v_mfma_f32_16x16x32_bf16 v[62:65], v[134:137], v[188:191], v[62:65]
	v_mfma_f32_16x16x32_bf16 v[58:61], v[138:141], v[184:187], v[58:61]
	v_mfma_f32_16x16x32_bf16 v[58:61], v[142:145], v[188:191], v[58:61]
	v_mfma_f32_16x16x32_bf16 v[46:49], v[130:133], v[192:195], v[46:49]
	v_mfma_f32_16x16x32_bf16 v[46:49], v[134:137], v[196:199], v[46:49]
	v_mfma_f32_16x16x32_bf16 v[42:45], v[138:141], v[192:195], v[42:45]
	v_mfma_f32_16x16x32_bf16 v[42:45], v[142:145], v[196:199], v[42:45]
	v_mfma_f32_16x16x32_bf16 v[30:33], v[130:133], v[210:213], v[30:33]
	v_mfma_f32_16x16x32_bf16 v[30:33], v[134:137], v[214:217], v[30:33]
	v_mfma_f32_16x16x32_bf16 v[26:29], v[138:141], v[210:213], v[26:29]
	v_mfma_f32_16x16x32_bf16 v[26:29], v[142:145], v[214:217], v[26:29]
	v_mfma_f32_16x16x32_bf16 v[14:17], v[130:133], v[218:221], v[14:17]
	v_mfma_f32_16x16x32_bf16 v[14:17], v[134:137], v[222:225], v[14:17]
	v_mfma_f32_16x16x32_bf16 v[10:13], v[138:141], v[218:221], v[10:13]
	v_mfma_f32_16x16x32_bf16 v[10:13], v[142:145], v[222:225], v[10:13]
	v_mfma_f32_16x16x32_bf16 v[54:57], v[146:149], v[184:187], v[54:57]
	v_mfma_f32_16x16x32_bf16 v[54:57], v[150:153], v[188:191], v[54:57]
	v_mfma_f32_16x16x32_bf16 v[50:53], v[176:179], v[184:187], v[50:53]
	v_mfma_f32_16x16x32_bf16 v[50:53], v[180:183], v[188:191], v[50:53]
	v_mfma_f32_16x16x32_bf16 v[38:41], v[146:149], v[192:195], v[38:41]
	v_mfma_f32_16x16x32_bf16 v[38:41], v[150:153], v[196:199], v[38:41]
	v_mfma_f32_16x16x32_bf16 v[34:37], v[176:179], v[192:195], v[34:37]
	v_mfma_f32_16x16x32_bf16 v[34:37], v[180:183], v[196:199], v[34:37]
	v_mfma_f32_16x16x32_bf16 v[22:25], v[146:149], v[210:213], v[22:25]
	v_mfma_f32_16x16x32_bf16 v[22:25], v[150:153], v[214:217], v[22:25]
	v_mfma_f32_16x16x32_bf16 v[18:21], v[176:179], v[210:213], v[18:21]
	v_mfma_f32_16x16x32_bf16 v[18:21], v[180:183], v[214:217], v[18:21]
	v_mfma_f32_16x16x32_bf16 v[6:9], v[146:149], v[218:221], v[6:9]
	v_mfma_f32_16x16x32_bf16 v[6:9], v[150:153], v[222:225], v[6:9]
	v_mfma_f32_16x16x32_bf16 v[2:5], v[176:179], v[218:221], v[2:5]
	v_mfma_f32_16x16x32_bf16 v[2:5], v[180:183], v[222:225], v[2:5]
	s_setprio 0
	s_barrier
	s_add_i32 s67, 0, 0x18000
	s_add_i32 s68, 0, 0x1c000
	v_add_u32_e32 v142, s67, v203
	v_add_u32_e32 v162, s68, v203
	ds_read_b128 v[130:133], v142
	ds_read_b128 v[134:137], v142 offset:1024
	ds_read_b128 v[138:141], v142 offset:2048
	ds_read_b128 v[142:145], v142 offset:3072
	ds_read_b128 v[146:149], v162
	ds_read_b128 v[150:153], v162 offset:1024
	ds_read_b128 v[176:179], v162 offset:2048
	ds_read_b128 v[180:183], v162 offset:3072
	s_add_u32 s46, s46, 0x400000
	s_addc_u32 s47, s47, 0
	s_mov_b32 m0, s55
	ds_read_b128 v[184:187], v208 offset:32768
	ds_read_b128 v[188:191], v208 offset:33792
	ds_read_b128 v[192:195], v208 offset:34816
	ds_read_b128 v[196:199], v208 offset:35840
	ds_read_b128 v[210:213], v208 offset:36864
	ds_read_b128 v[214:217], v208 offset:37888
	ds_read_b128 v[218:221], v208 offset:38912
	ds_read_b128 v[222:225], v208 offset:39936
	global_load_lds_dwordx4 v154, s[46:47]
	s_mov_b32 m0, s56
	s_nop 0
	global_load_lds_dwordx4 v158, s[46:47]
	s_waitcnt vmcnt(8)
	s_waitcnt lgkmcnt(0)
	s_barrier
	s_setprio 1
	s_waitcnt lgkmcnt(0)
	v_mfma_f32_16x16x32_bf16 v[126:129], v[130:133], v[184:187], v[126:129]
	v_mfma_f32_16x16x32_bf16 v[126:129], v[134:137], v[188:191], v[126:129]
	v_mfma_f32_16x16x32_bf16 v[122:125], v[138:141], v[184:187], v[122:125]
	v_mfma_f32_16x16x32_bf16 v[122:125], v[142:145], v[188:191], v[122:125]
	v_mfma_f32_16x16x32_bf16 v[110:113], v[130:133], v[192:195], v[110:113]
	v_mfma_f32_16x16x32_bf16 v[110:113], v[134:137], v[196:199], v[110:113]
	v_mfma_f32_16x16x32_bf16 v[106:109], v[138:141], v[192:195], v[106:109]
	v_mfma_f32_16x16x32_bf16 v[106:109], v[142:145], v[196:199], v[106:109]
	v_mfma_f32_16x16x32_bf16 v[94:97], v[130:133], v[210:213], v[94:97]
	v_mfma_f32_16x16x32_bf16 v[94:97], v[134:137], v[214:217], v[94:97]
	v_mfma_f32_16x16x32_bf16 v[90:93], v[138:141], v[210:213], v[90:93]
	v_mfma_f32_16x16x32_bf16 v[90:93], v[142:145], v[214:217], v[90:93]
	v_mfma_f32_16x16x32_bf16 v[78:81], v[130:133], v[218:221], v[78:81]
	v_mfma_f32_16x16x32_bf16 v[78:81], v[134:137], v[222:225], v[78:81]
	v_mfma_f32_16x16x32_bf16 v[74:77], v[138:141], v[218:221], v[74:77]
	v_mfma_f32_16x16x32_bf16 v[74:77], v[142:145], v[222:225], v[74:77]
	v_mfma_f32_16x16x32_bf16 v[118:121], v[146:149], v[184:187], v[118:121]
	v_mfma_f32_16x16x32_bf16 v[118:121], v[150:153], v[188:191], v[118:121]
	v_mfma_f32_16x16x32_bf16 v[114:117], v[176:179], v[184:187], v[114:117]
	v_mfma_f32_16x16x32_bf16 v[114:117], v[180:183], v[188:191], v[114:117]
	v_mfma_f32_16x16x32_bf16 v[102:105], v[146:149], v[192:195], v[102:105]
	v_mfma_f32_16x16x32_bf16 v[102:105], v[150:153], v[196:199], v[102:105]
	v_mfma_f32_16x16x32_bf16 v[98:101], v[176:179], v[192:195], v[98:101]
	v_mfma_f32_16x16x32_bf16 v[98:101], v[180:183], v[196:199], v[98:101]
	v_mfma_f32_16x16x32_bf16 v[86:89], v[146:149], v[210:213], v[86:89]
	v_mfma_f32_16x16x32_bf16 v[86:89], v[150:153], v[214:217], v[86:89]
	v_mfma_f32_16x16x32_bf16 v[82:85], v[176:179], v[210:213], v[82:85]
	v_mfma_f32_16x16x32_bf16 v[82:85], v[180:183], v[214:217], v[82:85]
	v_mfma_f32_16x16x32_bf16 v[70:73], v[146:149], v[218:221], v[70:73]
	v_mfma_f32_16x16x32_bf16 v[70:73], v[150:153], v[222:225], v[70:73]
	v_mfma_f32_16x16x32_bf16 v[66:69], v[176:179], v[218:221], v[66:69]
	v_mfma_f32_16x16x32_bf16 v[66:69], v[180:183], v[222:225], v[66:69]
	s_setprio 0
	s_barrier
	s_add_u32 s46, s44, 0x4000
	s_addc_u32 s47, s45, 0
	s_add_i32 s67, s67, s52
	s_mov_b32 m0, s67
	ds_read_b128 v[184:187], v208 offset:49152
	ds_read_b128 v[188:191], v208 offset:50176
	ds_read_b128 v[192:195], v208 offset:51200
	ds_read_b128 v[196:199], v208 offset:52224
	ds_read_b128 v[210:213], v208 offset:53248
	ds_read_b128 v[214:217], v208 offset:54272
	ds_read_b128 v[218:221], v208 offset:55296
	ds_read_b128 v[222:225], v208 offset:56320
	global_load_lds_dwordx4 v156, s[46:47]
	s_add_i32 m0, s67, 0x2000
	s_add_u32 s44, s44, 0x404000
	s_addc_u32 s45, s45, 0
	global_load_lds_dwordx4 v160, s[46:47]
	s_add_i32 s46, s68, s52
	s_mov_b32 m0, s46
	s_nop 0
	global_load_lds_dwordx4 v156, s[44:45]
	s_add_i32 m0, s46, 0x2000
	s_nop 0
	global_load_lds_dwordx4 v160, s[44:45]
	s_mov_b32 m0, s60
	s_nop 0
	global_load_lds_dwordx4 v154, s[42:43]
	s_mov_b32 m0, s61
	s_nop 0
	global_load_lds_dwordx4 v158, s[42:43]
	s_waitcnt vmcnt(8)
	s_waitcnt lgkmcnt(0)
	s_barrier
	s_setprio 1
	s_waitcnt lgkmcnt(0)
	v_mfma_f32_16x16x32_bf16 v[62:65], v[130:133], v[184:187], v[62:65]
	v_mfma_f32_16x16x32_bf16 v[62:65], v[134:137], v[188:191], v[62:65]
	v_mfma_f32_16x16x32_bf16 v[58:61], v[138:141], v[184:187], v[58:61]
	v_mfma_f32_16x16x32_bf16 v[58:61], v[142:145], v[188:191], v[58:61]
	v_mfma_f32_16x16x32_bf16 v[46:49], v[130:133], v[192:195], v[46:49]
	v_mfma_f32_16x16x32_bf16 v[46:49], v[134:137], v[196:199], v[46:49]
	v_mfma_f32_16x16x32_bf16 v[42:45], v[138:141], v[192:195], v[42:45]
	v_mfma_f32_16x16x32_bf16 v[42:45], v[142:145], v[196:199], v[42:45]
	v_mfma_f32_16x16x32_bf16 v[30:33], v[130:133], v[210:213], v[30:33]
	v_mfma_f32_16x16x32_bf16 v[30:33], v[134:137], v[214:217], v[30:33]
	v_mfma_f32_16x16x32_bf16 v[26:29], v[138:141], v[210:213], v[26:29]
	v_mfma_f32_16x16x32_bf16 v[26:29], v[142:145], v[214:217], v[26:29]
	v_mfma_f32_16x16x32_bf16 v[14:17], v[130:133], v[218:221], v[14:17]
	v_mfma_f32_16x16x32_bf16 v[14:17], v[134:137], v[222:225], v[14:17]
	v_mfma_f32_16x16x32_bf16 v[10:13], v[138:141], v[218:221], v[10:13]
	v_mfma_f32_16x16x32_bf16 v[10:13], v[142:145], v[222:225], v[10:13]
	v_mfma_f32_16x16x32_bf16 v[54:57], v[146:149], v[184:187], v[54:57]
	v_mfma_f32_16x16x32_bf16 v[54:57], v[150:153], v[188:191], v[54:57]
	v_mfma_f32_16x16x32_bf16 v[50:53], v[176:179], v[184:187], v[50:53]
	v_mfma_f32_16x16x32_bf16 v[50:53], v[180:183], v[188:191], v[50:53]
	v_mfma_f32_16x16x32_bf16 v[38:41], v[146:149], v[192:195], v[38:41]
	v_mfma_f32_16x16x32_bf16 v[38:41], v[150:153], v[196:199], v[38:41]
	v_mfma_f32_16x16x32_bf16 v[34:37], v[176:179], v[192:195], v[34:37]
	v_mfma_f32_16x16x32_bf16 v[34:37], v[180:183], v[196:199], v[34:37]
	v_mfma_f32_16x16x32_bf16 v[22:25], v[146:149], v[210:213], v[22:25]
	v_mfma_f32_16x16x32_bf16 v[22:25], v[150:153], v[214:217], v[22:25]
	v_mfma_f32_16x16x32_bf16 v[18:21], v[176:179], v[210:213], v[18:21]
	v_mfma_f32_16x16x32_bf16 v[18:21], v[180:183], v[214:217], v[18:21]
	v_mfma_f32_16x16x32_bf16 v[6:9], v[146:149], v[218:221], v[6:9]
	v_mfma_f32_16x16x32_bf16 v[6:9], v[150:153], v[222:225], v[6:9]
	v_mfma_f32_16x16x32_bf16 v[2:5], v[176:179], v[218:221], v[2:5]
	v_mfma_f32_16x16x32_bf16 v[2:5], v[180:183], v[222:225], v[2:5]
	s_setprio 0
	s_barrier
	s_add_i32 s66, s66, 2
	s_add_u32 s40, s40, 0x8000
	s_addc_u32 s41, s41, 0
	s_add_u32 s39, s39, 0x8000
	s_addc_u32 s65, s65, 0
	s_cmpk_gt_u32 s66, 0xfd
	s_cbranch_scc0 .LBB0_1292
	s_and_b64 vcc, exec, s[24:25]
	s_cbranch_vccz .LBB0_1295
	s_barrier

.LBB0_1387:
	ds_read_b128 v[62:65], v189
	ds_read_b128 v[66:69], v189 offset:1024
	ds_read_b128 v[74:77], v189 offset:2048
	ds_read_b128 v[78:81], v189 offset:3072
	ds_read_b128 v[146:149], v195
	ds_read_b128 v[150:153], v195 offset:1024
	ds_read_b128 v[154:157], v195 offset:2048
	ds_read_b128 v[158:161], v195 offset:3072
	s_add_u32 s34, s30, 0xfff04000
	s_addc_u32 s35, s31, -1
	s_cmp_eq_u32 s54, 60
	s_cselect_b32 s38, s27, s34
	s_cselect_b32 s39, s21, s35
	s_cselect_b32 s36, s29, s52
	s_cselect_b32 s37, s19, s53
	s_add_u32 s34, s38, 0x4000
	s_addc_u32 s35, s39, 0
	s_add_i32 m0, s40, 0xc000
	ds_read_b128 v[190:193], v197
	ds_read_b128 v[198:201], v197 offset:1024
	ds_read_b128 v[202:205], v197 offset:2048
	ds_read_b128 v[206:209], v197 offset:3072
	ds_read_b128 v[210:213], v197 offset:4096
	ds_read_b128 v[214:217], v197 offset:5120
	ds_read_b128 v[218:221], v197 offset:6144
	ds_read_b128 v[222:225], v197 offset:7168
	global_load_lds_dwordx4 v172, s[30:31]
	s_add_i32 m0, s40, 0xe000
	s_nop 0
	global_load_lds_dwordx4 v174, s[30:31]
	s_waitcnt vmcnt(8)
	s_waitcnt lgkmcnt(0)
	s_barrier
	s_setprio 1
	s_waitcnt lgkmcnt(0)
	v_mfma_f32_16x16x32_bf16 v[142:145], v[62:65], v[190:193], v[142:145]
	v_mfma_f32_16x16x32_bf16 v[142:145], v[66:69], v[198:201], v[142:145]
	v_mfma_f32_16x16x32_bf16 v[138:141], v[74:77], v[190:193], v[138:141]
	v_mfma_f32_16x16x32_bf16 v[138:141], v[78:81], v[198:201], v[138:141]
	v_mfma_f32_16x16x32_bf16 v[126:129], v[62:65], v[202:205], v[126:129]
	v_mfma_f32_16x16x32_bf16 v[126:129], v[66:69], v[206:209], v[126:129]
	v_mfma_f32_16x16x32_bf16 v[122:125], v[74:77], v[202:205], v[122:125]
	v_mfma_f32_16x16x32_bf16 v[122:125], v[78:81], v[206:209], v[122:125]
	v_mfma_f32_16x16x32_bf16 v[110:113], v[62:65], v[210:213], v[110:113]
	v_mfma_f32_16x16x32_bf16 v[110:113], v[66:69], v[214:217], v[110:113]
	v_mfma_f32_16x16x32_bf16 v[106:109], v[74:77], v[210:213], v[106:109]
	v_mfma_f32_16x16x32_bf16 v[106:109], v[78:81], v[214:217], v[106:109]
	v_mfma_f32_16x16x32_bf16 v[94:97], v[62:65], v[218:221], v[94:97]
	v_mfma_f32_16x16x32_bf16 v[94:97], v[66:69], v[222:225], v[94:97]
	v_mfma_f32_16x16x32_bf16 v[90:93], v[74:77], v[218:221], v[90:93]
	v_mfma_f32_16x16x32_bf16 v[90:93], v[78:81], v[222:225], v[90:93]
	v_mfma_f32_16x16x32_bf16 v[134:137], v[146:149], v[190:193], v[134:137]
	v_mfma_f32_16x16x32_bf16 v[134:137], v[150:153], v[198:201], v[134:137]
	v_mfma_f32_16x16x32_bf16 v[130:133], v[154:157], v[190:193], v[130:133]
	v_mfma_f32_16x16x32_bf16 v[130:133], v[158:161], v[198:201], v[130:133]
	v_mfma_f32_16x16x32_bf16 v[118:121], v[146:149], v[202:205], v[118:121]
	v_mfma_f32_16x16x32_bf16 v[118:121], v[150:153], v[206:209], v[118:121]
	v_mfma_f32_16x16x32_bf16 v[114:117], v[154:157], v[202:205], v[114:117]
	v_mfma_f32_16x16x32_bf16 v[114:117], v[158:161], v[206:209], v[114:117]
	v_mfma_f32_16x16x32_bf16 v[102:105], v[146:149], v[210:213], v[102:105]
	v_mfma_f32_16x16x32_bf16 v[102:105], v[150:153], v[214:217], v[102:105]
	v_mfma_f32_16x16x32_bf16 v[98:101], v[154:157], v[210:213], v[98:101]
	v_mfma_f32_16x16x32_bf16 v[98:101], v[158:161], v[214:217], v[98:101]
	v_mfma_f32_16x16x32_bf16 v[86:89], v[146:149], v[218:221], v[86:89]
	v_mfma_f32_16x16x32_bf16 v[86:89], v[150:153], v[222:225], v[86:89]
	v_mfma_f32_16x16x32_bf16 v[82:85], v[154:157], v[218:221], v[82:85]
	v_mfma_f32_16x16x32_bf16 v[82:85], v[158:161], v[222:225], v[82:85]
	s_setprio 0
	s_barrier
	s_add_i32 s55, s50, s33
	s_mov_b32 m0, s55
	ds_read_b128 v[190:193], v197 offset:16384
	ds_read_b128 v[198:201], v197 offset:17408
	ds_read_b128 v[202:205], v197 offset:18432
	ds_read_b128 v[206:209], v197 offset:19456
	ds_read_b128 v[210:213], v197 offset:20480
	ds_read_b128 v[214:217], v197 offset:21504
	ds_read_b128 v[218:221], v197 offset:22528
	ds_read_b128 v[222:225], v197 offset:23552
	global_load_lds_dwordx4 v166, s[36:37]
	s_add_i32 m0, s55, 0x2000
	s_add_u32 s56, s36, 0x100000
	s_addc_u32 s57, s37, 0
	s_add_i32 s55, s51, s33
	global_load_lds_dwordx4 v162, s[36:37]
	s_mov_b32 m0, s55
	s_nop 0
	global_load_lds_dwordx4 v166, s[56:57]
	s_add_i32 m0, s55, 0x2000
	s_nop 0
	global_load_lds_dwordx4 v162, s[56:57]
	s_mov_b32 m0, s40
	s_nop 0
	global_load_lds_dwordx4 v168, s[38:39]
	s_mov_b32 m0, s41
	s_nop 0
	global_load_lds_dwordx4 v164, s[38:39]
	s_waitcnt vmcnt(8)
	s_waitcnt lgkmcnt(0)
	s_barrier
	s_setprio 1
	s_waitcnt lgkmcnt(0)
	v_mfma_f32_16x16x32_bf16 v[70:73], v[62:65], v[190:193], v[70:73]
	v_mfma_f32_16x16x32_bf16 v[70:73], v[66:69], v[198:201], v[70:73]
	v_mfma_f32_16x16x32_bf16 v[58:61], v[74:77], v[190:193], v[58:61]
	v_mfma_f32_16x16x32_bf16 v[58:61], v[78:81], v[198:201], v[58:61]
	v_mfma_f32_16x16x32_bf16 v[46:49], v[62:65], v[202:205], v[46:49]
	v_mfma_f32_16x16x32_bf16 v[46:49], v[66:69], v[206:209], v[46:49]
	v_mfma_f32_16x16x32_bf16 v[42:45], v[74:77], v[202:205], v[42:45]
	v_mfma_f32_16x16x32_bf16 v[42:45], v[78:81], v[206:209], v[42:45]
	v_mfma_f32_16x16x32_bf16 v[30:33], v[62:65], v[210:213], v[30:33]
	v_mfma_f32_16x16x32_bf16 v[30:33], v[66:69], v[214:217], v[30:33]
	v_mfma_f32_16x16x32_bf16 v[26:29], v[74:77], v[210:213], v[26:29]
	v_mfma_f32_16x16x32_bf16 v[26:29], v[78:81], v[214:217], v[26:29]
	v_mfma_f32_16x16x32_bf16 v[14:17], v[62:65], v[218:221], v[14:17]
	v_mfma_f32_16x16x32_bf16 v[14:17], v[66:69], v[222:225], v[14:17]
	v_mfma_f32_16x16x32_bf16 v[10:13], v[74:77], v[218:221], v[10:13]
	v_mfma_f32_16x16x32_bf16 v[10:13], v[78:81], v[222:225], v[10:13]
	v_mfma_f32_16x16x32_bf16 v[54:57], v[146:149], v[190:193], v[54:57]
	v_mfma_f32_16x16x32_bf16 v[54:57], v[150:153], v[198:201], v[54:57]
	v_mfma_f32_16x16x32_bf16 v[50:53], v[154:157], v[190:193], v[50:53]
	v_mfma_f32_16x16x32_bf16 v[50:53], v[158:161], v[198:201], v[50:53]
	v_mfma_f32_16x16x32_bf16 v[38:41], v[146:149], v[202:205], v[38:41]
	v_mfma_f32_16x16x32_bf16 v[38:41], v[150:153], v[206:209], v[38:41]
	v_mfma_f32_16x16x32_bf16 v[34:37], v[154:157], v[202:205], v[34:37]
	v_mfma_f32_16x16x32_bf16 v[34:37], v[158:161], v[206:209], v[34:37]
	v_mfma_f32_16x16x32_bf16 v[22:25], v[146:149], v[210:213], v[22:25]
	v_mfma_f32_16x16x32_bf16 v[22:25], v[150:153], v[214:217], v[22:25]
	v_mfma_f32_16x16x32_bf16 v[18:21], v[154:157], v[210:213], v[18:21]
	v_mfma_f32_16x16x32_bf16 v[18:21], v[158:161], v[214:217], v[18:21]
	v_mfma_f32_16x16x32_bf16 v[6:9], v[146:149], v[218:221], v[6:9]
	v_mfma_f32_16x16x32_bf16 v[6:9], v[150:153], v[222:225], v[6:9]
	v_mfma_f32_16x16x32_bf16 v[2:5], v[154:157], v[218:221], v[2:5]
	v_mfma_f32_16x16x32_bf16 v[2:5], v[158:161], v[222:225], v[2:5]
	s_setprio 0
	s_barrier
	s_add_i32 s55, 0, 0x18000
	s_add_i32 s56, 0, 0x1c000
	v_add_u32_e32 v78, s55, v187
	v_add_u32_e32 v158, s56, v187
	ds_read_b128 v[62:65], v78
	ds_read_b128 v[66:69], v78 offset:1024
	ds_read_b128 v[74:77], v78 offset:2048
	ds_read_b128 v[78:81], v78 offset:3072
	ds_read_b128 v[146:149], v158
	ds_read_b128 v[150:153], v158 offset:1024
	ds_read_b128 v[154:157], v158 offset:2048
	ds_read_b128 v[158:161], v158 offset:3072
	s_add_u32 s38, s38, 0x100000
	s_addc_u32 s39, s39, 0
	s_mov_b32 m0, s42
	ds_read_b128 v[190:193], v197 offset:32768
	ds_read_b128 v[198:201], v197 offset:33792
	ds_read_b128 v[202:205], v197 offset:34816
	ds_read_b128 v[206:209], v197 offset:35840
	ds_read_b128 v[210:213], v197 offset:36864
	ds_read_b128 v[214:217], v197 offset:37888
	ds_read_b128 v[218:221], v197 offset:38912
	ds_read_b128 v[222:225], v197 offset:39936
	global_load_lds_dwordx4 v168, s[38:39]
	s_mov_b32 m0, s43
	s_nop 0
	global_load_lds_dwordx4 v164, s[38:39]
	s_waitcnt vmcnt(8)
	s_waitcnt lgkmcnt(0)
	s_barrier
	s_setprio 1
	s_waitcnt lgkmcnt(0)
	v_mfma_f32_16x16x32_bf16 v[142:145], v[62:65], v[190:193], v[142:145]
	v_mfma_f32_16x16x32_bf16 v[142:145], v[66:69], v[198:201], v[142:145]
	v_mfma_f32_16x16x32_bf16 v[138:141], v[74:77], v[190:193], v[138:141]
	v_mfma_f32_16x16x32_bf16 v[138:141], v[78:81], v[198:201], v[138:141]
	v_mfma_f32_16x16x32_bf16 v[126:129], v[62:65], v[202:205], v[126:129]
	v_mfma_f32_16x16x32_bf16 v[126:129], v[66:69], v[206:209], v[126:129]
	v_mfma_f32_16x16x32_bf16 v[122:125], v[74:77], v[202:205], v[122:125]
	v_mfma_f32_16x16x32_bf16 v[122:125], v[78:81], v[206:209], v[122:125]
	v_mfma_f32_16x16x32_bf16 v[110:113], v[62:65], v[210:213], v[110:113]
	v_mfma_f32_16x16x32_bf16 v[110:113], v[66:69], v[214:217], v[110:113]
	v_mfma_f32_16x16x32_bf16 v[106:109], v[74:77], v[210:213], v[106:109]
	v_mfma_f32_16x16x32_bf16 v[106:109], v[78:81], v[214:217], v[106:109]
	v_mfma_f32_16x16x32_bf16 v[94:97], v[62:65], v[218:221], v[94:97]
	v_mfma_f32_16x16x32_bf16 v[94:97], v[66:69], v[222:225], v[94:97]
	v_mfma_f32_16x16x32_bf16 v[90:93], v[74:77], v[218:221], v[90:93]
	v_mfma_f32_16x16x32_bf16 v[90:93], v[78:81], v[222:225], v[90:93]
	v_mfma_f32_16x16x32_bf16 v[134:137], v[146:149], v[190:193], v[134:137]
	v_mfma_f32_16x16x32_bf16 v[134:137], v[150:153], v[198:201], v[134:137]
	v_mfma_f32_16x16x32_bf16 v[130:133], v[154:157], v[190:193], v[130:133]
	v_mfma_f32_16x16x32_bf16 v[130:133], v[158:161], v[198:201], v[130:133]
	v_mfma_f32_16x16x32_bf16 v[118:121], v[146:149], v[202:205], v[118:121]
	v_mfma_f32_16x16x32_bf16 v[118:121], v[150:153], v[206:209], v[118:121]
	v_mfma_f32_16x16x32_bf16 v[114:117], v[154:157], v[202:205], v[114:117]
	v_mfma_f32_16x16x32_bf16 v[114:117], v[158:161], v[206:209], v[114:117]
	v_mfma_f32_16x16x32_bf16 v[102:105], v[146:149], v[210:213], v[102:105]
	v_mfma_f32_16x16x32_bf16 v[102:105], v[150:153], v[214:217], v[102:105]
	v_mfma_f32_16x16x32_bf16 v[98:101], v[154:157], v[210:213], v[98:101]
	v_mfma_f32_16x16x32_bf16 v[98:101], v[158:161], v[214:217], v[98:101]
	v_mfma_f32_16x16x32_bf16 v[86:89], v[146:149], v[218:221], v[86:89]
	v_mfma_f32_16x16x32_bf16 v[86:89], v[150:153], v[222:225], v[86:89]
	v_mfma_f32_16x16x32_bf16 v[82:85], v[154:157], v[218:221], v[82:85]
	v_mfma_f32_16x16x32_bf16 v[82:85], v[158:161], v[222:225], v[82:85]
	s_setprio 0
	s_barrier
	s_add_u32 s38, s36, 0x4000
	s_addc_u32 s39, s37, 0
	s_add_i32 s55, s55, s33
	s_mov_b32 m0, s55
	ds_read_b128 v[190:193], v197 offset:49152
	ds_read_b128 v[198:201], v197 offset:50176
	ds_read_b128 v[202:205], v197 offset:51200
	ds_read_b128 v[206:209], v197 offset:52224
	ds_read_b128 v[210:213], v197 offset:53248
	ds_read_b128 v[214:217], v197 offset:54272
	ds_read_b128 v[218:221], v197 offset:55296
	ds_read_b128 v[222:225], v197 offset:56320
	global_load_lds_dwordx4 v166, s[38:39]
	s_add_i32 m0, s55, 0x2000
	s_add_u32 s36, s36, 0x104000
	s_addc_u32 s37, s37, 0
	global_load_lds_dwordx4 v162, s[38:39]
	s_add_i32 s38, s56, s33
	s_mov_b32 m0, s38
	s_nop 0
	global_load_lds_dwordx4 v166, s[36:37]
	s_add_i32 m0, s38, 0x2000
	s_nop 0
	global_load_lds_dwordx4 v162, s[36:37]
	s_mov_b32 m0, s46
	s_nop 0
	global_load_lds_dwordx4 v168, s[34:35]
	s_mov_b32 m0, s47
	s_nop 0
	global_load_lds_dwordx4 v164, s[34:35]
	s_waitcnt vmcnt(8)
	s_waitcnt lgkmcnt(0)
	s_barrier
	s_setprio 1
	s_waitcnt lgkmcnt(0)
	v_mfma_f32_16x16x32_bf16 v[70:73], v[62:65], v[190:193], v[70:73]
	v_mfma_f32_16x16x32_bf16 v[70:73], v[66:69], v[198:201], v[70:73]
	v_mfma_f32_16x16x32_bf16 v[58:61], v[74:77], v[190:193], v[58:61]
	v_mfma_f32_16x16x32_bf16 v[58:61], v[78:81], v[198:201], v[58:61]
	v_mfma_f32_16x16x32_bf16 v[46:49], v[62:65], v[202:205], v[46:49]
	v_mfma_f32_16x16x32_bf16 v[46:49], v[66:69], v[206:209], v[46:49]
	v_mfma_f32_16x16x32_bf16 v[42:45], v[74:77], v[202:205], v[42:45]
	v_mfma_f32_16x16x32_bf16 v[42:45], v[78:81], v[206:209], v[42:45]
	v_mfma_f32_16x16x32_bf16 v[30:33], v[62:65], v[210:213], v[30:33]
	v_mfma_f32_16x16x32_bf16 v[30:33], v[66:69], v[214:217], v[30:33]
	v_mfma_f32_16x16x32_bf16 v[26:29], v[74:77], v[210:213], v[26:29]
	v_mfma_f32_16x16x32_bf16 v[26:29], v[78:81], v[214:217], v[26:29]
	v_mfma_f32_16x16x32_bf16 v[14:17], v[62:65], v[218:221], v[14:17]
	v_mfma_f32_16x16x32_bf16 v[14:17], v[66:69], v[222:225], v[14:17]
	v_mfma_f32_16x16x32_bf16 v[10:13], v[74:77], v[218:221], v[10:13]
	v_mfma_f32_16x16x32_bf16 v[10:13], v[78:81], v[222:225], v[10:13]
	v_mfma_f32_16x16x32_bf16 v[54:57], v[146:149], v[190:193], v[54:57]
	v_mfma_f32_16x16x32_bf16 v[54:57], v[150:153], v[198:201], v[54:57]
	v_mfma_f32_16x16x32_bf16 v[50:53], v[154:157], v[190:193], v[50:53]
	v_mfma_f32_16x16x32_bf16 v[50:53], v[158:161], v[198:201], v[50:53]
	v_mfma_f32_16x16x32_bf16 v[38:41], v[146:149], v[202:205], v[38:41]
	v_mfma_f32_16x16x32_bf16 v[38:41], v[150:153], v[206:209], v[38:41]
	v_mfma_f32_16x16x32_bf16 v[34:37], v[154:157], v[202:205], v[34:37]
	v_mfma_f32_16x16x32_bf16 v[34:37], v[158:161], v[206:209], v[34:37]
	v_mfma_f32_16x16x32_bf16 v[22:25], v[146:149], v[210:213], v[22:25]
	v_mfma_f32_16x16x32_bf16 v[22:25], v[150:153], v[214:217], v[22:25]
	v_mfma_f32_16x16x32_bf16 v[18:21], v[154:157], v[210:213], v[18:21]
	v_mfma_f32_16x16x32_bf16 v[18:21], v[158:161], v[214:217], v[18:21]
	v_mfma_f32_16x16x32_bf16 v[6:9], v[146:149], v[218:221], v[6:9]
	v_mfma_f32_16x16x32_bf16 v[6:9], v[150:153], v[222:225], v[6:9]
	v_mfma_f32_16x16x32_bf16 v[2:5], v[154:157], v[218:221], v[2:5]
	v_mfma_f32_16x16x32_bf16 v[2:5], v[158:161], v[222:225], v[2:5]
	s_setprio 0
	s_barrier
	s_add_i32 s54, s54, 2
	s_add_u32 s30, s30, 0x8000
	s_addc_u32 s31, s31, 0
	s_add_u32 s52, s52, 0x8000
	s_addc_u32 s53, s53, 0
	s_cmp_gt_u32 s54, 61
	s_cbranch_scc0 .LBB0_1387
	s_and_b64 vcc, exec, s[12:13]
	s_cbranch_vccz .LBB0_1390
	s_barrier
